# unfused U/V (grid barrier kept) with wo epilogue batched, for comparison with the fused build
# baseline (speedup 1.0000x reference)
; template <bool STORE>
; DI void peer_item(const Params& p, int item, char* smem) {
;     ...
; #pragma unroll
;       for (int u = 0; u < 8; ++u) {
;         int e = e_s[tl * 128 + k + u];
;         uq[u] = *(const u32x4*)(U8 + (size_t)e * 1024 + lane * 16);
;       }
;       float part[8];
; #pragma unroll
;       for (int u = 0; u < 8; ++u) {
;         float d = 0.f;
; #pragma unroll
;         for (int i = 0; i < 4; ++i) {
;           f32x2_t lo = __builtin_amdgcn_cvt_pk_f32_fp8((int)uq[u][i], false);
;           f32x2_t hi = __builtin_amdgcn_cvt_pk_f32_fp8((int)uq[u][i], true);
;           d += xf[4 * i] * lo.x + xf[4 * i + 1] * lo.y + xf[4 * i + 2] * hi.x + xf[4 * i + 3] * hi.y;
;         }
;         part[u] = d;
;       }
;       float q4[4], r2[2], h;
; #pragma unroll
;       for (int j = 0; j < 4; ++j) {
;         float mine = b5 ? part[j + 4] : part[j];
;         float other = b5 ? part[j] : part[j + 4];
;         q4[j] = mine + __shfl_xor(other, 32);
;       }
; #pragma unroll
;       for (int j = 0; j < 2; ++j) {
;         float mine = b4 ? q4[j + 2] : q4[j];
;         float other = b4 ? q4[j] : q4[j + 2];
;         r2[j] = mine + __shfl_xor(other, 16);
;       }
;       {
;         float mine = b3 ? r2[1] : r2[0];
;         float other = b3 ? r2[0] : r2[1];
;         h = mine + __shfl_xor(other, 8);
;       }
;       h += __shfl_xor(h, 4);
;       h += __shfl_xor(h, 2);
;       h += __shfl_xor(h, 1);
.Lup_k:
	v_readlane_b32 s48, v130, s72
	v_readlane_b32 s49, v130, s73
	v_readlane_b32 s50, v130, s74
	v_readlane_b32 s51, v130, s75
	v_readlane_b32 s52, v130, s76
	v_readlane_b32 s53, v130, s77
	v_readlane_b32 s54, v130, s78
	v_readlane_b32 s55, v130, s79
	s_add_u32 s32, s0, s48
	s_addc_u32 s33, s1, 0
	s_add_u32 s34, s0, s49
	s_addc_u32 s35, s1, 0
	s_add_u32 s36, s0, s50
	s_addc_u32 s37, s1, 0
	s_add_u32 s38, s0, s51
	s_addc_u32 s39, s1, 0
	s_add_u32 s40, s0, s52
	s_addc_u32 s41, s1, 0
	s_add_u32 s42, s0, s53
	s_addc_u32 s43, s1, 0
	s_add_u32 s44, s0, s54
	s_addc_u32 s45, s1, 0
	s_add_u32 s46, s0, s55
	s_addc_u32 s47, s1, 0
	global_load_dwordx4 v[176:179], v234, s[32:33]
	global_load_dwordx4 v[180:183], v234, s[34:35]
	global_load_dwordx4 v[184:187], v234, s[36:37]
	global_load_dwordx4 v[188:191], v234, s[38:39]
	global_load_dwordx4 v[192:195], v234, s[40:41]
	global_load_dwordx4 v[196:199], v234, s[42:43]
	global_load_dwordx4 v[200:203], v234, s[44:45]
	global_load_dwordx4 v[204:207], v234, s[46:47]
	s_waitcnt vmcnt(8)
	v_cvt_pk_f32_fp8_e32 v[214:215], v144
	v_cvt_pk_f32_fp8_sdwa v[216:217], v144 src0_sel:WORD_1
	v_cvt_pk_f32_fp8_e32 v[218:219], v145
	v_cvt_pk_f32_fp8_sdwa v[220:221], v145 src0_sel:WORD_1
	v_pk_mul_f32 v[222:223], v[0:1], v[214:215]
	v_pk_mul_f32 v[224:225], v[2:3], v[216:217]
	v_cvt_pk_f32_fp8_e32 v[214:215], v146
	v_cvt_pk_f32_fp8_sdwa v[216:217], v146 src0_sel:WORD_1
	v_pk_fma_f32 v[222:223], v[4:5], v[218:219], v[222:223]
	v_pk_fma_f32 v[224:225], v[6:7], v[220:221], v[224:225]
	v_cvt_pk_f32_fp8_e32 v[218:219], v147
	v_cvt_pk_f32_fp8_sdwa v[220:221], v147 src0_sel:WORD_1
	v_pk_fma_f32 v[222:223], v[8:9], v[214:215], v[222:223]
	v_pk_fma_f32 v[224:225], v[10:11], v[216:217], v[224:225]
	v_pk_fma_f32 v[222:223], v[12:13], v[218:219], v[222:223]
	v_pk_fma_f32 v[224:225], v[14:15], v[220:221], v[224:225]
	v_pk_add_f32 v[222:223], v[222:223], v[224:225]
	s_nop 0
	v_add_f32_e32 v226, v222, v223
	v_cvt_pk_f32_fp8_e32 v[214:215], v148
	v_cvt_pk_f32_fp8_sdwa v[216:217], v148 src0_sel:WORD_1
	v_cvt_pk_f32_fp8_e32 v[218:219], v149
	v_cvt_pk_f32_fp8_sdwa v[220:221], v149 src0_sel:WORD_1
	v_pk_mul_f32 v[222:223], v[0:1], v[214:215]
	v_pk_mul_f32 v[224:225], v[2:3], v[216:217]
	v_cvt_pk_f32_fp8_e32 v[214:215], v150
	v_cvt_pk_f32_fp8_sdwa v[216:217], v150 src0_sel:WORD_1
	v_pk_fma_f32 v[222:223], v[4:5], v[218:219], v[222:223]
	v_pk_fma_f32 v[224:225], v[6:7], v[220:221], v[224:225]
	v_cvt_pk_f32_fp8_e32 v[218:219], v151
	v_cvt_pk_f32_fp8_sdwa v[220:221], v151 src0_sel:WORD_1
	v_pk_fma_f32 v[222:223], v[8:9], v[214:215], v[222:223]
	v_pk_fma_f32 v[224:225], v[10:11], v[216:217], v[224:225]
	v_pk_fma_f32 v[222:223], v[12:13], v[218:219], v[222:223]
	v_pk_fma_f32 v[224:225], v[14:15], v[220:221], v[224:225]
	v_pk_add_f32 v[222:223], v[222:223], v[224:225]
	s_nop 0
	v_add_f32_e32 v227, v222, v223
	v_cvt_pk_f32_fp8_e32 v[214:215], v152
	v_cvt_pk_f32_fp8_sdwa v[216:217], v152 src0_sel:WORD_1
	v_cvt_pk_f32_fp8_e32 v[218:219], v153
	v_cvt_pk_f32_fp8_sdwa v[220:221], v153 src0_sel:WORD_1
	v_pk_mul_f32 v[222:223], v[0:1], v[214:215]
	v_pk_mul_f32 v[224:225], v[2:3], v[216:217]
	v_cvt_pk_f32_fp8_e32 v[214:215], v154
	v_cvt_pk_f32_fp8_sdwa v[216:217], v154 src0_sel:WORD_1
	v_pk_fma_f32 v[222:223], v[4:5], v[218:219], v[222:223]
	v_pk_fma_f32 v[224:225], v[6:7], v[220:221], v[224:225]
	v_cvt_pk_f32_fp8_e32 v[218:219], v155
	v_cvt_pk_f32_fp8_sdwa v[220:221], v155 src0_sel:WORD_1
	v_pk_fma_f32 v[222:223], v[8:9], v[214:215], v[222:223]
	v_pk_fma_f32 v[224:225], v[10:11], v[216:217], v[224:225]
	v_pk_fma_f32 v[222:223], v[12:13], v[218:219], v[222:223]
	v_pk_fma_f32 v[224:225], v[14:15], v[220:221], v[224:225]
	v_pk_add_f32 v[222:223], v[222:223], v[224:225]
	s_nop 0
	v_add_f32_e32 v228, v222, v223
	v_cvt_pk_f32_fp8_e32 v[214:215], v156
	v_cvt_pk_f32_fp8_sdwa v[216:217], v156 src0_sel:WORD_1
	v_cvt_pk_f32_fp8_e32 v[218:219], v157
	v_cvt_pk_f32_fp8_sdwa v[220:221], v157 src0_sel:WORD_1
	v_pk_mul_f32 v[222:223], v[0:1], v[214:215]
	v_pk_mul_f32 v[224:225], v[2:3], v[216:217]
	v_cvt_pk_f32_fp8_e32 v[214:215], v158
	v_cvt_pk_f32_fp8_sdwa v[216:217], v158 src0_sel:WORD_1
	v_pk_fma_f32 v[222:223], v[4:5], v[218:219], v[222:223]
	v_pk_fma_f32 v[224:225], v[6:7], v[220:221], v[224:225]
	v_cvt_pk_f32_fp8_e32 v[218:219], v159
	v_cvt_pk_f32_fp8_sdwa v[220:221], v159 src0_sel:WORD_1
	v_pk_fma_f32 v[222:223], v[8:9], v[214:215], v[222:223]
	v_pk_fma_f32 v[224:225], v[10:11], v[216:217], v[224:225]
	v_pk_fma_f32 v[222:223], v[12:13], v[218:219], v[222:223]
	v_pk_fma_f32 v[224:225], v[14:15], v[220:221], v[224:225]
	v_pk_add_f32 v[222:223], v[222:223], v[224:225]
	s_nop 0
	v_add_f32_e32 v229, v222, v223
	v_cvt_pk_f32_fp8_e32 v[214:215], v160
	v_cvt_pk_f32_fp8_sdwa v[216:217], v160 src0_sel:WORD_1
	v_cvt_pk_f32_fp8_e32 v[218:219], v161
	v_cvt_pk_f32_fp8_sdwa v[220:221], v161 src0_sel:WORD_1
	v_pk_mul_f32 v[222:223], v[0:1], v[214:215]
	v_pk_mul_f32 v[224:225], v[2:3], v[216:217]
	v_cvt_pk_f32_fp8_e32 v[214:215], v162
	v_cvt_pk_f32_fp8_sdwa v[216:217], v162 src0_sel:WORD_1
	v_pk_fma_f32 v[222:223], v[4:5], v[218:219], v[222:223]
	v_pk_fma_f32 v[224:225], v[6:7], v[220:221], v[224:225]
	v_cvt_pk_f32_fp8_e32 v[218:219], v163
	v_cvt_pk_f32_fp8_sdwa v[220:221], v163 src0_sel:WORD_1
	v_pk_fma_f32 v[222:223], v[8:9], v[214:215], v[222:223]
	v_pk_fma_f32 v[224:225], v[10:11], v[216:217], v[224:225]
	v_pk_fma_f32 v[222:223], v[12:13], v[218:219], v[222:223]
	v_pk_fma_f32 v[224:225], v[14:15], v[220:221], v[224:225]
	v_pk_add_f32 v[222:223], v[222:223], v[224:225]
	s_nop 0
	v_add_f32_e32 v230, v222, v223
	v_cvt_pk_f32_fp8_e32 v[214:215], v164
; template <bool STORE>
; DI void peer_item(const Params& p, int item, char* smem) {
;     ...
;       float part[8];
; #pragma unroll
;       for (int u = 0; u < 8; ++u) {
;         float d = 0.f;
; #pragma unroll
;         for (int i = 0; i < 4; ++i) {
;           f32x2_t lo = __builtin_amdgcn_cvt_pk_f32_fp8((int)uq[u][i], false);
;           f32x2_t hi = __builtin_amdgcn_cvt_pk_f32_fp8((int)uq[u][i], true);
;           d += xf[4 * i] * lo.x + xf[4 * i + 1] * lo.y + xf[4 * i + 2] * hi.x + xf[4 * i + 3] * hi.y;
;         }
;         part[u] = d;
;       }
;       float q4[4], r2[2], h;
; #pragma unroll
;       for (int j = 0; j < 4; ++j) {
;         float mine = b5 ? part[j + 4] : part[j];
;         float other = b5 ? part[j] : part[j + 4];
;         q4[j] = mine + __shfl_xor(other, 32);
;       }
; #pragma unroll
;       for (int j = 0; j < 2; ++j) {
;         float mine = b4 ? q4[j + 2] : q4[j];
;         float other = b4 ? q4[j] : q4[j + 2];
;         r2[j] = mine + __shfl_xor(other, 16);
;       }
;       {
;         float mine = b3 ? r2[1] : r2[0];
;         float other = b3 ? r2[0] : r2[1];
;         h = mine + __shfl_xor(other, 8);
;       }
;       h += __shfl_xor(h, 4);
;       h += __shfl_xor(h, 2);
;       h += __shfl_xor(h, 1);
	v_cvt_pk_f32_fp8_sdwa v[216:217], v164 src0_sel:WORD_1
	v_cvt_pk_f32_fp8_e32 v[218:219], v165
	v_cvt_pk_f32_fp8_sdwa v[220:221], v165 src0_sel:WORD_1
	v_pk_mul_f32 v[222:223], v[0:1], v[214:215]
	v_pk_mul_f32 v[224:225], v[2:3], v[216:217]
	v_cvt_pk_f32_fp8_e32 v[214:215], v166
	v_cvt_pk_f32_fp8_sdwa v[216:217], v166 src0_sel:WORD_1
	v_pk_fma_f32 v[222:223], v[4:5], v[218:219], v[222:223]
	v_pk_fma_f32 v[224:225], v[6:7], v[220:221], v[224:225]
	v_cvt_pk_f32_fp8_e32 v[218:219], v167
	v_cvt_pk_f32_fp8_sdwa v[220:221], v167 src0_sel:WORD_1
	v_pk_fma_f32 v[222:223], v[8:9], v[214:215], v[222:223]
	v_pk_fma_f32 v[224:225], v[10:11], v[216:217], v[224:225]
	v_pk_fma_f32 v[222:223], v[12:13], v[218:219], v[222:223]
	v_pk_fma_f32 v[224:225], v[14:15], v[220:221], v[224:225]
	v_pk_add_f32 v[222:223], v[222:223], v[224:225]
	s_nop 0
	v_add_f32_e32 v231, v222, v223
	v_cvt_pk_f32_fp8_e32 v[214:215], v168
	v_cvt_pk_f32_fp8_sdwa v[216:217], v168 src0_sel:WORD_1
	v_cvt_pk_f32_fp8_e32 v[218:219], v169
	v_cvt_pk_f32_fp8_sdwa v[220:221], v169 src0_sel:WORD_1
	v_pk_mul_f32 v[222:223], v[0:1], v[214:215]
	v_pk_mul_f32 v[224:225], v[2:3], v[216:217]
	v_cvt_pk_f32_fp8_e32 v[214:215], v170
	v_cvt_pk_f32_fp8_sdwa v[216:217], v170 src0_sel:WORD_1
	v_pk_fma_f32 v[222:223], v[4:5], v[218:219], v[222:223]
	v_pk_fma_f32 v[224:225], v[6:7], v[220:221], v[224:225]
	v_cvt_pk_f32_fp8_e32 v[218:219], v171
	v_cvt_pk_f32_fp8_sdwa v[220:221], v171 src0_sel:WORD_1
	v_pk_fma_f32 v[222:223], v[8:9], v[214:215], v[222:223]
	v_pk_fma_f32 v[224:225], v[10:11], v[216:217], v[224:225]
	v_pk_fma_f32 v[222:223], v[12:13], v[218:219], v[222:223]
	v_pk_fma_f32 v[224:225], v[14:15], v[220:221], v[224:225]
	v_pk_add_f32 v[222:223], v[222:223], v[224:225]
	s_nop 0
	v_add_f32_e32 v232, v222, v223
	v_cvt_pk_f32_fp8_e32 v[214:215], v172
	v_cvt_pk_f32_fp8_sdwa v[216:217], v172 src0_sel:WORD_1
	v_cvt_pk_f32_fp8_e32 v[218:219], v173
	v_cvt_pk_f32_fp8_sdwa v[220:221], v173 src0_sel:WORD_1
	v_pk_mul_f32 v[222:223], v[0:1], v[214:215]
	v_pk_mul_f32 v[224:225], v[2:3], v[216:217]
	v_cvt_pk_f32_fp8_e32 v[214:215], v174
	v_cvt_pk_f32_fp8_sdwa v[216:217], v174 src0_sel:WORD_1
	v_pk_fma_f32 v[222:223], v[4:5], v[218:219], v[222:223]
	v_pk_fma_f32 v[224:225], v[6:7], v[220:221], v[224:225]
	v_cvt_pk_f32_fp8_e32 v[218:219], v175
	v_cvt_pk_f32_fp8_sdwa v[220:221], v175 src0_sel:WORD_1
	v_pk_fma_f32 v[222:223], v[8:9], v[214:215], v[222:223]
	v_pk_fma_f32 v[224:225], v[10:11], v[216:217], v[224:225]
	v_pk_fma_f32 v[222:223], v[12:13], v[218:219], v[222:223]
	v_pk_fma_f32 v[224:225], v[14:15], v[220:221], v[224:225]
	v_pk_add_f32 v[222:223], v[222:223], v[224:225]
	s_nop 0
	v_add_f32_e32 v233, v222, v223
	v_permlane32_swap_b32_e32 v226, v230
	v_permlane32_swap_b32_e32 v227, v231
	v_permlane32_swap_b32_e32 v228, v232
	v_permlane32_swap_b32_e32 v229, v233
	v_add_f32_e32 v226, v226, v230
	v_add_f32_e32 v228, v228, v232
	v_add_f32_e32 v227, v227, v231
	v_add_f32_e32 v229, v229, v233
	s_nop 1
	v_permlane16_swap_b32_e32 v226, v228
	v_permlane16_swap_b32_e32 v227, v229
	v_add_f32_e32 v226, v226, v228
	v_add_f32_e32 v227, v227, v229
	s_nop 0
	v_cndmask_b32_e64 v230, v226, v227, s[24:25]
	v_cndmask_b32_e64 v231, v227, v226, s[24:25]
	s_nop 1
	v_add_f32_dpp v232, v231, v230 row_ror:8 row_mask:0xf bank_mask:0xf
	s_nop 1
	v_add_f32_dpp v233, v232, v232 quad_perm:[1,0,3,2] row_mask:0xf bank_mask:0xf
	s_nop 1
	v_add_f32_dpp v232, v233, v233 quad_perm:[2,3,0,1] row_mask:0xf bank_mask:0xf
	s_nop 1
	v_add_f32_dpp v233, v232, v232 row_half_mirror row_mask:0xf bank_mask:0xf
	ds_write_b32 v235, v233 offset:32768
	v_readlane_b32 s48, v132, s72
	v_readlane_b32 s49, v132, s73
	v_readlane_b32 s50, v132, s74
	v_readlane_b32 s51, v132, s75
	v_readlane_b32 s52, v132, s76
	v_readlane_b32 s53, v132, s77
	v_readlane_b32 s54, v132, s78
	v_readlane_b32 s55, v132, s79
	s_add_u32 s32, s0, s48
	s_addc_u32 s33, s1, 0
	s_add_u32 s34, s0, s49
	s_addc_u32 s35, s1, 0
	s_add_u32 s36, s0, s50
	s_addc_u32 s37, s1, 0
	s_add_u32 s38, s0, s51
	s_addc_u32 s39, s1, 0
	s_add_u32 s40, s0, s52
	s_addc_u32 s41, s1, 0
	s_add_u32 s42, s0, s53
	s_addc_u32 s43, s1, 0
	s_add_u32 s44, s0, s54
	s_addc_u32 s45, s1, 0
	s_add_u32 s46, s0, s55
	s_addc_u32 s47, s1, 0
	global_load_dwordx4 v[144:147], v234, s[32:33]
	global_load_dwordx4 v[148:151], v234, s[34:35]
	global_load_dwordx4 v[152:155], v234, s[36:37]
	global_load_dwordx4 v[156:159], v234, s[38:39]
	global_load_dwordx4 v[160:163], v234, s[40:41]
	global_load_dwordx4 v[164:167], v234, s[42:43]
	global_load_dwordx4 v[168:171], v234, s[44:45]
	global_load_dwordx4 v[172:175], v234, s[46:47]
	s_waitcnt vmcnt(8)
; template <bool STORE>
; DI void peer_item(const Params& p, int item, char* smem) {
;     ...
; #pragma unroll
;       for (int u = 0; u < 8; ++u) {
;         int e = e_s[tl * 128 + k + u];
;         uq[u] = *(const u32x4*)(U8 + (size_t)e * 1024 + lane * 16);
;       }
;       float part[8];
; #pragma unroll
;       for (int u = 0; u < 8; ++u) {
;         float d = 0.f;
; #pragma unroll
;         for (int i = 0; i < 4; ++i) {
;           f32x2_t lo = __builtin_amdgcn_cvt_pk_f32_fp8((int)uq[u][i], false);
;           f32x2_t hi = __builtin_amdgcn_cvt_pk_f32_fp8((int)uq[u][i], true);
;           d += xf[4 * i] * lo.x + xf[4 * i + 1] * lo.y + xf[4 * i + 2] * hi.x + xf[4 * i + 3] * hi.y;
;         }
;         part[u] = d;
;       }
	v_cvt_pk_f32_fp8_e32 v[214:215], v176
	v_cvt_pk_f32_fp8_sdwa v[216:217], v176 src0_sel:WORD_1
	v_cvt_pk_f32_fp8_e32 v[218:219], v177
	v_cvt_pk_f32_fp8_sdwa v[220:221], v177 src0_sel:WORD_1
	v_pk_mul_f32 v[222:223], v[16:17], v[214:215]
	v_pk_mul_f32 v[224:225], v[18:19], v[216:217]
	v_cvt_pk_f32_fp8_e32 v[214:215], v178
	v_cvt_pk_f32_fp8_sdwa v[216:217], v178 src0_sel:WORD_1
	v_pk_fma_f32 v[222:223], v[20:21], v[218:219], v[222:223]
	v_pk_fma_f32 v[224:225], v[22:23], v[220:221], v[224:225]
	v_cvt_pk_f32_fp8_e32 v[218:219], v179
	v_cvt_pk_f32_fp8_sdwa v[220:221], v179 src0_sel:WORD_1
	v_pk_fma_f32 v[222:223], v[24:25], v[214:215], v[222:223]
	v_pk_fma_f32 v[224:225], v[26:27], v[216:217], v[224:225]
	v_pk_fma_f32 v[222:223], v[28:29], v[218:219], v[222:223]
	v_pk_fma_f32 v[224:225], v[30:31], v[220:221], v[224:225]
	v_pk_add_f32 v[222:223], v[222:223], v[224:225]
	s_nop 0
	v_add_f32_e32 v226, v222, v223
	v_cvt_pk_f32_fp8_e32 v[214:215], v180
	v_cvt_pk_f32_fp8_sdwa v[216:217], v180 src0_sel:WORD_1
	v_cvt_pk_f32_fp8_e32 v[218:219], v181
	v_cvt_pk_f32_fp8_sdwa v[220:221], v181 src0_sel:WORD_1
	v_pk_mul_f32 v[222:223], v[16:17], v[214:215]
	v_pk_mul_f32 v[224:225], v[18:19], v[216:217]
	v_cvt_pk_f32_fp8_e32 v[214:215], v182
	v_cvt_pk_f32_fp8_sdwa v[216:217], v182 src0_sel:WORD_1
	v_pk_fma_f32 v[222:223], v[20:21], v[218:219], v[222:223]
	v_pk_fma_f32 v[224:225], v[22:23], v[220:221], v[224:225]
	v_cvt_pk_f32_fp8_e32 v[218:219], v183
	v_cvt_pk_f32_fp8_sdwa v[220:221], v183 src0_sel:WORD_1
	v_pk_fma_f32 v[222:223], v[24:25], v[214:215], v[222:223]
	v_pk_fma_f32 v[224:225], v[26:27], v[216:217], v[224:225]
	v_pk_fma_f32 v[222:223], v[28:29], v[218:219], v[222:223]
	v_pk_fma_f32 v[224:225], v[30:31], v[220:221], v[224:225]
	v_pk_add_f32 v[222:223], v[222:223], v[224:225]
	s_nop 0
	v_add_f32_e32 v227, v222, v223
	v_cvt_pk_f32_fp8_e32 v[214:215], v184
	v_cvt_pk_f32_fp8_sdwa v[216:217], v184 src0_sel:WORD_1
	v_cvt_pk_f32_fp8_e32 v[218:219], v185
	v_cvt_pk_f32_fp8_sdwa v[220:221], v185 src0_sel:WORD_1
	v_pk_mul_f32 v[222:223], v[16:17], v[214:215]
	v_pk_mul_f32 v[224:225], v[18:19], v[216:217]
	v_cvt_pk_f32_fp8_e32 v[214:215], v186
	v_cvt_pk_f32_fp8_sdwa v[216:217], v186 src0_sel:WORD_1
	v_pk_fma_f32 v[222:223], v[20:21], v[218:219], v[222:223]
	v_pk_fma_f32 v[224:225], v[22:23], v[220:221], v[224:225]
	v_cvt_pk_f32_fp8_e32 v[218:219], v187
	v_cvt_pk_f32_fp8_sdwa v[220:221], v187 src0_sel:WORD_1
	v_pk_fma_f32 v[222:223], v[24:25], v[214:215], v[222:223]
	v_pk_fma_f32 v[224:225], v[26:27], v[216:217], v[224:225]
	v_pk_fma_f32 v[222:223], v[28:29], v[218:219], v[222:223]
	v_pk_fma_f32 v[224:225], v[30:31], v[220:221], v[224:225]
	v_pk_add_f32 v[222:223], v[222:223], v[224:225]
	s_nop 0
	v_add_f32_e32 v228, v222, v223
	v_cvt_pk_f32_fp8_e32 v[214:215], v188
	v_cvt_pk_f32_fp8_sdwa v[216:217], v188 src0_sel:WORD_1
	v_cvt_pk_f32_fp8_e32 v[218:219], v189
	v_cvt_pk_f32_fp8_sdwa v[220:221], v189 src0_sel:WORD_1
	v_pk_mul_f32 v[222:223], v[16:17], v[214:215]
	v_pk_mul_f32 v[224:225], v[18:19], v[216:217]
	v_cvt_pk_f32_fp8_e32 v[214:215], v190
	v_cvt_pk_f32_fp8_sdwa v[216:217], v190 src0_sel:WORD_1
	v_pk_fma_f32 v[222:223], v[20:21], v[218:219], v[222:223]
	v_pk_fma_f32 v[224:225], v[22:23], v[220:221], v[224:225]
	v_cvt_pk_f32_fp8_e32 v[218:219], v191
	v_cvt_pk_f32_fp8_sdwa v[220:221], v191 src0_sel:WORD_1
	v_pk_fma_f32 v[222:223], v[24:25], v[214:215], v[222:223]
	v_pk_fma_f32 v[224:225], v[26:27], v[216:217], v[224:225]
	v_pk_fma_f32 v[222:223], v[28:29], v[218:219], v[222:223]
	v_pk_fma_f32 v[224:225], v[30:31], v[220:221], v[224:225]
	v_pk_add_f32 v[222:223], v[222:223], v[224:225]
	s_nop 0
	v_add_f32_e32 v229, v222, v223
	v_cvt_pk_f32_fp8_e32 v[214:215], v192
	v_cvt_pk_f32_fp8_sdwa v[216:217], v192 src0_sel:WORD_1
	v_cvt_pk_f32_fp8_e32 v[218:219], v193
	v_cvt_pk_f32_fp8_sdwa v[220:221], v193 src0_sel:WORD_1
	v_pk_mul_f32 v[222:223], v[16:17], v[214:215]
	v_pk_mul_f32 v[224:225], v[18:19], v[216:217]
	v_cvt_pk_f32_fp8_e32 v[214:215], v194
	v_cvt_pk_f32_fp8_sdwa v[216:217], v194 src0_sel:WORD_1
	v_pk_fma_f32 v[222:223], v[20:21], v[218:219], v[222:223]
	v_pk_fma_f32 v[224:225], v[22:23], v[220:221], v[224:225]
	v_cvt_pk_f32_fp8_e32 v[218:219], v195
	v_cvt_pk_f32_fp8_sdwa v[220:221], v195 src0_sel:WORD_1
	v_pk_fma_f32 v[222:223], v[24:25], v[214:215], v[222:223]
	v_pk_fma_f32 v[224:225], v[26:27], v[216:217], v[224:225]
	v_pk_fma_f32 v[222:223], v[28:29], v[218:219], v[222:223]
	v_pk_fma_f32 v[224:225], v[30:31], v[220:221], v[224:225]
	v_pk_add_f32 v[222:223], v[222:223], v[224:225]
	s_nop 0
	v_add_f32_e32 v230, v222, v223
	v_cvt_pk_f32_fp8_e32 v[214:215], v196
	v_cvt_pk_f32_fp8_sdwa v[216:217], v196 src0_sel:WORD_1
	v_cvt_pk_f32_fp8_e32 v[218:219], v197
	v_cvt_pk_f32_fp8_sdwa v[220:221], v197 src0_sel:WORD_1
	v_pk_mul_f32 v[222:223], v[16:17], v[214:215]
	v_pk_mul_f32 v[224:225], v[18:19], v[216:217]
	v_cvt_pk_f32_fp8_e32 v[214:215], v198
	v_cvt_pk_f32_fp8_sdwa v[216:217], v198 src0_sel:WORD_1
	v_pk_fma_f32 v[222:223], v[20:21], v[218:219], v[222:223]
	v_pk_fma_f32 v[224:225], v[22:23], v[220:221], v[224:225]
	v_cvt_pk_f32_fp8_e32 v[218:219], v199
	v_cvt_pk_f32_fp8_sdwa v[220:221], v199 src0_sel:WORD_1
	v_pk_fma_f32 v[222:223], v[24:25], v[214:215], v[222:223]
	v_pk_fma_f32 v[224:225], v[26:27], v[216:217], v[224:225]
	v_pk_fma_f32 v[222:223], v[28:29], v[218:219], v[222:223]
	v_pk_fma_f32 v[224:225], v[30:31], v[220:221], v[224:225]
	v_pk_add_f32 v[222:223], v[222:223], v[224:225]
	s_nop 0
	v_add_f32_e32 v231, v222, v223
	v_cvt_pk_f32_fp8_e32 v[214:215], v200
	v_cvt_pk_f32_fp8_sdwa v[216:217], v200 src0_sel:WORD_1
	v_cvt_pk_f32_fp8_e32 v[218:219], v201
; template <bool STORE>
; DI void peer_item(const Params& p, int item, char* smem) {
;     ...
; #pragma unroll
;       for (int u = 0; u < 8; ++u) {
;         int e = e_s[tl * 128 + k + u];
;         uq[u] = *(const u32x4*)(U8 + (size_t)e * 1024 + lane * 16);
;       }
;       float part[8];
; #pragma unroll
;       for (int u = 0; u < 8; ++u) {
;         float d = 0.f;
; #pragma unroll
;         for (int i = 0; i < 4; ++i) {
;           f32x2_t lo = __builtin_amdgcn_cvt_pk_f32_fp8((int)uq[u][i], false);
;           f32x2_t hi = __builtin_amdgcn_cvt_pk_f32_fp8((int)uq[u][i], true);
;           d += xf[4 * i] * lo.x + xf[4 * i + 1] * lo.y + xf[4 * i + 2] * hi.x + xf[4 * i + 3] * hi.y;
;         }
;         part[u] = d;
;       }
;       float q4[4], r2[2], h;
; #pragma unroll
;       for (int j = 0; j < 4; ++j) {
;         float mine = b5 ? part[j + 4] : part[j];
;         float other = b5 ? part[j] : part[j + 4];
;         q4[j] = mine + __shfl_xor(other, 32);
;       }
; #pragma unroll
;       for (int j = 0; j < 2; ++j) {
;         float mine = b4 ? q4[j + 2] : q4[j];
;         float other = b4 ? q4[j] : q4[j + 2];
;         r2[j] = mine + __shfl_xor(other, 16);
;       }
;       {
;         float mine = b3 ? r2[1] : r2[0];
;         float other = b3 ? r2[0] : r2[1];
;         h = mine + __shfl_xor(other, 8);
;       }
;       h += __shfl_xor(h, 4);
;       h += __shfl_xor(h, 2);
;       h += __shfl_xor(h, 1);
	v_cvt_pk_f32_fp8_sdwa v[220:221], v201 src0_sel:WORD_1
	v_pk_mul_f32 v[222:223], v[16:17], v[214:215]
	v_pk_mul_f32 v[224:225], v[18:19], v[216:217]
	v_cvt_pk_f32_fp8_e32 v[214:215], v202
	v_cvt_pk_f32_fp8_sdwa v[216:217], v202 src0_sel:WORD_1
	v_pk_fma_f32 v[222:223], v[20:21], v[218:219], v[222:223]
	v_pk_fma_f32 v[224:225], v[22:23], v[220:221], v[224:225]
	v_cvt_pk_f32_fp8_e32 v[218:219], v203
	v_cvt_pk_f32_fp8_sdwa v[220:221], v203 src0_sel:WORD_1
	v_pk_fma_f32 v[222:223], v[24:25], v[214:215], v[222:223]
	v_pk_fma_f32 v[224:225], v[26:27], v[216:217], v[224:225]
	v_pk_fma_f32 v[222:223], v[28:29], v[218:219], v[222:223]
	v_pk_fma_f32 v[224:225], v[30:31], v[220:221], v[224:225]
	v_pk_add_f32 v[222:223], v[222:223], v[224:225]
	s_nop 0
	v_add_f32_e32 v232, v222, v223
	v_cvt_pk_f32_fp8_e32 v[214:215], v204
	v_cvt_pk_f32_fp8_sdwa v[216:217], v204 src0_sel:WORD_1
	v_cvt_pk_f32_fp8_e32 v[218:219], v205
	v_cvt_pk_f32_fp8_sdwa v[220:221], v205 src0_sel:WORD_1
	v_pk_mul_f32 v[222:223], v[16:17], v[214:215]
	v_pk_mul_f32 v[224:225], v[18:19], v[216:217]
	v_cvt_pk_f32_fp8_e32 v[214:215], v206
	v_cvt_pk_f32_fp8_sdwa v[216:217], v206 src0_sel:WORD_1
	v_pk_fma_f32 v[222:223], v[20:21], v[218:219], v[222:223]
	v_pk_fma_f32 v[224:225], v[22:23], v[220:221], v[224:225]
	v_cvt_pk_f32_fp8_e32 v[218:219], v207
	v_cvt_pk_f32_fp8_sdwa v[220:221], v207 src0_sel:WORD_1
	v_pk_fma_f32 v[222:223], v[24:25], v[214:215], v[222:223]
	v_pk_fma_f32 v[224:225], v[26:27], v[216:217], v[224:225]
	v_pk_fma_f32 v[222:223], v[28:29], v[218:219], v[222:223]
	v_pk_fma_f32 v[224:225], v[30:31], v[220:221], v[224:225]
	v_pk_add_f32 v[222:223], v[222:223], v[224:225]
	s_nop 0
	v_add_f32_e32 v233, v222, v223
	v_permlane32_swap_b32_e32 v226, v230
	v_permlane32_swap_b32_e32 v227, v231
	v_permlane32_swap_b32_e32 v228, v232
	v_permlane32_swap_b32_e32 v229, v233
	v_add_f32_e32 v226, v226, v230
	v_add_f32_e32 v228, v228, v232
	v_add_f32_e32 v227, v227, v231
	v_add_f32_e32 v229, v229, v233
	s_nop 1
	v_permlane16_swap_b32_e32 v226, v228
	v_permlane16_swap_b32_e32 v227, v229
	v_add_f32_e32 v226, v226, v228
	v_add_f32_e32 v227, v227, v229
	s_nop 0
	v_cndmask_b32_e64 v230, v226, v227, s[24:25]
	v_cndmask_b32_e64 v231, v227, v226, s[24:25]
	s_nop 1
	v_add_f32_dpp v232, v231, v230 row_ror:8 row_mask:0xf bank_mask:0xf
	s_nop 1
	v_add_f32_dpp v233, v232, v232 quad_perm:[1,0,3,2] row_mask:0xf bank_mask:0xf
	s_nop 1
	v_add_f32_dpp v232, v233, v233 quad_perm:[2,3,0,1] row_mask:0xf bank_mask:0xf
	s_nop 1
	v_add_f32_dpp v233, v232, v232 row_half_mirror row_mask:0xf bank_mask:0xf
	ds_write_b32 v235, v233 offset:33280
	v_readlane_b32 s48, v134, s72
	v_readlane_b32 s49, v134, s73
	v_readlane_b32 s50, v134, s74
	v_readlane_b32 s51, v134, s75
	v_readlane_b32 s52, v134, s76
	v_readlane_b32 s53, v134, s77
	v_readlane_b32 s54, v134, s78
	v_readlane_b32 s55, v134, s79
	s_add_u32 s32, s0, s48
	s_addc_u32 s33, s1, 0
	s_add_u32 s34, s0, s49
	s_addc_u32 s35, s1, 0
	s_add_u32 s36, s0, s50
	s_addc_u32 s37, s1, 0
	s_add_u32 s38, s0, s51
	s_addc_u32 s39, s1, 0
	s_add_u32 s40, s0, s52
	s_addc_u32 s41, s1, 0
	s_add_u32 s42, s0, s53
	s_addc_u32 s43, s1, 0
	s_add_u32 s44, s0, s54
	s_addc_u32 s45, s1, 0
	s_add_u32 s46, s0, s55
	s_addc_u32 s47, s1, 0
	global_load_dwordx4 v[176:179], v234, s[32:33]
	global_load_dwordx4 v[180:183], v234, s[34:35]
	global_load_dwordx4 v[184:187], v234, s[36:37]
	global_load_dwordx4 v[188:191], v234, s[38:39]
	global_load_dwordx4 v[192:195], v234, s[40:41]
	global_load_dwordx4 v[196:199], v234, s[42:43]
	global_load_dwordx4 v[200:203], v234, s[44:45]
	global_load_dwordx4 v[204:207], v234, s[46:47]
	s_waitcnt vmcnt(8)
	v_cvt_pk_f32_fp8_e32 v[214:215], v144
	v_cvt_pk_f32_fp8_sdwa v[216:217], v144 src0_sel:WORD_1
	v_cvt_pk_f32_fp8_e32 v[218:219], v145
	v_cvt_pk_f32_fp8_sdwa v[220:221], v145 src0_sel:WORD_1
	v_pk_mul_f32 v[222:223], v[32:33], v[214:215]
	v_pk_mul_f32 v[224:225], v[34:35], v[216:217]
	v_cvt_pk_f32_fp8_e32 v[214:215], v146
	v_cvt_pk_f32_fp8_sdwa v[216:217], v146 src0_sel:WORD_1
	v_pk_fma_f32 v[222:223], v[36:37], v[218:219], v[222:223]
	v_pk_fma_f32 v[224:225], v[38:39], v[220:221], v[224:225]
	v_cvt_pk_f32_fp8_e32 v[218:219], v147
	v_cvt_pk_f32_fp8_sdwa v[220:221], v147 src0_sel:WORD_1
	v_pk_fma_f32 v[222:223], v[40:41], v[214:215], v[222:223]
	v_pk_fma_f32 v[224:225], v[42:43], v[216:217], v[224:225]
	v_pk_fma_f32 v[222:223], v[44:45], v[218:219], v[222:223]
	v_pk_fma_f32 v[224:225], v[46:47], v[220:221], v[224:225]
	v_pk_add_f32 v[222:223], v[222:223], v[224:225]
	s_nop 0
	v_add_f32_e32 v226, v222, v223
	v_cvt_pk_f32_fp8_e32 v[214:215], v148
	v_cvt_pk_f32_fp8_sdwa v[216:217], v148 src0_sel:WORD_1
	v_cvt_pk_f32_fp8_e32 v[218:219], v149
	v_cvt_pk_f32_fp8_sdwa v[220:221], v149 src0_sel:WORD_1
	v_pk_mul_f32 v[222:223], v[32:33], v[214:215]
	v_pk_mul_f32 v[224:225], v[34:35], v[216:217]
	v_cvt_pk_f32_fp8_e32 v[214:215], v150
	v_cvt_pk_f32_fp8_sdwa v[216:217], v150 src0_sel:WORD_1
	v_pk_fma_f32 v[222:223], v[36:37], v[218:219], v[222:223]
	v_pk_fma_f32 v[224:225], v[38:39], v[220:221], v[224:225]
	v_cvt_pk_f32_fp8_e32 v[218:219], v151
	v_cvt_pk_f32_fp8_sdwa v[220:221], v151 src0_sel:WORD_1
	v_pk_fma_f32 v[222:223], v[40:41], v[214:215], v[222:223]
	v_pk_fma_f32 v[224:225], v[42:43], v[216:217], v[224:225]
	v_pk_fma_f32 v[222:223], v[44:45], v[218:219], v[222:223]
	v_pk_fma_f32 v[224:225], v[46:47], v[220:221], v[224:225]
	v_pk_add_f32 v[222:223], v[222:223], v[224:225]
	s_nop 0
	v_add_f32_e32 v227, v222, v223
	v_cvt_pk_f32_fp8_e32 v[214:215], v152
	v_cvt_pk_f32_fp8_sdwa v[216:217], v152 src0_sel:WORD_1
	v_cvt_pk_f32_fp8_e32 v[218:219], v153
	v_cvt_pk_f32_fp8_sdwa v[220:221], v153 src0_sel:WORD_1
; template <bool STORE>
; DI void peer_item(const Params& p, int item, char* smem) {
;     ...
; #pragma unroll
;       for (int u = 0; u < 8; ++u) {
;         int e = e_s[tl * 128 + k + u];
;         uq[u] = *(const u32x4*)(U8 + (size_t)e * 1024 + lane * 16);
;       }
;       float part[8];
; #pragma unroll
;       for (int u = 0; u < 8; ++u) {
;         float d = 0.f;
; #pragma unroll
;         for (int i = 0; i < 4; ++i) {
;           f32x2_t lo = __builtin_amdgcn_cvt_pk_f32_fp8((int)uq[u][i], false);
;           f32x2_t hi = __builtin_amdgcn_cvt_pk_f32_fp8((int)uq[u][i], true);
;           d += xf[4 * i] * lo.x + xf[4 * i + 1] * lo.y + xf[4 * i + 2] * hi.x + xf[4 * i + 3] * hi.y;
;         }
;         part[u] = d;
;       }
;       float q4[4], r2[2], h;
; #pragma unroll
;       for (int j = 0; j < 4; ++j) {
;         float mine = b5 ? part[j + 4] : part[j];
;         float other = b5 ? part[j] : part[j + 4];
;         q4[j] = mine + __shfl_xor(other, 32);
;       }
; #pragma unroll
;       for (int j = 0; j < 2; ++j) {
;         float mine = b4 ? q4[j + 2] : q4[j];
;         float other = b4 ? q4[j] : q4[j + 2];
;         r2[j] = mine + __shfl_xor(other, 16);
;       }
	v_pk_mul_f32 v[222:223], v[32:33], v[214:215]
	v_pk_mul_f32 v[224:225], v[34:35], v[216:217]
	v_cvt_pk_f32_fp8_e32 v[214:215], v154
	v_cvt_pk_f32_fp8_sdwa v[216:217], v154 src0_sel:WORD_1
	v_pk_fma_f32 v[222:223], v[36:37], v[218:219], v[222:223]
	v_pk_fma_f32 v[224:225], v[38:39], v[220:221], v[224:225]
	v_cvt_pk_f32_fp8_e32 v[218:219], v155
	v_cvt_pk_f32_fp8_sdwa v[220:221], v155 src0_sel:WORD_1
	v_pk_fma_f32 v[222:223], v[40:41], v[214:215], v[222:223]
	v_pk_fma_f32 v[224:225], v[42:43], v[216:217], v[224:225]
	v_pk_fma_f32 v[222:223], v[44:45], v[218:219], v[222:223]
	v_pk_fma_f32 v[224:225], v[46:47], v[220:221], v[224:225]
	v_pk_add_f32 v[222:223], v[222:223], v[224:225]
	s_nop 0
	v_add_f32_e32 v228, v222, v223
	v_cvt_pk_f32_fp8_e32 v[214:215], v156
	v_cvt_pk_f32_fp8_sdwa v[216:217], v156 src0_sel:WORD_1
	v_cvt_pk_f32_fp8_e32 v[218:219], v157
	v_cvt_pk_f32_fp8_sdwa v[220:221], v157 src0_sel:WORD_1
	v_pk_mul_f32 v[222:223], v[32:33], v[214:215]
	v_pk_mul_f32 v[224:225], v[34:35], v[216:217]
	v_cvt_pk_f32_fp8_e32 v[214:215], v158
	v_cvt_pk_f32_fp8_sdwa v[216:217], v158 src0_sel:WORD_1
	v_pk_fma_f32 v[222:223], v[36:37], v[218:219], v[222:223]
	v_pk_fma_f32 v[224:225], v[38:39], v[220:221], v[224:225]
	v_cvt_pk_f32_fp8_e32 v[218:219], v159
	v_cvt_pk_f32_fp8_sdwa v[220:221], v159 src0_sel:WORD_1
	v_pk_fma_f32 v[222:223], v[40:41], v[214:215], v[222:223]
	v_pk_fma_f32 v[224:225], v[42:43], v[216:217], v[224:225]
	v_pk_fma_f32 v[222:223], v[44:45], v[218:219], v[222:223]
	v_pk_fma_f32 v[224:225], v[46:47], v[220:221], v[224:225]
	v_pk_add_f32 v[222:223], v[222:223], v[224:225]
	s_nop 0
	v_add_f32_e32 v229, v222, v223
	v_cvt_pk_f32_fp8_e32 v[214:215], v160
	v_cvt_pk_f32_fp8_sdwa v[216:217], v160 src0_sel:WORD_1
	v_cvt_pk_f32_fp8_e32 v[218:219], v161
	v_cvt_pk_f32_fp8_sdwa v[220:221], v161 src0_sel:WORD_1
	v_pk_mul_f32 v[222:223], v[32:33], v[214:215]
	v_pk_mul_f32 v[224:225], v[34:35], v[216:217]
	v_cvt_pk_f32_fp8_e32 v[214:215], v162
	v_cvt_pk_f32_fp8_sdwa v[216:217], v162 src0_sel:WORD_1
	v_pk_fma_f32 v[222:223], v[36:37], v[218:219], v[222:223]
	v_pk_fma_f32 v[224:225], v[38:39], v[220:221], v[224:225]
	v_cvt_pk_f32_fp8_e32 v[218:219], v163
	v_cvt_pk_f32_fp8_sdwa v[220:221], v163 src0_sel:WORD_1
	v_pk_fma_f32 v[222:223], v[40:41], v[214:215], v[222:223]
	v_pk_fma_f32 v[224:225], v[42:43], v[216:217], v[224:225]
	v_pk_fma_f32 v[222:223], v[44:45], v[218:219], v[222:223]
	v_pk_fma_f32 v[224:225], v[46:47], v[220:221], v[224:225]
	v_pk_add_f32 v[222:223], v[222:223], v[224:225]
	s_nop 0
	v_add_f32_e32 v230, v222, v223
	v_cvt_pk_f32_fp8_e32 v[214:215], v164
	v_cvt_pk_f32_fp8_sdwa v[216:217], v164 src0_sel:WORD_1
	v_cvt_pk_f32_fp8_e32 v[218:219], v165
	v_cvt_pk_f32_fp8_sdwa v[220:221], v165 src0_sel:WORD_1
	v_pk_mul_f32 v[222:223], v[32:33], v[214:215]
	v_pk_mul_f32 v[224:225], v[34:35], v[216:217]
	v_cvt_pk_f32_fp8_e32 v[214:215], v166
	v_cvt_pk_f32_fp8_sdwa v[216:217], v166 src0_sel:WORD_1
	v_pk_fma_f32 v[222:223], v[36:37], v[218:219], v[222:223]
	v_pk_fma_f32 v[224:225], v[38:39], v[220:221], v[224:225]
	v_cvt_pk_f32_fp8_e32 v[218:219], v167
	v_cvt_pk_f32_fp8_sdwa v[220:221], v167 src0_sel:WORD_1
	v_pk_fma_f32 v[222:223], v[40:41], v[214:215], v[222:223]
	v_pk_fma_f32 v[224:225], v[42:43], v[216:217], v[224:225]
	v_pk_fma_f32 v[222:223], v[44:45], v[218:219], v[222:223]
	v_pk_fma_f32 v[224:225], v[46:47], v[220:221], v[224:225]
	v_pk_add_f32 v[222:223], v[222:223], v[224:225]
	s_nop 0
	v_add_f32_e32 v231, v222, v223
	v_cvt_pk_f32_fp8_e32 v[214:215], v168
	v_cvt_pk_f32_fp8_sdwa v[216:217], v168 src0_sel:WORD_1
	v_cvt_pk_f32_fp8_e32 v[218:219], v169
	v_cvt_pk_f32_fp8_sdwa v[220:221], v169 src0_sel:WORD_1
	v_pk_mul_f32 v[222:223], v[32:33], v[214:215]
	v_pk_mul_f32 v[224:225], v[34:35], v[216:217]
	v_cvt_pk_f32_fp8_e32 v[214:215], v170
	v_cvt_pk_f32_fp8_sdwa v[216:217], v170 src0_sel:WORD_1
	v_pk_fma_f32 v[222:223], v[36:37], v[218:219], v[222:223]
	v_pk_fma_f32 v[224:225], v[38:39], v[220:221], v[224:225]
	v_cvt_pk_f32_fp8_e32 v[218:219], v171
	v_cvt_pk_f32_fp8_sdwa v[220:221], v171 src0_sel:WORD_1
	v_pk_fma_f32 v[222:223], v[40:41], v[214:215], v[222:223]
	v_pk_fma_f32 v[224:225], v[42:43], v[216:217], v[224:225]
	v_pk_fma_f32 v[222:223], v[44:45], v[218:219], v[222:223]
	v_pk_fma_f32 v[224:225], v[46:47], v[220:221], v[224:225]
	v_pk_add_f32 v[222:223], v[222:223], v[224:225]
	s_nop 0
	v_add_f32_e32 v232, v222, v223
	v_cvt_pk_f32_fp8_e32 v[214:215], v172
	v_cvt_pk_f32_fp8_sdwa v[216:217], v172 src0_sel:WORD_1
	v_cvt_pk_f32_fp8_e32 v[218:219], v173
	v_cvt_pk_f32_fp8_sdwa v[220:221], v173 src0_sel:WORD_1
	v_pk_mul_f32 v[222:223], v[32:33], v[214:215]
	v_pk_mul_f32 v[224:225], v[34:35], v[216:217]
	v_cvt_pk_f32_fp8_e32 v[214:215], v174
	v_cvt_pk_f32_fp8_sdwa v[216:217], v174 src0_sel:WORD_1
	v_pk_fma_f32 v[222:223], v[36:37], v[218:219], v[222:223]
	v_pk_fma_f32 v[224:225], v[38:39], v[220:221], v[224:225]
	v_cvt_pk_f32_fp8_e32 v[218:219], v175
	v_cvt_pk_f32_fp8_sdwa v[220:221], v175 src0_sel:WORD_1
	v_pk_fma_f32 v[222:223], v[40:41], v[214:215], v[222:223]
	v_pk_fma_f32 v[224:225], v[42:43], v[216:217], v[224:225]
	v_pk_fma_f32 v[222:223], v[44:45], v[218:219], v[222:223]
	v_pk_fma_f32 v[224:225], v[46:47], v[220:221], v[224:225]
	v_pk_add_f32 v[222:223], v[222:223], v[224:225]
	s_nop 0
	v_add_f32_e32 v233, v222, v223
	v_permlane32_swap_b32_e32 v226, v230
	v_permlane32_swap_b32_e32 v227, v231
	v_permlane32_swap_b32_e32 v228, v232
	v_permlane32_swap_b32_e32 v229, v233
	v_add_f32_e32 v226, v226, v230
	v_add_f32_e32 v228, v228, v232
	v_add_f32_e32 v227, v227, v231
	v_add_f32_e32 v229, v229, v233
	s_nop 1
	v_permlane16_swap_b32_e32 v226, v228
; template <bool STORE>
; DI void peer_item(const Params& p, int item, char* smem) {
;     ...
; #pragma unroll
;       for (int u = 0; u < 8; ++u) {
;         int e = e_s[tl * 128 + k + u];
;         uq[u] = *(const u32x4*)(U8 + (size_t)e * 1024 + lane * 16);
;       }
;       float part[8];
; #pragma unroll
;       for (int u = 0; u < 8; ++u) {
;         float d = 0.f;
; #pragma unroll
;         for (int i = 0; i < 4; ++i) {
;           f32x2_t lo = __builtin_amdgcn_cvt_pk_f32_fp8((int)uq[u][i], false);
;           f32x2_t hi = __builtin_amdgcn_cvt_pk_f32_fp8((int)uq[u][i], true);
;           d += xf[4 * i] * lo.x + xf[4 * i + 1] * lo.y + xf[4 * i + 2] * hi.x + xf[4 * i + 3] * hi.y;
;         }
;         part[u] = d;
;       }
;       float q4[4], r2[2], h;
; #pragma unroll
;       for (int j = 0; j < 4; ++j) {
;         float mine = b5 ? part[j + 4] : part[j];
;         float other = b5 ? part[j] : part[j + 4];
;         q4[j] = mine + __shfl_xor(other, 32);
;       }
; #pragma unroll
;       for (int j = 0; j < 2; ++j) {
;         float mine = b4 ? q4[j + 2] : q4[j];
;         float other = b4 ? q4[j] : q4[j + 2];
;         r2[j] = mine + __shfl_xor(other, 16);
;       }
;       {
;         float mine = b3 ? r2[1] : r2[0];
;         float other = b3 ? r2[0] : r2[1];
;         h = mine + __shfl_xor(other, 8);
;       }
;       h += __shfl_xor(h, 4);
;       h += __shfl_xor(h, 2);
;       h += __shfl_xor(h, 1);
	v_permlane16_swap_b32_e32 v227, v229
	v_add_f32_e32 v226, v226, v228
	v_add_f32_e32 v227, v227, v229
	s_nop 0
	v_cndmask_b32_e64 v230, v226, v227, s[24:25]
	v_cndmask_b32_e64 v231, v227, v226, s[24:25]
	s_nop 1
	v_add_f32_dpp v232, v231, v230 row_ror:8 row_mask:0xf bank_mask:0xf
	s_nop 1
	v_add_f32_dpp v233, v232, v232 quad_perm:[1,0,3,2] row_mask:0xf bank_mask:0xf
	s_nop 1
	v_add_f32_dpp v232, v233, v233 quad_perm:[2,3,0,1] row_mask:0xf bank_mask:0xf
	s_nop 1
	v_add_f32_dpp v233, v232, v232 row_half_mirror row_mask:0xf bank_mask:0xf
	ds_write_b32 v235, v233 offset:33792
	v_readlane_b32 s48, v136, s72
	v_readlane_b32 s49, v136, s73
	v_readlane_b32 s50, v136, s74
	v_readlane_b32 s51, v136, s75
	v_readlane_b32 s52, v136, s76
	v_readlane_b32 s53, v136, s77
	v_readlane_b32 s54, v136, s78
	v_readlane_b32 s55, v136, s79
	s_add_u32 s32, s0, s48
	s_addc_u32 s33, s1, 0
	s_add_u32 s34, s0, s49
	s_addc_u32 s35, s1, 0
	s_add_u32 s36, s0, s50
	s_addc_u32 s37, s1, 0
	s_add_u32 s38, s0, s51
	s_addc_u32 s39, s1, 0
	s_add_u32 s40, s0, s52
	s_addc_u32 s41, s1, 0
	s_add_u32 s42, s0, s53
	s_addc_u32 s43, s1, 0
	s_add_u32 s44, s0, s54
	s_addc_u32 s45, s1, 0
	s_add_u32 s46, s0, s55
	s_addc_u32 s47, s1, 0
	global_load_dwordx4 v[144:147], v234, s[32:33]
	global_load_dwordx4 v[148:151], v234, s[34:35]
	global_load_dwordx4 v[152:155], v234, s[36:37]
	global_load_dwordx4 v[156:159], v234, s[38:39]
	global_load_dwordx4 v[160:163], v234, s[40:41]
	global_load_dwordx4 v[164:167], v234, s[42:43]
	global_load_dwordx4 v[168:171], v234, s[44:45]
	global_load_dwordx4 v[172:175], v234, s[46:47]
	s_waitcnt vmcnt(8)
	v_cvt_pk_f32_fp8_e32 v[214:215], v176
	v_cvt_pk_f32_fp8_sdwa v[216:217], v176 src0_sel:WORD_1
	v_cvt_pk_f32_fp8_e32 v[218:219], v177
	v_cvt_pk_f32_fp8_sdwa v[220:221], v177 src0_sel:WORD_1
	v_pk_mul_f32 v[222:223], v[48:49], v[214:215]
	v_pk_mul_f32 v[224:225], v[50:51], v[216:217]
	v_cvt_pk_f32_fp8_e32 v[214:215], v178
	v_cvt_pk_f32_fp8_sdwa v[216:217], v178 src0_sel:WORD_1
	v_pk_fma_f32 v[222:223], v[52:53], v[218:219], v[222:223]
	v_pk_fma_f32 v[224:225], v[54:55], v[220:221], v[224:225]
	v_cvt_pk_f32_fp8_e32 v[218:219], v179
	v_cvt_pk_f32_fp8_sdwa v[220:221], v179 src0_sel:WORD_1
	v_pk_fma_f32 v[222:223], v[56:57], v[214:215], v[222:223]
	v_pk_fma_f32 v[224:225], v[58:59], v[216:217], v[224:225]
	v_pk_fma_f32 v[222:223], v[60:61], v[218:219], v[222:223]
	v_pk_fma_f32 v[224:225], v[62:63], v[220:221], v[224:225]
	v_pk_add_f32 v[222:223], v[222:223], v[224:225]
	s_nop 0
	v_add_f32_e32 v226, v222, v223
	v_cvt_pk_f32_fp8_e32 v[214:215], v180
	v_cvt_pk_f32_fp8_sdwa v[216:217], v180 src0_sel:WORD_1
	v_cvt_pk_f32_fp8_e32 v[218:219], v181
	v_cvt_pk_f32_fp8_sdwa v[220:221], v181 src0_sel:WORD_1
	v_pk_mul_f32 v[222:223], v[48:49], v[214:215]
	v_pk_mul_f32 v[224:225], v[50:51], v[216:217]
	v_cvt_pk_f32_fp8_e32 v[214:215], v182
	v_cvt_pk_f32_fp8_sdwa v[216:217], v182 src0_sel:WORD_1
	v_pk_fma_f32 v[222:223], v[52:53], v[218:219], v[222:223]
	v_pk_fma_f32 v[224:225], v[54:55], v[220:221], v[224:225]
	v_cvt_pk_f32_fp8_e32 v[218:219], v183
	v_cvt_pk_f32_fp8_sdwa v[220:221], v183 src0_sel:WORD_1
	v_pk_fma_f32 v[222:223], v[56:57], v[214:215], v[222:223]
	v_pk_fma_f32 v[224:225], v[58:59], v[216:217], v[224:225]
	v_pk_fma_f32 v[222:223], v[60:61], v[218:219], v[222:223]
	v_pk_fma_f32 v[224:225], v[62:63], v[220:221], v[224:225]
	v_pk_add_f32 v[222:223], v[222:223], v[224:225]
	s_nop 0
	v_add_f32_e32 v227, v222, v223
	v_cvt_pk_f32_fp8_e32 v[214:215], v184
	v_cvt_pk_f32_fp8_sdwa v[216:217], v184 src0_sel:WORD_1
	v_cvt_pk_f32_fp8_e32 v[218:219], v185
	v_cvt_pk_f32_fp8_sdwa v[220:221], v185 src0_sel:WORD_1
	v_pk_mul_f32 v[222:223], v[48:49], v[214:215]
	v_pk_mul_f32 v[224:225], v[50:51], v[216:217]
	v_cvt_pk_f32_fp8_e32 v[214:215], v186
	v_cvt_pk_f32_fp8_sdwa v[216:217], v186 src0_sel:WORD_1
	v_pk_fma_f32 v[222:223], v[52:53], v[218:219], v[222:223]
	v_pk_fma_f32 v[224:225], v[54:55], v[220:221], v[224:225]
	v_cvt_pk_f32_fp8_e32 v[218:219], v187
	v_cvt_pk_f32_fp8_sdwa v[220:221], v187 src0_sel:WORD_1
	v_pk_fma_f32 v[222:223], v[56:57], v[214:215], v[222:223]
	v_pk_fma_f32 v[224:225], v[58:59], v[216:217], v[224:225]
	v_pk_fma_f32 v[222:223], v[60:61], v[218:219], v[222:223]
	v_pk_fma_f32 v[224:225], v[62:63], v[220:221], v[224:225]
	v_pk_add_f32 v[222:223], v[222:223], v[224:225]
	s_nop 0
	v_add_f32_e32 v228, v222, v223
	v_cvt_pk_f32_fp8_e32 v[214:215], v188
	v_cvt_pk_f32_fp8_sdwa v[216:217], v188 src0_sel:WORD_1
	v_cvt_pk_f32_fp8_e32 v[218:219], v189
	v_cvt_pk_f32_fp8_sdwa v[220:221], v189 src0_sel:WORD_1
	v_pk_mul_f32 v[222:223], v[48:49], v[214:215]
	v_pk_mul_f32 v[224:225], v[50:51], v[216:217]
	v_cvt_pk_f32_fp8_e32 v[214:215], v190
	v_cvt_pk_f32_fp8_sdwa v[216:217], v190 src0_sel:WORD_1
	v_pk_fma_f32 v[222:223], v[52:53], v[218:219], v[222:223]
	v_pk_fma_f32 v[224:225], v[54:55], v[220:221], v[224:225]
	v_cvt_pk_f32_fp8_e32 v[218:219], v191
	v_cvt_pk_f32_fp8_sdwa v[220:221], v191 src0_sel:WORD_1
	v_pk_fma_f32 v[222:223], v[56:57], v[214:215], v[222:223]
	v_pk_fma_f32 v[224:225], v[58:59], v[216:217], v[224:225]
	v_pk_fma_f32 v[222:223], v[60:61], v[218:219], v[222:223]
	v_pk_fma_f32 v[224:225], v[62:63], v[220:221], v[224:225]
	v_pk_add_f32 v[222:223], v[222:223], v[224:225]
	s_nop 0
	v_add_f32_e32 v229, v222, v223
	v_cvt_pk_f32_fp8_e32 v[214:215], v192
	v_cvt_pk_f32_fp8_sdwa v[216:217], v192 src0_sel:WORD_1
	v_cvt_pk_f32_fp8_e32 v[218:219], v193
	v_cvt_pk_f32_fp8_sdwa v[220:221], v193 src0_sel:WORD_1
	v_pk_mul_f32 v[222:223], v[48:49], v[214:215]
	v_pk_mul_f32 v[224:225], v[50:51], v[216:217]
	v_cvt_pk_f32_fp8_e32 v[214:215], v194
	v_cvt_pk_f32_fp8_sdwa v[216:217], v194 src0_sel:WORD_1
; template <bool STORE>
; DI void peer_item(const Params& p, int item, char* smem) {
;     ...
; #pragma unroll
;       for (int u = 0; u < 8; ++u) {
;         int e = e_s[tl * 128 + k + u];
;         uq[u] = *(const u32x4*)(U8 + (size_t)e * 1024 + lane * 16);
;       }
;       float part[8];
; #pragma unroll
;       for (int u = 0; u < 8; ++u) {
;         float d = 0.f;
; #pragma unroll
;         for (int i = 0; i < 4; ++i) {
;           f32x2_t lo = __builtin_amdgcn_cvt_pk_f32_fp8((int)uq[u][i], false);
;           f32x2_t hi = __builtin_amdgcn_cvt_pk_f32_fp8((int)uq[u][i], true);
;           d += xf[4 * i] * lo.x + xf[4 * i + 1] * lo.y + xf[4 * i + 2] * hi.x + xf[4 * i + 3] * hi.y;
;         }
;         part[u] = d;
;       }
;       float q4[4], r2[2], h;
; #pragma unroll
;       for (int j = 0; j < 4; ++j) {
;         float mine = b5 ? part[j + 4] : part[j];
;         float other = b5 ? part[j] : part[j + 4];
;         q4[j] = mine + __shfl_xor(other, 32);
;       }
; #pragma unroll
;       for (int j = 0; j < 2; ++j) {
;         float mine = b4 ? q4[j + 2] : q4[j];
;         float other = b4 ? q4[j] : q4[j + 2];
;         r2[j] = mine + __shfl_xor(other, 16);
;       }
;       {
;         float mine = b3 ? r2[1] : r2[0];
;         float other = b3 ? r2[0] : r2[1];
;         h = mine + __shfl_xor(other, 8);
;       }
;       h += __shfl_xor(h, 4);
;       h += __shfl_xor(h, 2);
;       h += __shfl_xor(h, 1);
	v_pk_fma_f32 v[222:223], v[52:53], v[218:219], v[222:223]
	v_pk_fma_f32 v[224:225], v[54:55], v[220:221], v[224:225]
	v_cvt_pk_f32_fp8_e32 v[218:219], v195
	v_cvt_pk_f32_fp8_sdwa v[220:221], v195 src0_sel:WORD_1
	v_pk_fma_f32 v[222:223], v[56:57], v[214:215], v[222:223]
	v_pk_fma_f32 v[224:225], v[58:59], v[216:217], v[224:225]
	v_pk_fma_f32 v[222:223], v[60:61], v[218:219], v[222:223]
	v_pk_fma_f32 v[224:225], v[62:63], v[220:221], v[224:225]
	v_pk_add_f32 v[222:223], v[222:223], v[224:225]
	s_nop 0
	v_add_f32_e32 v230, v222, v223
	v_cvt_pk_f32_fp8_e32 v[214:215], v196
	v_cvt_pk_f32_fp8_sdwa v[216:217], v196 src0_sel:WORD_1
	v_cvt_pk_f32_fp8_e32 v[218:219], v197
	v_cvt_pk_f32_fp8_sdwa v[220:221], v197 src0_sel:WORD_1
	v_pk_mul_f32 v[222:223], v[48:49], v[214:215]
	v_pk_mul_f32 v[224:225], v[50:51], v[216:217]
	v_cvt_pk_f32_fp8_e32 v[214:215], v198
	v_cvt_pk_f32_fp8_sdwa v[216:217], v198 src0_sel:WORD_1
	v_pk_fma_f32 v[222:223], v[52:53], v[218:219], v[222:223]
	v_pk_fma_f32 v[224:225], v[54:55], v[220:221], v[224:225]
	v_cvt_pk_f32_fp8_e32 v[218:219], v199
	v_cvt_pk_f32_fp8_sdwa v[220:221], v199 src0_sel:WORD_1
	v_pk_fma_f32 v[222:223], v[56:57], v[214:215], v[222:223]
	v_pk_fma_f32 v[224:225], v[58:59], v[216:217], v[224:225]
	v_pk_fma_f32 v[222:223], v[60:61], v[218:219], v[222:223]
	v_pk_fma_f32 v[224:225], v[62:63], v[220:221], v[224:225]
	v_pk_add_f32 v[222:223], v[222:223], v[224:225]
	s_nop 0
	v_add_f32_e32 v231, v222, v223
	v_cvt_pk_f32_fp8_e32 v[214:215], v200
	v_cvt_pk_f32_fp8_sdwa v[216:217], v200 src0_sel:WORD_1
	v_cvt_pk_f32_fp8_e32 v[218:219], v201
	v_cvt_pk_f32_fp8_sdwa v[220:221], v201 src0_sel:WORD_1
	v_pk_mul_f32 v[222:223], v[48:49], v[214:215]
	v_pk_mul_f32 v[224:225], v[50:51], v[216:217]
	v_cvt_pk_f32_fp8_e32 v[214:215], v202
	v_cvt_pk_f32_fp8_sdwa v[216:217], v202 src0_sel:WORD_1
	v_pk_fma_f32 v[222:223], v[52:53], v[218:219], v[222:223]
	v_pk_fma_f32 v[224:225], v[54:55], v[220:221], v[224:225]
	v_cvt_pk_f32_fp8_e32 v[218:219], v203
	v_cvt_pk_f32_fp8_sdwa v[220:221], v203 src0_sel:WORD_1
	v_pk_fma_f32 v[222:223], v[56:57], v[214:215], v[222:223]
	v_pk_fma_f32 v[224:225], v[58:59], v[216:217], v[224:225]
	v_pk_fma_f32 v[222:223], v[60:61], v[218:219], v[222:223]
	v_pk_fma_f32 v[224:225], v[62:63], v[220:221], v[224:225]
	v_pk_add_f32 v[222:223], v[222:223], v[224:225]
	s_nop 0
	v_add_f32_e32 v232, v222, v223
	v_cvt_pk_f32_fp8_e32 v[214:215], v204
	v_cvt_pk_f32_fp8_sdwa v[216:217], v204 src0_sel:WORD_1
	v_cvt_pk_f32_fp8_e32 v[218:219], v205
	v_cvt_pk_f32_fp8_sdwa v[220:221], v205 src0_sel:WORD_1
	v_pk_mul_f32 v[222:223], v[48:49], v[214:215]
	v_pk_mul_f32 v[224:225], v[50:51], v[216:217]
	v_cvt_pk_f32_fp8_e32 v[214:215], v206
	v_cvt_pk_f32_fp8_sdwa v[216:217], v206 src0_sel:WORD_1
	v_pk_fma_f32 v[222:223], v[52:53], v[218:219], v[222:223]
	v_pk_fma_f32 v[224:225], v[54:55], v[220:221], v[224:225]
	v_cvt_pk_f32_fp8_e32 v[218:219], v207
	v_cvt_pk_f32_fp8_sdwa v[220:221], v207 src0_sel:WORD_1
	v_pk_fma_f32 v[222:223], v[56:57], v[214:215], v[222:223]
	v_pk_fma_f32 v[224:225], v[58:59], v[216:217], v[224:225]
	v_pk_fma_f32 v[222:223], v[60:61], v[218:219], v[222:223]
	v_pk_fma_f32 v[224:225], v[62:63], v[220:221], v[224:225]
	v_pk_add_f32 v[222:223], v[222:223], v[224:225]
	s_nop 0
	v_add_f32_e32 v233, v222, v223
	v_permlane32_swap_b32_e32 v226, v230
	v_permlane32_swap_b32_e32 v227, v231
	v_permlane32_swap_b32_e32 v228, v232
	v_permlane32_swap_b32_e32 v229, v233
	v_add_f32_e32 v226, v226, v230
	v_add_f32_e32 v228, v228, v232
	v_add_f32_e32 v227, v227, v231
	v_add_f32_e32 v229, v229, v233
	s_nop 1
	v_permlane16_swap_b32_e32 v226, v228
	v_permlane16_swap_b32_e32 v227, v229
	v_add_f32_e32 v226, v226, v228
	v_add_f32_e32 v227, v227, v229
	s_nop 0
	v_cndmask_b32_e64 v230, v226, v227, s[24:25]
	v_cndmask_b32_e64 v231, v227, v226, s[24:25]
	s_nop 1
	v_add_f32_dpp v232, v231, v230 row_ror:8 row_mask:0xf bank_mask:0xf
	s_nop 1
	v_add_f32_dpp v233, v232, v232 quad_perm:[1,0,3,2] row_mask:0xf bank_mask:0xf
	s_nop 1
	v_add_f32_dpp v232, v233, v233 quad_perm:[2,3,0,1] row_mask:0xf bank_mask:0xf
	s_nop 1
	v_add_f32_dpp v233, v232, v232 row_half_mirror row_mask:0xf bank_mask:0xf
	ds_write_b32 v235, v233 offset:34304
	v_readlane_b32 s48, v138, s72
	v_readlane_b32 s49, v138, s73
	v_readlane_b32 s50, v138, s74
	v_readlane_b32 s51, v138, s75
	v_readlane_b32 s52, v138, s76
	v_readlane_b32 s53, v138, s77
	v_readlane_b32 s54, v138, s78
	v_readlane_b32 s55, v138, s79
	s_add_u32 s32, s0, s48
	s_addc_u32 s33, s1, 0
	s_add_u32 s34, s0, s49
	s_addc_u32 s35, s1, 0
	s_add_u32 s36, s0, s50
	s_addc_u32 s37, s1, 0
	s_add_u32 s38, s0, s51
	s_addc_u32 s39, s1, 0
	s_add_u32 s40, s0, s52
	s_addc_u32 s41, s1, 0
	s_add_u32 s42, s0, s53
	s_addc_u32 s43, s1, 0
	s_add_u32 s44, s0, s54
	s_addc_u32 s45, s1, 0
	s_add_u32 s46, s0, s55
	s_addc_u32 s47, s1, 0
	global_load_dwordx4 v[176:179], v234, s[32:33]
	global_load_dwordx4 v[180:183], v234, s[34:35]
	global_load_dwordx4 v[184:187], v234, s[36:37]
	global_load_dwordx4 v[188:191], v234, s[38:39]
	global_load_dwordx4 v[192:195], v234, s[40:41]
	global_load_dwordx4 v[196:199], v234, s[42:43]
	global_load_dwordx4 v[200:203], v234, s[44:45]
	global_load_dwordx4 v[204:207], v234, s[46:47]
	s_waitcnt vmcnt(8)
; template <bool STORE>
; DI void peer_item(const Params& p, int item, char* smem) {
;     ...
; #pragma unroll
;       for (int u = 0; u < 8; ++u) {
;         int e = e_s[tl * 128 + k + u];
;         uq[u] = *(const u32x4*)(U8 + (size_t)e * 1024 + lane * 16);
;       }
;       float part[8];
; #pragma unroll
;       for (int u = 0; u < 8; ++u) {
;         float d = 0.f;
; #pragma unroll
;         for (int i = 0; i < 4; ++i) {
;           f32x2_t lo = __builtin_amdgcn_cvt_pk_f32_fp8((int)uq[u][i], false);
;           f32x2_t hi = __builtin_amdgcn_cvt_pk_f32_fp8((int)uq[u][i], true);
;           d += xf[4 * i] * lo.x + xf[4 * i + 1] * lo.y + xf[4 * i + 2] * hi.x + xf[4 * i + 3] * hi.y;
;         }
;         part[u] = d;
;       }
	v_cvt_pk_f32_fp8_e32 v[214:215], v144
	v_cvt_pk_f32_fp8_sdwa v[216:217], v144 src0_sel:WORD_1
	v_cvt_pk_f32_fp8_e32 v[218:219], v145
	v_cvt_pk_f32_fp8_sdwa v[220:221], v145 src0_sel:WORD_1
	v_pk_mul_f32 v[222:223], v[64:65], v[214:215]
	v_pk_mul_f32 v[224:225], v[66:67], v[216:217]
	v_cvt_pk_f32_fp8_e32 v[214:215], v146
	v_cvt_pk_f32_fp8_sdwa v[216:217], v146 src0_sel:WORD_1
	v_pk_fma_f32 v[222:223], v[68:69], v[218:219], v[222:223]
	v_pk_fma_f32 v[224:225], v[70:71], v[220:221], v[224:225]
	v_cvt_pk_f32_fp8_e32 v[218:219], v147
	v_cvt_pk_f32_fp8_sdwa v[220:221], v147 src0_sel:WORD_1
	v_pk_fma_f32 v[222:223], v[72:73], v[214:215], v[222:223]
	v_pk_fma_f32 v[224:225], v[74:75], v[216:217], v[224:225]
	v_pk_fma_f32 v[222:223], v[76:77], v[218:219], v[222:223]
	v_pk_fma_f32 v[224:225], v[78:79], v[220:221], v[224:225]
	v_pk_add_f32 v[222:223], v[222:223], v[224:225]
	s_nop 0
	v_add_f32_e32 v226, v222, v223
	v_cvt_pk_f32_fp8_e32 v[214:215], v148
	v_cvt_pk_f32_fp8_sdwa v[216:217], v148 src0_sel:WORD_1
	v_cvt_pk_f32_fp8_e32 v[218:219], v149
	v_cvt_pk_f32_fp8_sdwa v[220:221], v149 src0_sel:WORD_1
	v_pk_mul_f32 v[222:223], v[64:65], v[214:215]
	v_pk_mul_f32 v[224:225], v[66:67], v[216:217]
	v_cvt_pk_f32_fp8_e32 v[214:215], v150
	v_cvt_pk_f32_fp8_sdwa v[216:217], v150 src0_sel:WORD_1
	v_pk_fma_f32 v[222:223], v[68:69], v[218:219], v[222:223]
	v_pk_fma_f32 v[224:225], v[70:71], v[220:221], v[224:225]
	v_cvt_pk_f32_fp8_e32 v[218:219], v151
	v_cvt_pk_f32_fp8_sdwa v[220:221], v151 src0_sel:WORD_1
	v_pk_fma_f32 v[222:223], v[72:73], v[214:215], v[222:223]
	v_pk_fma_f32 v[224:225], v[74:75], v[216:217], v[224:225]
	v_pk_fma_f32 v[222:223], v[76:77], v[218:219], v[222:223]
	v_pk_fma_f32 v[224:225], v[78:79], v[220:221], v[224:225]
	v_pk_add_f32 v[222:223], v[222:223], v[224:225]
	s_nop 0
	v_add_f32_e32 v227, v222, v223
	v_cvt_pk_f32_fp8_e32 v[214:215], v152
	v_cvt_pk_f32_fp8_sdwa v[216:217], v152 src0_sel:WORD_1
	v_cvt_pk_f32_fp8_e32 v[218:219], v153
	v_cvt_pk_f32_fp8_sdwa v[220:221], v153 src0_sel:WORD_1
	v_pk_mul_f32 v[222:223], v[64:65], v[214:215]
	v_pk_mul_f32 v[224:225], v[66:67], v[216:217]
	v_cvt_pk_f32_fp8_e32 v[214:215], v154
	v_cvt_pk_f32_fp8_sdwa v[216:217], v154 src0_sel:WORD_1
	v_pk_fma_f32 v[222:223], v[68:69], v[218:219], v[222:223]
	v_pk_fma_f32 v[224:225], v[70:71], v[220:221], v[224:225]
	v_cvt_pk_f32_fp8_e32 v[218:219], v155
	v_cvt_pk_f32_fp8_sdwa v[220:221], v155 src0_sel:WORD_1
	v_pk_fma_f32 v[222:223], v[72:73], v[214:215], v[222:223]
	v_pk_fma_f32 v[224:225], v[74:75], v[216:217], v[224:225]
	v_pk_fma_f32 v[222:223], v[76:77], v[218:219], v[222:223]
	v_pk_fma_f32 v[224:225], v[78:79], v[220:221], v[224:225]
	v_pk_add_f32 v[222:223], v[222:223], v[224:225]
	s_nop 0
	v_add_f32_e32 v228, v222, v223
	v_cvt_pk_f32_fp8_e32 v[214:215], v156
	v_cvt_pk_f32_fp8_sdwa v[216:217], v156 src0_sel:WORD_1
	v_cvt_pk_f32_fp8_e32 v[218:219], v157
	v_cvt_pk_f32_fp8_sdwa v[220:221], v157 src0_sel:WORD_1
	v_pk_mul_f32 v[222:223], v[64:65], v[214:215]
	v_pk_mul_f32 v[224:225], v[66:67], v[216:217]
	v_cvt_pk_f32_fp8_e32 v[214:215], v158
	v_cvt_pk_f32_fp8_sdwa v[216:217], v158 src0_sel:WORD_1
	v_pk_fma_f32 v[222:223], v[68:69], v[218:219], v[222:223]
	v_pk_fma_f32 v[224:225], v[70:71], v[220:221], v[224:225]
	v_cvt_pk_f32_fp8_e32 v[218:219], v159
	v_cvt_pk_f32_fp8_sdwa v[220:221], v159 src0_sel:WORD_1
	v_pk_fma_f32 v[222:223], v[72:73], v[214:215], v[222:223]
	v_pk_fma_f32 v[224:225], v[74:75], v[216:217], v[224:225]
	v_pk_fma_f32 v[222:223], v[76:77], v[218:219], v[222:223]
	v_pk_fma_f32 v[224:225], v[78:79], v[220:221], v[224:225]
	v_pk_add_f32 v[222:223], v[222:223], v[224:225]
	s_nop 0
	v_add_f32_e32 v229, v222, v223
	v_cvt_pk_f32_fp8_e32 v[214:215], v160
	v_cvt_pk_f32_fp8_sdwa v[216:217], v160 src0_sel:WORD_1
	v_cvt_pk_f32_fp8_e32 v[218:219], v161
	v_cvt_pk_f32_fp8_sdwa v[220:221], v161 src0_sel:WORD_1
	v_pk_mul_f32 v[222:223], v[64:65], v[214:215]
	v_pk_mul_f32 v[224:225], v[66:67], v[216:217]
	v_cvt_pk_f32_fp8_e32 v[214:215], v162
	v_cvt_pk_f32_fp8_sdwa v[216:217], v162 src0_sel:WORD_1
	v_pk_fma_f32 v[222:223], v[68:69], v[218:219], v[222:223]
	v_pk_fma_f32 v[224:225], v[70:71], v[220:221], v[224:225]
	v_cvt_pk_f32_fp8_e32 v[218:219], v163
	v_cvt_pk_f32_fp8_sdwa v[220:221], v163 src0_sel:WORD_1
	v_pk_fma_f32 v[222:223], v[72:73], v[214:215], v[222:223]
	v_pk_fma_f32 v[224:225], v[74:75], v[216:217], v[224:225]
	v_pk_fma_f32 v[222:223], v[76:77], v[218:219], v[222:223]
	v_pk_fma_f32 v[224:225], v[78:79], v[220:221], v[224:225]
	v_pk_add_f32 v[222:223], v[222:223], v[224:225]
	s_nop 0
	v_add_f32_e32 v230, v222, v223
	v_cvt_pk_f32_fp8_e32 v[214:215], v164
	v_cvt_pk_f32_fp8_sdwa v[216:217], v164 src0_sel:WORD_1
	v_cvt_pk_f32_fp8_e32 v[218:219], v165
	v_cvt_pk_f32_fp8_sdwa v[220:221], v165 src0_sel:WORD_1
	v_pk_mul_f32 v[222:223], v[64:65], v[214:215]
	v_pk_mul_f32 v[224:225], v[66:67], v[216:217]
	v_cvt_pk_f32_fp8_e32 v[214:215], v166
	v_cvt_pk_f32_fp8_sdwa v[216:217], v166 src0_sel:WORD_1
	v_pk_fma_f32 v[222:223], v[68:69], v[218:219], v[222:223]
	v_pk_fma_f32 v[224:225], v[70:71], v[220:221], v[224:225]
	v_cvt_pk_f32_fp8_e32 v[218:219], v167
	v_cvt_pk_f32_fp8_sdwa v[220:221], v167 src0_sel:WORD_1
	v_pk_fma_f32 v[222:223], v[72:73], v[214:215], v[222:223]
	v_pk_fma_f32 v[224:225], v[74:75], v[216:217], v[224:225]
	v_pk_fma_f32 v[222:223], v[76:77], v[218:219], v[222:223]
	v_pk_fma_f32 v[224:225], v[78:79], v[220:221], v[224:225]
	v_pk_add_f32 v[222:223], v[222:223], v[224:225]
	s_nop 0
	v_add_f32_e32 v231, v222, v223
	v_cvt_pk_f32_fp8_e32 v[214:215], v168
	v_cvt_pk_f32_fp8_sdwa v[216:217], v168 src0_sel:WORD_1
	v_cvt_pk_f32_fp8_e32 v[218:219], v169
; template <bool STORE>
; DI void peer_item(const Params& p, int item, char* smem) {
;     ...
; #pragma unroll
;       for (int u = 0; u < 8; ++u) {
;         int e = e_s[tl * 128 + k + u];
;         uq[u] = *(const u32x4*)(U8 + (size_t)e * 1024 + lane * 16);
;       }
;       float part[8];
; #pragma unroll
;       for (int u = 0; u < 8; ++u) {
;         float d = 0.f;
; #pragma unroll
;         for (int i = 0; i < 4; ++i) {
;           f32x2_t lo = __builtin_amdgcn_cvt_pk_f32_fp8((int)uq[u][i], false);
;           f32x2_t hi = __builtin_amdgcn_cvt_pk_f32_fp8((int)uq[u][i], true);
;           d += xf[4 * i] * lo.x + xf[4 * i + 1] * lo.y + xf[4 * i + 2] * hi.x + xf[4 * i + 3] * hi.y;
;         }
;         part[u] = d;
;       }
;       float q4[4], r2[2], h;
; #pragma unroll
;       for (int j = 0; j < 4; ++j) {
;         float mine = b5 ? part[j + 4] : part[j];
;         float other = b5 ? part[j] : part[j + 4];
;         q4[j] = mine + __shfl_xor(other, 32);
;       }
; #pragma unroll
;       for (int j = 0; j < 2; ++j) {
;         float mine = b4 ? q4[j + 2] : q4[j];
;         float other = b4 ? q4[j] : q4[j + 2];
;         r2[j] = mine + __shfl_xor(other, 16);
;       }
;       {
;         float mine = b3 ? r2[1] : r2[0];
;         float other = b3 ? r2[0] : r2[1];
;         h = mine + __shfl_xor(other, 8);
;       }
;       h += __shfl_xor(h, 4);
;       h += __shfl_xor(h, 2);
;       h += __shfl_xor(h, 1);
	v_cvt_pk_f32_fp8_sdwa v[220:221], v169 src0_sel:WORD_1
	v_pk_mul_f32 v[222:223], v[64:65], v[214:215]
	v_pk_mul_f32 v[224:225], v[66:67], v[216:217]
	v_cvt_pk_f32_fp8_e32 v[214:215], v170
	v_cvt_pk_f32_fp8_sdwa v[216:217], v170 src0_sel:WORD_1
	v_pk_fma_f32 v[222:223], v[68:69], v[218:219], v[222:223]
	v_pk_fma_f32 v[224:225], v[70:71], v[220:221], v[224:225]
	v_cvt_pk_f32_fp8_e32 v[218:219], v171
	v_cvt_pk_f32_fp8_sdwa v[220:221], v171 src0_sel:WORD_1
	v_pk_fma_f32 v[222:223], v[72:73], v[214:215], v[222:223]
	v_pk_fma_f32 v[224:225], v[74:75], v[216:217], v[224:225]
	v_pk_fma_f32 v[222:223], v[76:77], v[218:219], v[222:223]
	v_pk_fma_f32 v[224:225], v[78:79], v[220:221], v[224:225]
	v_pk_add_f32 v[222:223], v[222:223], v[224:225]
	s_nop 0
	v_add_f32_e32 v232, v222, v223
	v_cvt_pk_f32_fp8_e32 v[214:215], v172
	v_cvt_pk_f32_fp8_sdwa v[216:217], v172 src0_sel:WORD_1
	v_cvt_pk_f32_fp8_e32 v[218:219], v173
	v_cvt_pk_f32_fp8_sdwa v[220:221], v173 src0_sel:WORD_1
	v_pk_mul_f32 v[222:223], v[64:65], v[214:215]
	v_pk_mul_f32 v[224:225], v[66:67], v[216:217]
	v_cvt_pk_f32_fp8_e32 v[214:215], v174
	v_cvt_pk_f32_fp8_sdwa v[216:217], v174 src0_sel:WORD_1
	v_pk_fma_f32 v[222:223], v[68:69], v[218:219], v[222:223]
	v_pk_fma_f32 v[224:225], v[70:71], v[220:221], v[224:225]
	v_cvt_pk_f32_fp8_e32 v[218:219], v175
	v_cvt_pk_f32_fp8_sdwa v[220:221], v175 src0_sel:WORD_1
	v_pk_fma_f32 v[222:223], v[72:73], v[214:215], v[222:223]
	v_pk_fma_f32 v[224:225], v[74:75], v[216:217], v[224:225]
	v_pk_fma_f32 v[222:223], v[76:77], v[218:219], v[222:223]
	v_pk_fma_f32 v[224:225], v[78:79], v[220:221], v[224:225]
	v_pk_add_f32 v[222:223], v[222:223], v[224:225]
	s_nop 0
	v_add_f32_e32 v233, v222, v223
	v_permlane32_swap_b32_e32 v226, v230
	v_permlane32_swap_b32_e32 v227, v231
	v_permlane32_swap_b32_e32 v228, v232
	v_permlane32_swap_b32_e32 v229, v233
	v_add_f32_e32 v226, v226, v230
	v_add_f32_e32 v228, v228, v232
	v_add_f32_e32 v227, v227, v231
	v_add_f32_e32 v229, v229, v233
	s_nop 1
	v_permlane16_swap_b32_e32 v226, v228
	v_permlane16_swap_b32_e32 v227, v229
	v_add_f32_e32 v226, v226, v228
	v_add_f32_e32 v227, v227, v229
	s_nop 0
	v_cndmask_b32_e64 v230, v226, v227, s[24:25]
	v_cndmask_b32_e64 v231, v227, v226, s[24:25]
	s_nop 1
	v_add_f32_dpp v232, v231, v230 row_ror:8 row_mask:0xf bank_mask:0xf
	s_nop 1
	v_add_f32_dpp v233, v232, v232 quad_perm:[1,0,3,2] row_mask:0xf bank_mask:0xf
	s_nop 1
	v_add_f32_dpp v232, v233, v233 quad_perm:[2,3,0,1] row_mask:0xf bank_mask:0xf
	s_nop 1
	v_add_f32_dpp v233, v232, v232 row_half_mirror row_mask:0xf bank_mask:0xf
	ds_write_b32 v235, v233 offset:34816
	v_readlane_b32 s48, v140, s72
	v_readlane_b32 s49, v140, s73
	v_readlane_b32 s50, v140, s74
	v_readlane_b32 s51, v140, s75
	v_readlane_b32 s52, v140, s76
	v_readlane_b32 s53, v140, s77
	v_readlane_b32 s54, v140, s78
	v_readlane_b32 s55, v140, s79
	s_add_u32 s32, s0, s48
	s_addc_u32 s33, s1, 0
	s_add_u32 s34, s0, s49
	s_addc_u32 s35, s1, 0
	s_add_u32 s36, s0, s50
	s_addc_u32 s37, s1, 0
	s_add_u32 s38, s0, s51
	s_addc_u32 s39, s1, 0
	s_add_u32 s40, s0, s52
	s_addc_u32 s41, s1, 0
	s_add_u32 s42, s0, s53
	s_addc_u32 s43, s1, 0
	s_add_u32 s44, s0, s54
	s_addc_u32 s45, s1, 0
	s_add_u32 s46, s0, s55
	s_addc_u32 s47, s1, 0
	global_load_dwordx4 v[144:147], v234, s[32:33]
	global_load_dwordx4 v[148:151], v234, s[34:35]
	global_load_dwordx4 v[152:155], v234, s[36:37]
	global_load_dwordx4 v[156:159], v234, s[38:39]
	global_load_dwordx4 v[160:163], v234, s[40:41]
	global_load_dwordx4 v[164:167], v234, s[42:43]
	global_load_dwordx4 v[168:171], v234, s[44:45]
	global_load_dwordx4 v[172:175], v234, s[46:47]
	s_waitcnt vmcnt(8)
	v_cvt_pk_f32_fp8_e32 v[214:215], v176
	v_cvt_pk_f32_fp8_sdwa v[216:217], v176 src0_sel:WORD_1
	v_cvt_pk_f32_fp8_e32 v[218:219], v177
	v_cvt_pk_f32_fp8_sdwa v[220:221], v177 src0_sel:WORD_1
	v_pk_mul_f32 v[222:223], v[80:81], v[214:215]
	v_pk_mul_f32 v[224:225], v[82:83], v[216:217]
	v_cvt_pk_f32_fp8_e32 v[214:215], v178
	v_cvt_pk_f32_fp8_sdwa v[216:217], v178 src0_sel:WORD_1
	v_pk_fma_f32 v[222:223], v[84:85], v[218:219], v[222:223]
	v_pk_fma_f32 v[224:225], v[86:87], v[220:221], v[224:225]
	v_cvt_pk_f32_fp8_e32 v[218:219], v179
	v_cvt_pk_f32_fp8_sdwa v[220:221], v179 src0_sel:WORD_1
	v_pk_fma_f32 v[222:223], v[88:89], v[214:215], v[222:223]
	v_pk_fma_f32 v[224:225], v[90:91], v[216:217], v[224:225]
	v_pk_fma_f32 v[222:223], v[92:93], v[218:219], v[222:223]
	v_pk_fma_f32 v[224:225], v[94:95], v[220:221], v[224:225]
	v_pk_add_f32 v[222:223], v[222:223], v[224:225]
	s_nop 0
	v_add_f32_e32 v226, v222, v223
	v_cvt_pk_f32_fp8_e32 v[214:215], v180
	v_cvt_pk_f32_fp8_sdwa v[216:217], v180 src0_sel:WORD_1
	v_cvt_pk_f32_fp8_e32 v[218:219], v181
	v_cvt_pk_f32_fp8_sdwa v[220:221], v181 src0_sel:WORD_1
	v_pk_mul_f32 v[222:223], v[80:81], v[214:215]
	v_pk_mul_f32 v[224:225], v[82:83], v[216:217]
	v_cvt_pk_f32_fp8_e32 v[214:215], v182
	v_cvt_pk_f32_fp8_sdwa v[216:217], v182 src0_sel:WORD_1
	v_pk_fma_f32 v[222:223], v[84:85], v[218:219], v[222:223]
	v_pk_fma_f32 v[224:225], v[86:87], v[220:221], v[224:225]
	v_cvt_pk_f32_fp8_e32 v[218:219], v183
	v_cvt_pk_f32_fp8_sdwa v[220:221], v183 src0_sel:WORD_1
	v_pk_fma_f32 v[222:223], v[88:89], v[214:215], v[222:223]
	v_pk_fma_f32 v[224:225], v[90:91], v[216:217], v[224:225]
	v_pk_fma_f32 v[222:223], v[92:93], v[218:219], v[222:223]
	v_pk_fma_f32 v[224:225], v[94:95], v[220:221], v[224:225]
	v_pk_add_f32 v[222:223], v[222:223], v[224:225]
	s_nop 0
	v_add_f32_e32 v227, v222, v223
	v_cvt_pk_f32_fp8_e32 v[214:215], v184
	v_cvt_pk_f32_fp8_sdwa v[216:217], v184 src0_sel:WORD_1
	v_cvt_pk_f32_fp8_e32 v[218:219], v185
	v_cvt_pk_f32_fp8_sdwa v[220:221], v185 src0_sel:WORD_1
; template <bool STORE>
; DI void peer_item(const Params& p, int item, char* smem) {
;     ...
; #pragma unroll
;       for (int u = 0; u < 8; ++u) {
;         int e = e_s[tl * 128 + k + u];
;         uq[u] = *(const u32x4*)(U8 + (size_t)e * 1024 + lane * 16);
;       }
;       float part[8];
; #pragma unroll
;       for (int u = 0; u < 8; ++u) {
;         float d = 0.f;
; #pragma unroll
;         for (int i = 0; i < 4; ++i) {
;           f32x2_t lo = __builtin_amdgcn_cvt_pk_f32_fp8((int)uq[u][i], false);
;           f32x2_t hi = __builtin_amdgcn_cvt_pk_f32_fp8((int)uq[u][i], true);
;           d += xf[4 * i] * lo.x + xf[4 * i + 1] * lo.y + xf[4 * i + 2] * hi.x + xf[4 * i + 3] * hi.y;
;         }
;         part[u] = d;
;       }
;       float q4[4], r2[2], h;
; #pragma unroll
;       for (int j = 0; j < 4; ++j) {
;         float mine = b5 ? part[j + 4] : part[j];
;         float other = b5 ? part[j] : part[j + 4];
;         q4[j] = mine + __shfl_xor(other, 32);
;       }
; #pragma unroll
;       for (int j = 0; j < 2; ++j) {
;         float mine = b4 ? q4[j + 2] : q4[j];
;         float other = b4 ? q4[j] : q4[j + 2];
;         r2[j] = mine + __shfl_xor(other, 16);
;       }
	v_pk_mul_f32 v[222:223], v[80:81], v[214:215]
	v_pk_mul_f32 v[224:225], v[82:83], v[216:217]
	v_cvt_pk_f32_fp8_e32 v[214:215], v186
	v_cvt_pk_f32_fp8_sdwa v[216:217], v186 src0_sel:WORD_1
	v_pk_fma_f32 v[222:223], v[84:85], v[218:219], v[222:223]
	v_pk_fma_f32 v[224:225], v[86:87], v[220:221], v[224:225]
	v_cvt_pk_f32_fp8_e32 v[218:219], v187
	v_cvt_pk_f32_fp8_sdwa v[220:221], v187 src0_sel:WORD_1
	v_pk_fma_f32 v[222:223], v[88:89], v[214:215], v[222:223]
	v_pk_fma_f32 v[224:225], v[90:91], v[216:217], v[224:225]
	v_pk_fma_f32 v[222:223], v[92:93], v[218:219], v[222:223]
	v_pk_fma_f32 v[224:225], v[94:95], v[220:221], v[224:225]
	v_pk_add_f32 v[222:223], v[222:223], v[224:225]
	s_nop 0
	v_add_f32_e32 v228, v222, v223
	v_cvt_pk_f32_fp8_e32 v[214:215], v188
	v_cvt_pk_f32_fp8_sdwa v[216:217], v188 src0_sel:WORD_1
	v_cvt_pk_f32_fp8_e32 v[218:219], v189
	v_cvt_pk_f32_fp8_sdwa v[220:221], v189 src0_sel:WORD_1
	v_pk_mul_f32 v[222:223], v[80:81], v[214:215]
	v_pk_mul_f32 v[224:225], v[82:83], v[216:217]
	v_cvt_pk_f32_fp8_e32 v[214:215], v190
	v_cvt_pk_f32_fp8_sdwa v[216:217], v190 src0_sel:WORD_1
	v_pk_fma_f32 v[222:223], v[84:85], v[218:219], v[222:223]
	v_pk_fma_f32 v[224:225], v[86:87], v[220:221], v[224:225]
	v_cvt_pk_f32_fp8_e32 v[218:219], v191
	v_cvt_pk_f32_fp8_sdwa v[220:221], v191 src0_sel:WORD_1
	v_pk_fma_f32 v[222:223], v[88:89], v[214:215], v[222:223]
	v_pk_fma_f32 v[224:225], v[90:91], v[216:217], v[224:225]
	v_pk_fma_f32 v[222:223], v[92:93], v[218:219], v[222:223]
	v_pk_fma_f32 v[224:225], v[94:95], v[220:221], v[224:225]
	v_pk_add_f32 v[222:223], v[222:223], v[224:225]
	s_nop 0
	v_add_f32_e32 v229, v222, v223
	v_cvt_pk_f32_fp8_e32 v[214:215], v192
	v_cvt_pk_f32_fp8_sdwa v[216:217], v192 src0_sel:WORD_1
	v_cvt_pk_f32_fp8_e32 v[218:219], v193
	v_cvt_pk_f32_fp8_sdwa v[220:221], v193 src0_sel:WORD_1
	v_pk_mul_f32 v[222:223], v[80:81], v[214:215]
	v_pk_mul_f32 v[224:225], v[82:83], v[216:217]
	v_cvt_pk_f32_fp8_e32 v[214:215], v194
	v_cvt_pk_f32_fp8_sdwa v[216:217], v194 src0_sel:WORD_1
	v_pk_fma_f32 v[222:223], v[84:85], v[218:219], v[222:223]
	v_pk_fma_f32 v[224:225], v[86:87], v[220:221], v[224:225]
	v_cvt_pk_f32_fp8_e32 v[218:219], v195
	v_cvt_pk_f32_fp8_sdwa v[220:221], v195 src0_sel:WORD_1
	v_pk_fma_f32 v[222:223], v[88:89], v[214:215], v[222:223]
	v_pk_fma_f32 v[224:225], v[90:91], v[216:217], v[224:225]
	v_pk_fma_f32 v[222:223], v[92:93], v[218:219], v[222:223]
	v_pk_fma_f32 v[224:225], v[94:95], v[220:221], v[224:225]
	v_pk_add_f32 v[222:223], v[222:223], v[224:225]
	s_nop 0
	v_add_f32_e32 v230, v222, v223
	v_cvt_pk_f32_fp8_e32 v[214:215], v196
	v_cvt_pk_f32_fp8_sdwa v[216:217], v196 src0_sel:WORD_1
	v_cvt_pk_f32_fp8_e32 v[218:219], v197
	v_cvt_pk_f32_fp8_sdwa v[220:221], v197 src0_sel:WORD_1
	v_pk_mul_f32 v[222:223], v[80:81], v[214:215]
	v_pk_mul_f32 v[224:225], v[82:83], v[216:217]
	v_cvt_pk_f32_fp8_e32 v[214:215], v198
	v_cvt_pk_f32_fp8_sdwa v[216:217], v198 src0_sel:WORD_1
	v_pk_fma_f32 v[222:223], v[84:85], v[218:219], v[222:223]
	v_pk_fma_f32 v[224:225], v[86:87], v[220:221], v[224:225]
	v_cvt_pk_f32_fp8_e32 v[218:219], v199
	v_cvt_pk_f32_fp8_sdwa v[220:221], v199 src0_sel:WORD_1
	v_pk_fma_f32 v[222:223], v[88:89], v[214:215], v[222:223]
	v_pk_fma_f32 v[224:225], v[90:91], v[216:217], v[224:225]
	v_pk_fma_f32 v[222:223], v[92:93], v[218:219], v[222:223]
	v_pk_fma_f32 v[224:225], v[94:95], v[220:221], v[224:225]
	v_pk_add_f32 v[222:223], v[222:223], v[224:225]
	s_nop 0
	v_add_f32_e32 v231, v222, v223
	v_cvt_pk_f32_fp8_e32 v[214:215], v200
	v_cvt_pk_f32_fp8_sdwa v[216:217], v200 src0_sel:WORD_1
	v_cvt_pk_f32_fp8_e32 v[218:219], v201
	v_cvt_pk_f32_fp8_sdwa v[220:221], v201 src0_sel:WORD_1
	v_pk_mul_f32 v[222:223], v[80:81], v[214:215]
	v_pk_mul_f32 v[224:225], v[82:83], v[216:217]
	v_cvt_pk_f32_fp8_e32 v[214:215], v202
	v_cvt_pk_f32_fp8_sdwa v[216:217], v202 src0_sel:WORD_1
	v_pk_fma_f32 v[222:223], v[84:85], v[218:219], v[222:223]
	v_pk_fma_f32 v[224:225], v[86:87], v[220:221], v[224:225]
	v_cvt_pk_f32_fp8_e32 v[218:219], v203
	v_cvt_pk_f32_fp8_sdwa v[220:221], v203 src0_sel:WORD_1
	v_pk_fma_f32 v[222:223], v[88:89], v[214:215], v[222:223]
	v_pk_fma_f32 v[224:225], v[90:91], v[216:217], v[224:225]
	v_pk_fma_f32 v[222:223], v[92:93], v[218:219], v[222:223]
	v_pk_fma_f32 v[224:225], v[94:95], v[220:221], v[224:225]
	v_pk_add_f32 v[222:223], v[222:223], v[224:225]
	s_nop 0
	v_add_f32_e32 v232, v222, v223
	v_cvt_pk_f32_fp8_e32 v[214:215], v204
	v_cvt_pk_f32_fp8_sdwa v[216:217], v204 src0_sel:WORD_1
	v_cvt_pk_f32_fp8_e32 v[218:219], v205
	v_cvt_pk_f32_fp8_sdwa v[220:221], v205 src0_sel:WORD_1
	v_pk_mul_f32 v[222:223], v[80:81], v[214:215]
	v_pk_mul_f32 v[224:225], v[82:83], v[216:217]
	v_cvt_pk_f32_fp8_e32 v[214:215], v206
	v_cvt_pk_f32_fp8_sdwa v[216:217], v206 src0_sel:WORD_1
	v_pk_fma_f32 v[222:223], v[84:85], v[218:219], v[222:223]
	v_pk_fma_f32 v[224:225], v[86:87], v[220:221], v[224:225]
	v_cvt_pk_f32_fp8_e32 v[218:219], v207
	v_cvt_pk_f32_fp8_sdwa v[220:221], v207 src0_sel:WORD_1
	v_pk_fma_f32 v[222:223], v[88:89], v[214:215], v[222:223]
	v_pk_fma_f32 v[224:225], v[90:91], v[216:217], v[224:225]
	v_pk_fma_f32 v[222:223], v[92:93], v[218:219], v[222:223]
	v_pk_fma_f32 v[224:225], v[94:95], v[220:221], v[224:225]
	v_pk_add_f32 v[222:223], v[222:223], v[224:225]
	s_nop 0
	v_add_f32_e32 v233, v222, v223
	v_permlane32_swap_b32_e32 v226, v230
	v_permlane32_swap_b32_e32 v227, v231
	v_permlane32_swap_b32_e32 v228, v232
	v_permlane32_swap_b32_e32 v229, v233
	v_add_f32_e32 v226, v226, v230
	v_add_f32_e32 v228, v228, v232
	v_add_f32_e32 v227, v227, v231
	v_add_f32_e32 v229, v229, v233
	s_nop 1
	v_permlane16_swap_b32_e32 v226, v228
; DI float gelu_exact(float x) { return 0.5f * x * (1.f + erff(x * 0.7071067811865476f)); }
; template <bool STORE>
; DI void peer_item(const Params& p, int item, char* smem) {
;     ...
; #pragma unroll 2
;     for (int k = 0; k < 128; k += 8) {
;       u32x4 uq[8];
;       const int emine = e_s[tl * 128 + k + (lane >> 3)];
;       const float gmine = g_s[tl * 128 + k + (lane >> 3)];
;       const float su = SU[emine], sv = SV[emine];
; #pragma unroll
;       for (int u = 0; u < 8; ++u) {
;         int e = e_s[tl * 128 + k + u];
;         uq[u] = *(const u32x4*)(U8 + (size_t)e * 1024 + lane * 16);
;       }
;       float part[8];
; #pragma unroll
;       for (int u = 0; u < 8; ++u) {
;         float d = 0.f;
; #pragma unroll
;         for (int i = 0; i < 4; ++i) {
;           f32x2_t lo = __builtin_amdgcn_cvt_pk_f32_fp8((int)uq[u][i], false);
;           f32x2_t hi = __builtin_amdgcn_cvt_pk_f32_fp8((int)uq[u][i], true);
;           d += xf[4 * i] * lo.x + xf[4 * i + 1] * lo.y + xf[4 * i + 2] * hi.x + xf[4 * i + 3] * hi.y;
;         }
;         part[u] = d;
;       }
;       float q4[4], r2[2], h;
; #pragma unroll
;       for (int j = 0; j < 4; ++j) {
;         float mine = b5 ? part[j + 4] : part[j];
;         float other = b5 ? part[j] : part[j + 4];
;         q4[j] = mine + __shfl_xor(other, 32);
;       }
; #pragma unroll
;       for (int j = 0; j < 2; ++j) {
;         float mine = b4 ? q4[j + 2] : q4[j];
;         float other = b4 ? q4[j] : q4[j + 2];
;         r2[j] = mine + __shfl_xor(other, 16);
;       }
;       {
;         float mine = b3 ? r2[1] : r2[0];
;         float other = b3 ? r2[0] : r2[1];
;         h = mine + __shfl_xor(other, 8);
;       }
;       h += __shfl_xor(h, 4);
;       h += __shfl_xor(h, 2);
;       h += __shfl_xor(h, 1);
;       const float amine = gelu_exact(h * su) * gmine * sv;
;       if ((lane & 7) == 0) {
;         EG[tok * 128 + k + (lane >> 3)] = emine;
;         AG[tok * 128 + k + (lane >> 3)] = amine;
;       }
;     }
	v_permlane16_swap_b32_e32 v227, v229
	v_add_f32_e32 v226, v226, v228
	v_add_f32_e32 v227, v227, v229
	s_nop 0
	v_cndmask_b32_e64 v230, v226, v227, s[24:25]
	v_cndmask_b32_e64 v231, v227, v226, s[24:25]
	s_nop 1
	v_add_f32_dpp v232, v231, v230 row_ror:8 row_mask:0xf bank_mask:0xf
	s_nop 1
	v_add_f32_dpp v233, v232, v232 quad_perm:[1,0,3,2] row_mask:0xf bank_mask:0xf
	s_nop 1
	v_add_f32_dpp v232, v233, v233 quad_perm:[2,3,0,1] row_mask:0xf bank_mask:0xf
	s_nop 1
	v_add_f32_dpp v233, v232, v232 row_half_mirror row_mask:0xf bank_mask:0xf
	ds_write_b32 v235, v233 offset:35328
	v_readlane_b32 s48, v142, s72
	v_readlane_b32 s49, v142, s73
	v_readlane_b32 s50, v142, s74
	v_readlane_b32 s51, v142, s75
	v_readlane_b32 s52, v142, s76
	v_readlane_b32 s53, v142, s77
	v_readlane_b32 s54, v142, s78
	v_readlane_b32 s55, v142, s79
	s_add_u32 s32, s0, s48
	s_addc_u32 s33, s1, 0
	s_add_u32 s34, s0, s49
	s_addc_u32 s35, s1, 0
	s_add_u32 s36, s0, s50
	s_addc_u32 s37, s1, 0
	s_add_u32 s38, s0, s51
	s_addc_u32 s39, s1, 0
	s_add_u32 s40, s0, s52
	s_addc_u32 s41, s1, 0
	s_add_u32 s42, s0, s53
	s_addc_u32 s43, s1, 0
	s_add_u32 s44, s0, s54
	s_addc_u32 s45, s1, 0
	s_add_u32 s46, s0, s55
	s_addc_u32 s47, s1, 0
	global_load_dwordx4 v[176:179], v234, s[32:33]
	global_load_dwordx4 v[180:183], v234, s[34:35]
	global_load_dwordx4 v[184:187], v234, s[36:37]
	global_load_dwordx4 v[188:191], v234, s[38:39]
	global_load_dwordx4 v[192:195], v234, s[40:41]
	global_load_dwordx4 v[196:199], v234, s[42:43]
	global_load_dwordx4 v[200:203], v234, s[44:45]
	global_load_dwordx4 v[204:207], v234, s[46:47]
	s_waitcnt vmcnt(8)
	v_cvt_pk_f32_fp8_e32 v[214:215], v144
	v_cvt_pk_f32_fp8_sdwa v[216:217], v144 src0_sel:WORD_1
	v_cvt_pk_f32_fp8_e32 v[218:219], v145
	v_cvt_pk_f32_fp8_sdwa v[220:221], v145 src0_sel:WORD_1
	v_pk_mul_f32 v[222:223], v[96:97], v[214:215]
	v_pk_mul_f32 v[224:225], v[98:99], v[216:217]
	v_cvt_pk_f32_fp8_e32 v[214:215], v146
	v_cvt_pk_f32_fp8_sdwa v[216:217], v146 src0_sel:WORD_1
	v_pk_fma_f32 v[222:223], v[100:101], v[218:219], v[222:223]
	v_pk_fma_f32 v[224:225], v[102:103], v[220:221], v[224:225]
	v_cvt_pk_f32_fp8_e32 v[218:219], v147
	v_cvt_pk_f32_fp8_sdwa v[220:221], v147 src0_sel:WORD_1
	v_pk_fma_f32 v[222:223], v[104:105], v[214:215], v[222:223]
	v_pk_fma_f32 v[224:225], v[106:107], v[216:217], v[224:225]
	v_pk_fma_f32 v[222:223], v[108:109], v[218:219], v[222:223]
	v_pk_fma_f32 v[224:225], v[110:111], v[220:221], v[224:225]
	v_pk_add_f32 v[222:223], v[222:223], v[224:225]
	s_nop 0
	v_add_f32_e32 v226, v222, v223
	v_cvt_pk_f32_fp8_e32 v[214:215], v148
	v_cvt_pk_f32_fp8_sdwa v[216:217], v148 src0_sel:WORD_1
	v_cvt_pk_f32_fp8_e32 v[218:219], v149
	v_cvt_pk_f32_fp8_sdwa v[220:221], v149 src0_sel:WORD_1
	v_pk_mul_f32 v[222:223], v[96:97], v[214:215]
	v_pk_mul_f32 v[224:225], v[98:99], v[216:217]
	v_cvt_pk_f32_fp8_e32 v[214:215], v150
	v_cvt_pk_f32_fp8_sdwa v[216:217], v150 src0_sel:WORD_1
	v_pk_fma_f32 v[222:223], v[100:101], v[218:219], v[222:223]
	v_pk_fma_f32 v[224:225], v[102:103], v[220:221], v[224:225]
	v_cvt_pk_f32_fp8_e32 v[218:219], v151
	v_cvt_pk_f32_fp8_sdwa v[220:221], v151 src0_sel:WORD_1
	v_pk_fma_f32 v[222:223], v[104:105], v[214:215], v[222:223]
	v_pk_fma_f32 v[224:225], v[106:107], v[216:217], v[224:225]
	v_pk_fma_f32 v[222:223], v[108:109], v[218:219], v[222:223]
	v_pk_fma_f32 v[224:225], v[110:111], v[220:221], v[224:225]
	v_pk_add_f32 v[222:223], v[222:223], v[224:225]
	s_nop 0
	v_add_f32_e32 v227, v222, v223
	v_cvt_pk_f32_fp8_e32 v[214:215], v152
	v_cvt_pk_f32_fp8_sdwa v[216:217], v152 src0_sel:WORD_1
	v_cvt_pk_f32_fp8_e32 v[218:219], v153
	v_cvt_pk_f32_fp8_sdwa v[220:221], v153 src0_sel:WORD_1
	v_pk_mul_f32 v[222:223], v[96:97], v[214:215]
	v_pk_mul_f32 v[224:225], v[98:99], v[216:217]
	v_cvt_pk_f32_fp8_e32 v[214:215], v154
	v_cvt_pk_f32_fp8_sdwa v[216:217], v154 src0_sel:WORD_1
	v_pk_fma_f32 v[222:223], v[100:101], v[218:219], v[222:223]
	v_pk_fma_f32 v[224:225], v[102:103], v[220:221], v[224:225]
	v_cvt_pk_f32_fp8_e32 v[218:219], v155
	v_cvt_pk_f32_fp8_sdwa v[220:221], v155 src0_sel:WORD_1
	v_pk_fma_f32 v[222:223], v[104:105], v[214:215], v[222:223]
	v_pk_fma_f32 v[224:225], v[106:107], v[216:217], v[224:225]
	v_pk_fma_f32 v[222:223], v[108:109], v[218:219], v[222:223]
	v_pk_fma_f32 v[224:225], v[110:111], v[220:221], v[224:225]
	v_pk_add_f32 v[222:223], v[222:223], v[224:225]
	s_nop 0
	v_add_f32_e32 v228, v222, v223
	v_cvt_pk_f32_fp8_e32 v[214:215], v156
	v_cvt_pk_f32_fp8_sdwa v[216:217], v156 src0_sel:WORD_1
	v_cvt_pk_f32_fp8_e32 v[218:219], v157
	v_cvt_pk_f32_fp8_sdwa v[220:221], v157 src0_sel:WORD_1
	v_pk_mul_f32 v[222:223], v[96:97], v[214:215]
	v_pk_mul_f32 v[224:225], v[98:99], v[216:217]
	v_cvt_pk_f32_fp8_e32 v[214:215], v158
	v_cvt_pk_f32_fp8_sdwa v[216:217], v158 src0_sel:WORD_1
	v_pk_fma_f32 v[222:223], v[100:101], v[218:219], v[222:223]
	v_pk_fma_f32 v[224:225], v[102:103], v[220:221], v[224:225]
	v_cvt_pk_f32_fp8_e32 v[218:219], v159
	v_cvt_pk_f32_fp8_sdwa v[220:221], v159 src0_sel:WORD_1
	v_pk_fma_f32 v[222:223], v[104:105], v[214:215], v[222:223]
	v_pk_fma_f32 v[224:225], v[106:107], v[216:217], v[224:225]
	v_pk_fma_f32 v[222:223], v[108:109], v[218:219], v[222:223]
	v_pk_fma_f32 v[224:225], v[110:111], v[220:221], v[224:225]
	v_pk_add_f32 v[222:223], v[222:223], v[224:225]
	s_nop 0
	v_add_f32_e32 v229, v222, v223
	v_cvt_pk_f32_fp8_e32 v[214:215], v160
	v_cvt_pk_f32_fp8_sdwa v[216:217], v160 src0_sel:WORD_1
	v_cvt_pk_f32_fp8_e32 v[218:219], v161
	v_cvt_pk_f32_fp8_sdwa v[220:221], v161 src0_sel:WORD_1
	v_pk_mul_f32 v[222:223], v[96:97], v[214:215]
	v_pk_mul_f32 v[224:225], v[98:99], v[216:217]
	v_cvt_pk_f32_fp8_e32 v[214:215], v162
; DI float gelu_exact(float x) { return 0.5f * x * (1.f + erff(x * 0.7071067811865476f)); }
; template <bool STORE>
; DI void peer_item(const Params& p, int item, char* smem) {
;     ...
; #pragma unroll 2
;     for (int k = 0; k < 128; k += 8) {
;       u32x4 uq[8];
;       const int emine = e_s[tl * 128 + k + (lane >> 3)];
;       const float gmine = g_s[tl * 128 + k + (lane >> 3)];
;       const float su = SU[emine], sv = SV[emine];
; #pragma unroll
;       for (int u = 0; u < 8; ++u) {
;         int e = e_s[tl * 128 + k + u];
;         uq[u] = *(const u32x4*)(U8 + (size_t)e * 1024 + lane * 16);
;       }
;       float part[8];
; #pragma unroll
;       for (int u = 0; u < 8; ++u) {
;         float d = 0.f;
; #pragma unroll
;         for (int i = 0; i < 4; ++i) {
;           f32x2_t lo = __builtin_amdgcn_cvt_pk_f32_fp8((int)uq[u][i], false);
;           f32x2_t hi = __builtin_amdgcn_cvt_pk_f32_fp8((int)uq[u][i], true);
;           d += xf[4 * i] * lo.x + xf[4 * i + 1] * lo.y + xf[4 * i + 2] * hi.x + xf[4 * i + 3] * hi.y;
;         }
;         part[u] = d;
;       }
;       float q4[4], r2[2], h;
; #pragma unroll
;       for (int j = 0; j < 4; ++j) {
;         float mine = b5 ? part[j + 4] : part[j];
;         float other = b5 ? part[j] : part[j + 4];
;         q4[j] = mine + __shfl_xor(other, 32);
;       }
; #pragma unroll
;       for (int j = 0; j < 2; ++j) {
;         float mine = b4 ? q4[j + 2] : q4[j];
;         float other = b4 ? q4[j] : q4[j + 2];
;         r2[j] = mine + __shfl_xor(other, 16);
;       }
;       {
;         float mine = b3 ? r2[1] : r2[0];
;         float other = b3 ? r2[0] : r2[1];
;         h = mine + __shfl_xor(other, 8);
;       }
;       h += __shfl_xor(h, 4);
;       h += __shfl_xor(h, 2);
;       h += __shfl_xor(h, 1);
;       const float amine = gelu_exact(h * su) * gmine * sv;
;       if ((lane & 7) == 0) {
;         EG[tok * 128 + k + (lane >> 3)] = emine;
;         AG[tok * 128 + k + (lane >> 3)] = amine;
;       }
;     }
	v_cvt_pk_f32_fp8_sdwa v[216:217], v162 src0_sel:WORD_1
	v_pk_fma_f32 v[222:223], v[100:101], v[218:219], v[222:223]
	v_pk_fma_f32 v[224:225], v[102:103], v[220:221], v[224:225]
	v_cvt_pk_f32_fp8_e32 v[218:219], v163
	v_cvt_pk_f32_fp8_sdwa v[220:221], v163 src0_sel:WORD_1
	v_pk_fma_f32 v[222:223], v[104:105], v[214:215], v[222:223]
	v_pk_fma_f32 v[224:225], v[106:107], v[216:217], v[224:225]
	v_pk_fma_f32 v[222:223], v[108:109], v[218:219], v[222:223]
	v_pk_fma_f32 v[224:225], v[110:111], v[220:221], v[224:225]
	v_pk_add_f32 v[222:223], v[222:223], v[224:225]
	s_nop 0
	v_add_f32_e32 v230, v222, v223
	v_cvt_pk_f32_fp8_e32 v[214:215], v164
	v_cvt_pk_f32_fp8_sdwa v[216:217], v164 src0_sel:WORD_1
	v_cvt_pk_f32_fp8_e32 v[218:219], v165
	v_cvt_pk_f32_fp8_sdwa v[220:221], v165 src0_sel:WORD_1
	v_pk_mul_f32 v[222:223], v[96:97], v[214:215]
	v_pk_mul_f32 v[224:225], v[98:99], v[216:217]
	v_cvt_pk_f32_fp8_e32 v[214:215], v166
	v_cvt_pk_f32_fp8_sdwa v[216:217], v166 src0_sel:WORD_1
	v_pk_fma_f32 v[222:223], v[100:101], v[218:219], v[222:223]
	v_pk_fma_f32 v[224:225], v[102:103], v[220:221], v[224:225]
	v_cvt_pk_f32_fp8_e32 v[218:219], v167
	v_cvt_pk_f32_fp8_sdwa v[220:221], v167 src0_sel:WORD_1
	v_pk_fma_f32 v[222:223], v[104:105], v[214:215], v[222:223]
	v_pk_fma_f32 v[224:225], v[106:107], v[216:217], v[224:225]
	v_pk_fma_f32 v[222:223], v[108:109], v[218:219], v[222:223]
	v_pk_fma_f32 v[224:225], v[110:111], v[220:221], v[224:225]
	v_pk_add_f32 v[222:223], v[222:223], v[224:225]
	s_nop 0
	v_add_f32_e32 v231, v222, v223
	v_cvt_pk_f32_fp8_e32 v[214:215], v168
	v_cvt_pk_f32_fp8_sdwa v[216:217], v168 src0_sel:WORD_1
	v_cvt_pk_f32_fp8_e32 v[218:219], v169
	v_cvt_pk_f32_fp8_sdwa v[220:221], v169 src0_sel:WORD_1
	v_pk_mul_f32 v[222:223], v[96:97], v[214:215]
	v_pk_mul_f32 v[224:225], v[98:99], v[216:217]
	v_cvt_pk_f32_fp8_e32 v[214:215], v170
	v_cvt_pk_f32_fp8_sdwa v[216:217], v170 src0_sel:WORD_1
	v_pk_fma_f32 v[222:223], v[100:101], v[218:219], v[222:223]
	v_pk_fma_f32 v[224:225], v[102:103], v[220:221], v[224:225]
	v_cvt_pk_f32_fp8_e32 v[218:219], v171
	v_cvt_pk_f32_fp8_sdwa v[220:221], v171 src0_sel:WORD_1
	v_pk_fma_f32 v[222:223], v[104:105], v[214:215], v[222:223]
	v_pk_fma_f32 v[224:225], v[106:107], v[216:217], v[224:225]
	v_pk_fma_f32 v[222:223], v[108:109], v[218:219], v[222:223]
	v_pk_fma_f32 v[224:225], v[110:111], v[220:221], v[224:225]
	v_pk_add_f32 v[222:223], v[222:223], v[224:225]
	s_nop 0
	v_add_f32_e32 v232, v222, v223
	v_cvt_pk_f32_fp8_e32 v[214:215], v172
	v_cvt_pk_f32_fp8_sdwa v[216:217], v172 src0_sel:WORD_1
	v_cvt_pk_f32_fp8_e32 v[218:219], v173
	v_cvt_pk_f32_fp8_sdwa v[220:221], v173 src0_sel:WORD_1
	v_pk_mul_f32 v[222:223], v[96:97], v[214:215]
	v_pk_mul_f32 v[224:225], v[98:99], v[216:217]
	v_cvt_pk_f32_fp8_e32 v[214:215], v174
	v_cvt_pk_f32_fp8_sdwa v[216:217], v174 src0_sel:WORD_1
	v_pk_fma_f32 v[222:223], v[100:101], v[218:219], v[222:223]
	v_pk_fma_f32 v[224:225], v[102:103], v[220:221], v[224:225]
	v_cvt_pk_f32_fp8_e32 v[218:219], v175
	v_cvt_pk_f32_fp8_sdwa v[220:221], v175 src0_sel:WORD_1
	v_pk_fma_f32 v[222:223], v[104:105], v[214:215], v[222:223]
	v_pk_fma_f32 v[224:225], v[106:107], v[216:217], v[224:225]
	v_pk_fma_f32 v[222:223], v[108:109], v[218:219], v[222:223]
	v_pk_fma_f32 v[224:225], v[110:111], v[220:221], v[224:225]
	v_pk_add_f32 v[222:223], v[222:223], v[224:225]
	s_nop 0
	v_add_f32_e32 v233, v222, v223
	v_permlane32_swap_b32_e32 v226, v230
	v_permlane32_swap_b32_e32 v227, v231
	v_permlane32_swap_b32_e32 v228, v232
	v_permlane32_swap_b32_e32 v229, v233
	v_add_f32_e32 v226, v226, v230
	v_add_f32_e32 v228, v228, v232
	v_add_f32_e32 v227, v227, v231
	v_add_f32_e32 v229, v229, v233
	s_nop 1
	v_permlane16_swap_b32_e32 v226, v228
	v_permlane16_swap_b32_e32 v227, v229
	v_add_f32_e32 v226, v226, v228
	v_add_f32_e32 v227, v227, v229
	s_nop 0
	v_cndmask_b32_e64 v230, v226, v227, s[24:25]
	v_cndmask_b32_e64 v231, v227, v226, s[24:25]
	s_nop 1
	v_add_f32_dpp v232, v231, v230 row_ror:8 row_mask:0xf bank_mask:0xf
	s_nop 1
	v_add_f32_dpp v233, v232, v232 quad_perm:[1,0,3,2] row_mask:0xf bank_mask:0xf
	s_nop 1
	v_add_f32_dpp v232, v233, v233 quad_perm:[2,3,0,1] row_mask:0xf bank_mask:0xf
	s_nop 1
	v_add_f32_dpp v233, v232, v232 row_half_mirror row_mask:0xf bank_mask:0xf
	ds_write_b32 v235, v233 offset:35840
	v_readlane_b32 s48, v129, s72
	v_readlane_b32 s49, v129, s73
	v_readlane_b32 s50, v129, s74
	v_readlane_b32 s51, v129, s75
	v_readlane_b32 s52, v129, s76
	v_readlane_b32 s53, v129, s77
	v_readlane_b32 s54, v129, s78
	v_readlane_b32 s55, v129, s79
	s_add_u32 s32, s0, s48
	s_addc_u32 s33, s1, 0
	s_add_u32 s34, s0, s49
	s_addc_u32 s35, s1, 0
	s_add_u32 s36, s0, s50
	s_addc_u32 s37, s1, 0
	s_add_u32 s38, s0, s51
	s_addc_u32 s39, s1, 0
	s_add_u32 s40, s0, s52
	s_addc_u32 s41, s1, 0
	s_add_u32 s42, s0, s53
	s_addc_u32 s43, s1, 0
	s_add_u32 s44, s0, s54
	s_addc_u32 s45, s1, 0
	s_add_u32 s46, s0, s55
	s_addc_u32 s47, s1, 0
	global_load_dwordx4 v[144:147], v234, s[32:33]
	global_load_dwordx4 v[148:151], v234, s[34:35]
	global_load_dwordx4 v[152:155], v234, s[36:37]
	global_load_dwordx4 v[156:159], v234, s[38:39]
	global_load_dwordx4 v[160:163], v234, s[40:41]
	global_load_dwordx4 v[164:167], v234, s[42:43]
	global_load_dwordx4 v[168:171], v234, s[44:45]
	global_load_dwordx4 v[172:175], v234, s[46:47]
	s_waitcnt vmcnt(8)
; template <bool STORE>
; DI void peer_item(const Params& p, int item, char* smem) {
;     ...
;       for (int u = 0; u < 8; ++u) {
;         int e = e_s[tl * 128 + k + u];
;         uq[u] = *(const u32x4*)(U8 + (size_t)e * 1024 + lane * 16);
;       }
;       float part[8];
; #pragma unroll
;       for (int u = 0; u < 8; ++u) {
;         float d = 0.f;
; #pragma unroll
;         for (int i = 0; i < 4; ++i) {
;           f32x2_t lo = __builtin_amdgcn_cvt_pk_f32_fp8((int)uq[u][i], false);
;           f32x2_t hi = __builtin_amdgcn_cvt_pk_f32_fp8((int)uq[u][i], true);
;           d += xf[4 * i] * lo.x + xf[4 * i + 1] * lo.y + xf[4 * i + 2] * hi.x + xf[4 * i + 3] * hi.y;
;         }
;         part[u] = d;
;       }
	v_cvt_pk_f32_fp8_e32 v[214:215], v176
	v_cvt_pk_f32_fp8_sdwa v[216:217], v176 src0_sel:WORD_1
	v_cvt_pk_f32_fp8_e32 v[218:219], v177
	v_cvt_pk_f32_fp8_sdwa v[220:221], v177 src0_sel:WORD_1
	v_pk_mul_f32 v[222:223], v[112:113], v[214:215]
	v_pk_mul_f32 v[224:225], v[114:115], v[216:217]
	v_cvt_pk_f32_fp8_e32 v[214:215], v178
	v_cvt_pk_f32_fp8_sdwa v[216:217], v178 src0_sel:WORD_1
	v_pk_fma_f32 v[222:223], v[116:117], v[218:219], v[222:223]
	v_pk_fma_f32 v[224:225], v[118:119], v[220:221], v[224:225]
	v_cvt_pk_f32_fp8_e32 v[218:219], v179
	v_cvt_pk_f32_fp8_sdwa v[220:221], v179 src0_sel:WORD_1
	v_pk_fma_f32 v[222:223], v[120:121], v[214:215], v[222:223]
	v_pk_fma_f32 v[224:225], v[122:123], v[216:217], v[224:225]
	v_pk_fma_f32 v[222:223], v[124:125], v[218:219], v[222:223]
	v_pk_fma_f32 v[224:225], v[126:127], v[220:221], v[224:225]
	v_pk_add_f32 v[222:223], v[222:223], v[224:225]
	s_nop 0
	v_add_f32_e32 v226, v222, v223
	v_cvt_pk_f32_fp8_e32 v[214:215], v180
	v_cvt_pk_f32_fp8_sdwa v[216:217], v180 src0_sel:WORD_1
	v_cvt_pk_f32_fp8_e32 v[218:219], v181
	v_cvt_pk_f32_fp8_sdwa v[220:221], v181 src0_sel:WORD_1
	v_pk_mul_f32 v[222:223], v[112:113], v[214:215]
	v_pk_mul_f32 v[224:225], v[114:115], v[216:217]
	v_cvt_pk_f32_fp8_e32 v[214:215], v182
	v_cvt_pk_f32_fp8_sdwa v[216:217], v182 src0_sel:WORD_1
	v_pk_fma_f32 v[222:223], v[116:117], v[218:219], v[222:223]
	v_pk_fma_f32 v[224:225], v[118:119], v[220:221], v[224:225]
	v_cvt_pk_f32_fp8_e32 v[218:219], v183
	v_cvt_pk_f32_fp8_sdwa v[220:221], v183 src0_sel:WORD_1
	v_pk_fma_f32 v[222:223], v[120:121], v[214:215], v[222:223]
	v_pk_fma_f32 v[224:225], v[122:123], v[216:217], v[224:225]
	v_pk_fma_f32 v[222:223], v[124:125], v[218:219], v[222:223]
	v_pk_fma_f32 v[224:225], v[126:127], v[220:221], v[224:225]
	v_pk_add_f32 v[222:223], v[222:223], v[224:225]
	s_nop 0
	v_add_f32_e32 v227, v222, v223
	v_cvt_pk_f32_fp8_e32 v[214:215], v184
	v_cvt_pk_f32_fp8_sdwa v[216:217], v184 src0_sel:WORD_1
	v_cvt_pk_f32_fp8_e32 v[218:219], v185
	v_cvt_pk_f32_fp8_sdwa v[220:221], v185 src0_sel:WORD_1
	v_pk_mul_f32 v[222:223], v[112:113], v[214:215]
	v_pk_mul_f32 v[224:225], v[114:115], v[216:217]
	v_cvt_pk_f32_fp8_e32 v[214:215], v186
	v_cvt_pk_f32_fp8_sdwa v[216:217], v186 src0_sel:WORD_1
	v_pk_fma_f32 v[222:223], v[116:117], v[218:219], v[222:223]
	v_pk_fma_f32 v[224:225], v[118:119], v[220:221], v[224:225]
	v_cvt_pk_f32_fp8_e32 v[218:219], v187
	v_cvt_pk_f32_fp8_sdwa v[220:221], v187 src0_sel:WORD_1
	v_pk_fma_f32 v[222:223], v[120:121], v[214:215], v[222:223]
	v_pk_fma_f32 v[224:225], v[122:123], v[216:217], v[224:225]
	v_pk_fma_f32 v[222:223], v[124:125], v[218:219], v[222:223]
	v_pk_fma_f32 v[224:225], v[126:127], v[220:221], v[224:225]
	v_pk_add_f32 v[222:223], v[222:223], v[224:225]
	s_nop 0
	v_add_f32_e32 v228, v222, v223
	v_cvt_pk_f32_fp8_e32 v[214:215], v188
	v_cvt_pk_f32_fp8_sdwa v[216:217], v188 src0_sel:WORD_1
	v_cvt_pk_f32_fp8_e32 v[218:219], v189
	v_cvt_pk_f32_fp8_sdwa v[220:221], v189 src0_sel:WORD_1
	v_pk_mul_f32 v[222:223], v[112:113], v[214:215]
	v_pk_mul_f32 v[224:225], v[114:115], v[216:217]
	v_cvt_pk_f32_fp8_e32 v[214:215], v190
	v_cvt_pk_f32_fp8_sdwa v[216:217], v190 src0_sel:WORD_1
	v_pk_fma_f32 v[222:223], v[116:117], v[218:219], v[222:223]
	v_pk_fma_f32 v[224:225], v[118:119], v[220:221], v[224:225]
	v_cvt_pk_f32_fp8_e32 v[218:219], v191
	v_cvt_pk_f32_fp8_sdwa v[220:221], v191 src0_sel:WORD_1
	v_pk_fma_f32 v[222:223], v[120:121], v[214:215], v[222:223]
	v_pk_fma_f32 v[224:225], v[122:123], v[216:217], v[224:225]
	v_pk_fma_f32 v[222:223], v[124:125], v[218:219], v[222:223]
	v_pk_fma_f32 v[224:225], v[126:127], v[220:221], v[224:225]
	v_pk_add_f32 v[222:223], v[222:223], v[224:225]
	s_nop 0
	v_add_f32_e32 v229, v222, v223
	v_cvt_pk_f32_fp8_e32 v[214:215], v192
	v_cvt_pk_f32_fp8_sdwa v[216:217], v192 src0_sel:WORD_1
	v_cvt_pk_f32_fp8_e32 v[218:219], v193
	v_cvt_pk_f32_fp8_sdwa v[220:221], v193 src0_sel:WORD_1
	v_pk_mul_f32 v[222:223], v[112:113], v[214:215]
	v_pk_mul_f32 v[224:225], v[114:115], v[216:217]
	v_cvt_pk_f32_fp8_e32 v[214:215], v194
	v_cvt_pk_f32_fp8_sdwa v[216:217], v194 src0_sel:WORD_1
	v_pk_fma_f32 v[222:223], v[116:117], v[218:219], v[222:223]
	v_pk_fma_f32 v[224:225], v[118:119], v[220:221], v[224:225]
	v_cvt_pk_f32_fp8_e32 v[218:219], v195
	v_cvt_pk_f32_fp8_sdwa v[220:221], v195 src0_sel:WORD_1
	v_pk_fma_f32 v[222:223], v[120:121], v[214:215], v[222:223]
	v_pk_fma_f32 v[224:225], v[122:123], v[216:217], v[224:225]
	v_pk_fma_f32 v[222:223], v[124:125], v[218:219], v[222:223]
	v_pk_fma_f32 v[224:225], v[126:127], v[220:221], v[224:225]
	v_pk_add_f32 v[222:223], v[222:223], v[224:225]
	s_nop 0
	v_add_f32_e32 v230, v222, v223
	v_cvt_pk_f32_fp8_e32 v[214:215], v196
	v_cvt_pk_f32_fp8_sdwa v[216:217], v196 src0_sel:WORD_1
	v_cvt_pk_f32_fp8_e32 v[218:219], v197
	v_cvt_pk_f32_fp8_sdwa v[220:221], v197 src0_sel:WORD_1
	v_pk_mul_f32 v[222:223], v[112:113], v[214:215]
	v_pk_mul_f32 v[224:225], v[114:115], v[216:217]
	v_cvt_pk_f32_fp8_e32 v[214:215], v198
	v_cvt_pk_f32_fp8_sdwa v[216:217], v198 src0_sel:WORD_1
	v_pk_fma_f32 v[222:223], v[116:117], v[218:219], v[222:223]
	v_pk_fma_f32 v[224:225], v[118:119], v[220:221], v[224:225]
	v_cvt_pk_f32_fp8_e32 v[218:219], v199
	v_cvt_pk_f32_fp8_sdwa v[220:221], v199 src0_sel:WORD_1
	v_pk_fma_f32 v[222:223], v[120:121], v[214:215], v[222:223]
	v_pk_fma_f32 v[224:225], v[122:123], v[216:217], v[224:225]
	v_pk_fma_f32 v[222:223], v[124:125], v[218:219], v[222:223]
	v_pk_fma_f32 v[224:225], v[126:127], v[220:221], v[224:225]
	v_pk_add_f32 v[222:223], v[222:223], v[224:225]
	s_nop 0
	v_add_f32_e32 v231, v222, v223
	v_cvt_pk_f32_fp8_e32 v[214:215], v200
; template <bool STORE>
; DI void peer_item(const Params& p, int item, char* smem) {
;     ...
;       for (int u = 0; u < 8; ++u) {
;         int e = e_s[tl * 128 + k + u];
;         uq[u] = *(const u32x4*)(U8 + (size_t)e * 1024 + lane * 16);
;       }
;       float part[8];
; #pragma unroll
;       for (int u = 0; u < 8; ++u) {
;         float d = 0.f;
; #pragma unroll
;         for (int i = 0; i < 4; ++i) {
;           f32x2_t lo = __builtin_amdgcn_cvt_pk_f32_fp8((int)uq[u][i], false);
;           f32x2_t hi = __builtin_amdgcn_cvt_pk_f32_fp8((int)uq[u][i], true);
;           d += xf[4 * i] * lo.x + xf[4 * i + 1] * lo.y + xf[4 * i + 2] * hi.x + xf[4 * i + 3] * hi.y;
;         }
;         part[u] = d;
;       }
;       float q4[4], r2[2], h;
; #pragma unroll
;       for (int j = 0; j < 4; ++j) {
;         float mine = b5 ? part[j + 4] : part[j];
;         float other = b5 ? part[j] : part[j + 4];
;         q4[j] = mine + __shfl_xor(other, 32);
;       }
; #pragma unroll
;       for (int j = 0; j < 2; ++j) {
;         float mine = b4 ? q4[j + 2] : q4[j];
;         float other = b4 ? q4[j] : q4[j + 2];
;         r2[j] = mine + __shfl_xor(other, 16);
;       }
;       {
;         float mine = b3 ? r2[1] : r2[0];
;         float other = b3 ? r2[0] : r2[1];
;         h = mine + __shfl_xor(other, 8);
;       }
;       h += __shfl_xor(h, 4);
;       h += __shfl_xor(h, 2);
;       h += __shfl_xor(h, 1);
	v_cvt_pk_f32_fp8_sdwa v[216:217], v200 src0_sel:WORD_1
	v_cvt_pk_f32_fp8_e32 v[218:219], v201
	v_cvt_pk_f32_fp8_sdwa v[220:221], v201 src0_sel:WORD_1
	v_pk_mul_f32 v[222:223], v[112:113], v[214:215]
	v_pk_mul_f32 v[224:225], v[114:115], v[216:217]
	v_cvt_pk_f32_fp8_e32 v[214:215], v202
	v_cvt_pk_f32_fp8_sdwa v[216:217], v202 src0_sel:WORD_1
	v_pk_fma_f32 v[222:223], v[116:117], v[218:219], v[222:223]
	v_pk_fma_f32 v[224:225], v[118:119], v[220:221], v[224:225]
	v_cvt_pk_f32_fp8_e32 v[218:219], v203
	v_cvt_pk_f32_fp8_sdwa v[220:221], v203 src0_sel:WORD_1
	v_pk_fma_f32 v[222:223], v[120:121], v[214:215], v[222:223]
	v_pk_fma_f32 v[224:225], v[122:123], v[216:217], v[224:225]
	v_pk_fma_f32 v[222:223], v[124:125], v[218:219], v[222:223]
	v_pk_fma_f32 v[224:225], v[126:127], v[220:221], v[224:225]
	v_pk_add_f32 v[222:223], v[222:223], v[224:225]
	s_nop 0
	v_add_f32_e32 v232, v222, v223
	v_cvt_pk_f32_fp8_e32 v[214:215], v204
	v_cvt_pk_f32_fp8_sdwa v[216:217], v204 src0_sel:WORD_1
	v_cvt_pk_f32_fp8_e32 v[218:219], v205
	v_cvt_pk_f32_fp8_sdwa v[220:221], v205 src0_sel:WORD_1
	v_pk_mul_f32 v[222:223], v[112:113], v[214:215]
	v_pk_mul_f32 v[224:225], v[114:115], v[216:217]
	v_cvt_pk_f32_fp8_e32 v[214:215], v206
	v_cvt_pk_f32_fp8_sdwa v[216:217], v206 src0_sel:WORD_1
	v_pk_fma_f32 v[222:223], v[116:117], v[218:219], v[222:223]
	v_pk_fma_f32 v[224:225], v[118:119], v[220:221], v[224:225]
	v_cvt_pk_f32_fp8_e32 v[218:219], v207
	v_cvt_pk_f32_fp8_sdwa v[220:221], v207 src0_sel:WORD_1
	v_pk_fma_f32 v[222:223], v[120:121], v[214:215], v[222:223]
	v_pk_fma_f32 v[224:225], v[122:123], v[216:217], v[224:225]
	v_pk_fma_f32 v[222:223], v[124:125], v[218:219], v[222:223]
	v_pk_fma_f32 v[224:225], v[126:127], v[220:221], v[224:225]
	v_pk_add_f32 v[222:223], v[222:223], v[224:225]
	s_nop 0
	v_add_f32_e32 v233, v222, v223
	v_permlane32_swap_b32_e32 v226, v230
	v_permlane32_swap_b32_e32 v227, v231
	v_permlane32_swap_b32_e32 v228, v232
	v_permlane32_swap_b32_e32 v229, v233
	v_add_f32_e32 v226, v226, v230
	v_add_f32_e32 v228, v228, v232
	v_add_f32_e32 v227, v227, v231
	v_add_f32_e32 v229, v229, v233
	s_nop 1
	v_permlane16_swap_b32_e32 v226, v228
	v_permlane16_swap_b32_e32 v227, v229
	v_add_f32_e32 v226, v226, v228
	v_add_f32_e32 v227, v227, v229
	s_nop 0
	v_cndmask_b32_e64 v230, v226, v227, s[24:25]
	v_cndmask_b32_e64 v231, v227, v226, s[24:25]
	s_nop 1
	v_add_f32_dpp v232, v231, v230 row_ror:8 row_mask:0xf bank_mask:0xf
	s_nop 1
	v_add_f32_dpp v233, v232, v232 quad_perm:[1,0,3,2] row_mask:0xf bank_mask:0xf
	s_nop 1
	v_add_f32_dpp v232, v233, v233 quad_perm:[2,3,0,1] row_mask:0xf bank_mask:0xf
	s_nop 1
	v_add_f32_dpp v233, v232, v232 row_half_mirror row_mask:0xf bank_mask:0xf
	ds_write_b32 v235, v233 offset:36352
	v_readlane_b32 s48, v131, s72
	v_readlane_b32 s49, v131, s73
	v_readlane_b32 s50, v131, s74
	v_readlane_b32 s51, v131, s75
	v_readlane_b32 s52, v131, s76
	v_readlane_b32 s53, v131, s77
	v_readlane_b32 s54, v131, s78
	v_readlane_b32 s55, v131, s79
	s_add_u32 s32, s0, s48
	s_addc_u32 s33, s1, 0
	s_add_u32 s34, s0, s49
	s_addc_u32 s35, s1, 0
	s_add_u32 s36, s0, s50
	s_addc_u32 s37, s1, 0
	s_add_u32 s38, s0, s51
	s_addc_u32 s39, s1, 0
	s_add_u32 s40, s0, s52
	s_addc_u32 s41, s1, 0
	s_add_u32 s42, s0, s53
	s_addc_u32 s43, s1, 0
	s_add_u32 s44, s0, s54
	s_addc_u32 s45, s1, 0
	s_add_u32 s46, s0, s55
	s_addc_u32 s47, s1, 0
	global_load_dwordx4 v[176:179], v234, s[32:33]
	global_load_dwordx4 v[180:183], v234, s[34:35]
	global_load_dwordx4 v[184:187], v234, s[36:37]
	global_load_dwordx4 v[188:191], v234, s[38:39]
	global_load_dwordx4 v[192:195], v234, s[40:41]
	global_load_dwordx4 v[196:199], v234, s[42:43]
	global_load_dwordx4 v[200:203], v234, s[44:45]
	global_load_dwordx4 v[204:207], v234, s[46:47]
	s_waitcnt vmcnt(8)
	v_cvt_pk_f32_fp8_e32 v[214:215], v144
	v_cvt_pk_f32_fp8_sdwa v[216:217], v144 src0_sel:WORD_1
	v_cvt_pk_f32_fp8_e32 v[218:219], v145
	v_cvt_pk_f32_fp8_sdwa v[220:221], v145 src0_sel:WORD_1
	v_pk_mul_f32 v[222:223], v[0:1], v[214:215]
	v_pk_mul_f32 v[224:225], v[2:3], v[216:217]
	v_cvt_pk_f32_fp8_e32 v[214:215], v146
	v_cvt_pk_f32_fp8_sdwa v[216:217], v146 src0_sel:WORD_1
	v_pk_fma_f32 v[222:223], v[4:5], v[218:219], v[222:223]
	v_pk_fma_f32 v[224:225], v[6:7], v[220:221], v[224:225]
	v_cvt_pk_f32_fp8_e32 v[218:219], v147
	v_cvt_pk_f32_fp8_sdwa v[220:221], v147 src0_sel:WORD_1
	v_pk_fma_f32 v[222:223], v[8:9], v[214:215], v[222:223]
	v_pk_fma_f32 v[224:225], v[10:11], v[216:217], v[224:225]
	v_pk_fma_f32 v[222:223], v[12:13], v[218:219], v[222:223]
	v_pk_fma_f32 v[224:225], v[14:15], v[220:221], v[224:225]
	v_pk_add_f32 v[222:223], v[222:223], v[224:225]
	s_nop 0
	v_add_f32_e32 v226, v222, v223
	v_cvt_pk_f32_fp8_e32 v[214:215], v148
	v_cvt_pk_f32_fp8_sdwa v[216:217], v148 src0_sel:WORD_1
	v_cvt_pk_f32_fp8_e32 v[218:219], v149
	v_cvt_pk_f32_fp8_sdwa v[220:221], v149 src0_sel:WORD_1
	v_pk_mul_f32 v[222:223], v[0:1], v[214:215]
	v_pk_mul_f32 v[224:225], v[2:3], v[216:217]
	v_cvt_pk_f32_fp8_e32 v[214:215], v150
	v_cvt_pk_f32_fp8_sdwa v[216:217], v150 src0_sel:WORD_1
	v_pk_fma_f32 v[222:223], v[4:5], v[218:219], v[222:223]
	v_pk_fma_f32 v[224:225], v[6:7], v[220:221], v[224:225]
	v_cvt_pk_f32_fp8_e32 v[218:219], v151
	v_cvt_pk_f32_fp8_sdwa v[220:221], v151 src0_sel:WORD_1
	v_pk_fma_f32 v[222:223], v[8:9], v[214:215], v[222:223]
	v_pk_fma_f32 v[224:225], v[10:11], v[216:217], v[224:225]
	v_pk_fma_f32 v[222:223], v[12:13], v[218:219], v[222:223]
	v_pk_fma_f32 v[224:225], v[14:15], v[220:221], v[224:225]
	v_pk_add_f32 v[222:223], v[222:223], v[224:225]
	s_nop 0
	v_add_f32_e32 v227, v222, v223
	v_cvt_pk_f32_fp8_e32 v[214:215], v152
; template <bool STORE>
; DI void peer_item(const Params& p, int item, char* smem) {
;     ...
; #pragma unroll
;       for (int u = 0; u < 8; ++u) {
;         float d = 0.f;
; #pragma unroll
;         for (int i = 0; i < 4; ++i) {
;           f32x2_t lo = __builtin_amdgcn_cvt_pk_f32_fp8((int)uq[u][i], false);
;           f32x2_t hi = __builtin_amdgcn_cvt_pk_f32_fp8((int)uq[u][i], true);
;           d += xf[4 * i] * lo.x + xf[4 * i + 1] * lo.y + xf[4 * i + 2] * hi.x + xf[4 * i + 3] * hi.y;
;         }
;         part[u] = d;
;       }
;       float q4[4], r2[2], h;
; #pragma unroll
;       for (int j = 0; j < 4; ++j) {
;         float mine = b5 ? part[j + 4] : part[j];
;         float other = b5 ? part[j] : part[j + 4];
;         q4[j] = mine + __shfl_xor(other, 32);
	v_cvt_pk_f32_fp8_sdwa v[216:217], v152 src0_sel:WORD_1
	v_cvt_pk_f32_fp8_e32 v[218:219], v153
	v_cvt_pk_f32_fp8_sdwa v[220:221], v153 src0_sel:WORD_1
	v_pk_mul_f32 v[222:223], v[0:1], v[214:215]
	v_pk_mul_f32 v[224:225], v[2:3], v[216:217]
	v_cvt_pk_f32_fp8_e32 v[214:215], v154
	v_cvt_pk_f32_fp8_sdwa v[216:217], v154 src0_sel:WORD_1
	v_pk_fma_f32 v[222:223], v[4:5], v[218:219], v[222:223]
	v_pk_fma_f32 v[224:225], v[6:7], v[220:221], v[224:225]
	v_cvt_pk_f32_fp8_e32 v[218:219], v155
	v_cvt_pk_f32_fp8_sdwa v[220:221], v155 src0_sel:WORD_1
	v_pk_fma_f32 v[222:223], v[8:9], v[214:215], v[222:223]
	v_pk_fma_f32 v[224:225], v[10:11], v[216:217], v[224:225]
	v_pk_fma_f32 v[222:223], v[12:13], v[218:219], v[222:223]
	v_pk_fma_f32 v[224:225], v[14:15], v[220:221], v[224:225]
	v_pk_add_f32 v[222:223], v[222:223], v[224:225]
	s_nop 0
	v_add_f32_e32 v228, v222, v223
	v_cvt_pk_f32_fp8_e32 v[214:215], v156
	v_cvt_pk_f32_fp8_sdwa v[216:217], v156 src0_sel:WORD_1
	v_cvt_pk_f32_fp8_e32 v[218:219], v157
	v_cvt_pk_f32_fp8_sdwa v[220:221], v157 src0_sel:WORD_1
	v_pk_mul_f32 v[222:223], v[0:1], v[214:215]
	v_pk_mul_f32 v[224:225], v[2:3], v[216:217]
	v_cvt_pk_f32_fp8_e32 v[214:215], v158
	v_cvt_pk_f32_fp8_sdwa v[216:217], v158 src0_sel:WORD_1
	v_pk_fma_f32 v[222:223], v[4:5], v[218:219], v[222:223]
	v_pk_fma_f32 v[224:225], v[6:7], v[220:221], v[224:225]
	v_cvt_pk_f32_fp8_e32 v[218:219], v159
	v_cvt_pk_f32_fp8_sdwa v[220:221], v159 src0_sel:WORD_1
	v_pk_fma_f32 v[222:223], v[8:9], v[214:215], v[222:223]
	v_pk_fma_f32 v[224:225], v[10:11], v[216:217], v[224:225]
	v_pk_fma_f32 v[222:223], v[12:13], v[218:219], v[222:223]
	v_pk_fma_f32 v[224:225], v[14:15], v[220:221], v[224:225]
	v_pk_add_f32 v[222:223], v[222:223], v[224:225]
	s_nop 0
	v_add_f32_e32 v229, v222, v223
	v_cvt_pk_f32_fp8_e32 v[214:215], v160
	v_cvt_pk_f32_fp8_sdwa v[216:217], v160 src0_sel:WORD_1
	v_cvt_pk_f32_fp8_e32 v[218:219], v161
	v_cvt_pk_f32_fp8_sdwa v[220:221], v161 src0_sel:WORD_1
	v_pk_mul_f32 v[222:223], v[0:1], v[214:215]
	v_pk_mul_f32 v[224:225], v[2:3], v[216:217]
	v_cvt_pk_f32_fp8_e32 v[214:215], v162
	v_cvt_pk_f32_fp8_sdwa v[216:217], v162 src0_sel:WORD_1
	v_pk_fma_f32 v[222:223], v[4:5], v[218:219], v[222:223]
	v_pk_fma_f32 v[224:225], v[6:7], v[220:221], v[224:225]
	v_cvt_pk_f32_fp8_e32 v[218:219], v163
	v_cvt_pk_f32_fp8_sdwa v[220:221], v163 src0_sel:WORD_1
	v_pk_fma_f32 v[222:223], v[8:9], v[214:215], v[222:223]
	v_pk_fma_f32 v[224:225], v[10:11], v[216:217], v[224:225]
	v_pk_fma_f32 v[222:223], v[12:13], v[218:219], v[222:223]
	v_pk_fma_f32 v[224:225], v[14:15], v[220:221], v[224:225]
	v_pk_add_f32 v[222:223], v[222:223], v[224:225]
	s_nop 0
	v_add_f32_e32 v230, v222, v223
	v_cvt_pk_f32_fp8_e32 v[214:215], v164
	v_cvt_pk_f32_fp8_sdwa v[216:217], v164 src0_sel:WORD_1
	v_cvt_pk_f32_fp8_e32 v[218:219], v165
	v_cvt_pk_f32_fp8_sdwa v[220:221], v165 src0_sel:WORD_1
	v_pk_mul_f32 v[222:223], v[0:1], v[214:215]
	v_pk_mul_f32 v[224:225], v[2:3], v[216:217]
	v_cvt_pk_f32_fp8_e32 v[214:215], v166
	v_cvt_pk_f32_fp8_sdwa v[216:217], v166 src0_sel:WORD_1
	v_pk_fma_f32 v[222:223], v[4:5], v[218:219], v[222:223]
	v_pk_fma_f32 v[224:225], v[6:7], v[220:221], v[224:225]
	v_cvt_pk_f32_fp8_e32 v[218:219], v167
	v_cvt_pk_f32_fp8_sdwa v[220:221], v167 src0_sel:WORD_1
	v_pk_fma_f32 v[222:223], v[8:9], v[214:215], v[222:223]
	v_pk_fma_f32 v[224:225], v[10:11], v[216:217], v[224:225]
	v_pk_fma_f32 v[222:223], v[12:13], v[218:219], v[222:223]
	v_pk_fma_f32 v[224:225], v[14:15], v[220:221], v[224:225]
	v_pk_add_f32 v[222:223], v[222:223], v[224:225]
	s_nop 0
	v_add_f32_e32 v231, v222, v223
	v_cvt_pk_f32_fp8_e32 v[214:215], v168
	v_cvt_pk_f32_fp8_sdwa v[216:217], v168 src0_sel:WORD_1
	v_cvt_pk_f32_fp8_e32 v[218:219], v169
	v_cvt_pk_f32_fp8_sdwa v[220:221], v169 src0_sel:WORD_1
	v_pk_mul_f32 v[222:223], v[0:1], v[214:215]
	v_pk_mul_f32 v[224:225], v[2:3], v[216:217]
	v_cvt_pk_f32_fp8_e32 v[214:215], v170
	v_cvt_pk_f32_fp8_sdwa v[216:217], v170 src0_sel:WORD_1
	v_pk_fma_f32 v[222:223], v[4:5], v[218:219], v[222:223]
	v_pk_fma_f32 v[224:225], v[6:7], v[220:221], v[224:225]
	v_cvt_pk_f32_fp8_e32 v[218:219], v171
	v_cvt_pk_f32_fp8_sdwa v[220:221], v171 src0_sel:WORD_1
	v_pk_fma_f32 v[222:223], v[8:9], v[214:215], v[222:223]
	v_pk_fma_f32 v[224:225], v[10:11], v[216:217], v[224:225]
	v_pk_fma_f32 v[222:223], v[12:13], v[218:219], v[222:223]
	v_pk_fma_f32 v[224:225], v[14:15], v[220:221], v[224:225]
	v_pk_add_f32 v[222:223], v[222:223], v[224:225]
	s_nop 0
	v_add_f32_e32 v232, v222, v223
	v_cvt_pk_f32_fp8_e32 v[214:215], v172
	v_cvt_pk_f32_fp8_sdwa v[216:217], v172 src0_sel:WORD_1
	v_cvt_pk_f32_fp8_e32 v[218:219], v173
	v_cvt_pk_f32_fp8_sdwa v[220:221], v173 src0_sel:WORD_1
	v_pk_mul_f32 v[222:223], v[0:1], v[214:215]
	v_pk_mul_f32 v[224:225], v[2:3], v[216:217]
	v_cvt_pk_f32_fp8_e32 v[214:215], v174
	v_cvt_pk_f32_fp8_sdwa v[216:217], v174 src0_sel:WORD_1
	v_pk_fma_f32 v[222:223], v[4:5], v[218:219], v[222:223]
	v_pk_fma_f32 v[224:225], v[6:7], v[220:221], v[224:225]
	v_cvt_pk_f32_fp8_e32 v[218:219], v175
	v_cvt_pk_f32_fp8_sdwa v[220:221], v175 src0_sel:WORD_1
	v_pk_fma_f32 v[222:223], v[8:9], v[214:215], v[222:223]
	v_pk_fma_f32 v[224:225], v[10:11], v[216:217], v[224:225]
	v_pk_fma_f32 v[222:223], v[12:13], v[218:219], v[222:223]
	v_pk_fma_f32 v[224:225], v[14:15], v[220:221], v[224:225]
	v_pk_add_f32 v[222:223], v[222:223], v[224:225]
	s_nop 0
	v_add_f32_e32 v233, v222, v223
	v_permlane32_swap_b32_e32 v226, v230
	v_permlane32_swap_b32_e32 v227, v231
	v_permlane32_swap_b32_e32 v228, v232
	v_permlane32_swap_b32_e32 v229, v233
	v_add_f32_e32 v226, v226, v230
	v_add_f32_e32 v228, v228, v232
; DI float gelu_exact(float x) { return 0.5f * x * (1.f + erff(x * 0.7071067811865476f)); }
; template <bool STORE>
; DI void peer_item(const Params& p, int item, char* smem) {
;     ...
;       float q4[4], r2[2], h;
; #pragma unroll
;       for (int j = 0; j < 4; ++j) {
;         float mine = b5 ? part[j + 4] : part[j];
;         float other = b5 ? part[j] : part[j + 4];
;         q4[j] = mine + __shfl_xor(other, 32);
;       }
; #pragma unroll
;       for (int j = 0; j < 2; ++j) {
;         float mine = b4 ? q4[j + 2] : q4[j];
;         float other = b4 ? q4[j] : q4[j + 2];
;         r2[j] = mine + __shfl_xor(other, 16);
;       }
;       {
;         float mine = b3 ? r2[1] : r2[0];
;         float other = b3 ? r2[0] : r2[1];
;         h = mine + __shfl_xor(other, 8);
;       }
;       h += __shfl_xor(h, 4);
;       h += __shfl_xor(h, 2);
;       h += __shfl_xor(h, 1);
;       const float amine = gelu_exact(h * su) * gmine * sv;
;       if ((lane & 7) == 0) {
;         EG[tok * 128 + k + (lane >> 3)] = emine;
;         AG[tok * 128 + k + (lane >> 3)] = amine;
;       }
;     }
	v_add_f32_e32 v227, v227, v231
	v_add_f32_e32 v229, v229, v233
	s_nop 1
	v_permlane16_swap_b32_e32 v226, v228
	v_permlane16_swap_b32_e32 v227, v229
	v_add_f32_e32 v226, v226, v228
	v_add_f32_e32 v227, v227, v229
	s_nop 0
	v_cndmask_b32_e64 v230, v226, v227, s[24:25]
	v_cndmask_b32_e64 v231, v227, v226, s[24:25]
	s_nop 1
	v_add_f32_dpp v232, v231, v230 row_ror:8 row_mask:0xf bank_mask:0xf
	s_nop 1
	v_add_f32_dpp v233, v232, v232 quad_perm:[1,0,3,2] row_mask:0xf bank_mask:0xf
	s_nop 1
	v_add_f32_dpp v232, v233, v233 quad_perm:[2,3,0,1] row_mask:0xf bank_mask:0xf
	s_nop 1
	v_add_f32_dpp v233, v232, v232 row_half_mirror row_mask:0xf bank_mask:0xf
	ds_write_b32 v235, v233 offset:32800
	v_readlane_b32 s48, v133, s72
	v_readlane_b32 s49, v133, s73
	v_readlane_b32 s50, v133, s74
	v_readlane_b32 s51, v133, s75
	v_readlane_b32 s52, v133, s76
	v_readlane_b32 s53, v133, s77
	v_readlane_b32 s54, v133, s78
	v_readlane_b32 s55, v133, s79
	s_add_u32 s32, s0, s48
	s_addc_u32 s33, s1, 0
	s_add_u32 s34, s0, s49
	s_addc_u32 s35, s1, 0
	s_add_u32 s36, s0, s50
	s_addc_u32 s37, s1, 0
	s_add_u32 s38, s0, s51
	s_addc_u32 s39, s1, 0
	s_add_u32 s40, s0, s52
	s_addc_u32 s41, s1, 0
	s_add_u32 s42, s0, s53
	s_addc_u32 s43, s1, 0
	s_add_u32 s44, s0, s54
	s_addc_u32 s45, s1, 0
	s_add_u32 s46, s0, s55
	s_addc_u32 s47, s1, 0
	global_load_dwordx4 v[144:147], v234, s[32:33]
	global_load_dwordx4 v[148:151], v234, s[34:35]
	global_load_dwordx4 v[152:155], v234, s[36:37]
	global_load_dwordx4 v[156:159], v234, s[38:39]
	global_load_dwordx4 v[160:163], v234, s[40:41]
	global_load_dwordx4 v[164:167], v234, s[42:43]
	global_load_dwordx4 v[168:171], v234, s[44:45]
	global_load_dwordx4 v[172:175], v234, s[46:47]
	s_waitcnt vmcnt(8)
	v_cvt_pk_f32_fp8_e32 v[214:215], v176
	v_cvt_pk_f32_fp8_sdwa v[216:217], v176 src0_sel:WORD_1
	v_cvt_pk_f32_fp8_e32 v[218:219], v177
	v_cvt_pk_f32_fp8_sdwa v[220:221], v177 src0_sel:WORD_1
	v_pk_mul_f32 v[222:223], v[16:17], v[214:215]
	v_pk_mul_f32 v[224:225], v[18:19], v[216:217]
	v_cvt_pk_f32_fp8_e32 v[214:215], v178
	v_cvt_pk_f32_fp8_sdwa v[216:217], v178 src0_sel:WORD_1
	v_pk_fma_f32 v[222:223], v[20:21], v[218:219], v[222:223]
	v_pk_fma_f32 v[224:225], v[22:23], v[220:221], v[224:225]
	v_cvt_pk_f32_fp8_e32 v[218:219], v179
	v_cvt_pk_f32_fp8_sdwa v[220:221], v179 src0_sel:WORD_1
	v_pk_fma_f32 v[222:223], v[24:25], v[214:215], v[222:223]
	v_pk_fma_f32 v[224:225], v[26:27], v[216:217], v[224:225]
	v_pk_fma_f32 v[222:223], v[28:29], v[218:219], v[222:223]
	v_pk_fma_f32 v[224:225], v[30:31], v[220:221], v[224:225]
	v_pk_add_f32 v[222:223], v[222:223], v[224:225]
	s_nop 0
	v_add_f32_e32 v226, v222, v223
	v_cvt_pk_f32_fp8_e32 v[214:215], v180
	v_cvt_pk_f32_fp8_sdwa v[216:217], v180 src0_sel:WORD_1
	v_cvt_pk_f32_fp8_e32 v[218:219], v181
	v_cvt_pk_f32_fp8_sdwa v[220:221], v181 src0_sel:WORD_1
	v_pk_mul_f32 v[222:223], v[16:17], v[214:215]
	v_pk_mul_f32 v[224:225], v[18:19], v[216:217]
	v_cvt_pk_f32_fp8_e32 v[214:215], v182
	v_cvt_pk_f32_fp8_sdwa v[216:217], v182 src0_sel:WORD_1
	v_pk_fma_f32 v[222:223], v[20:21], v[218:219], v[222:223]
	v_pk_fma_f32 v[224:225], v[22:23], v[220:221], v[224:225]
	v_cvt_pk_f32_fp8_e32 v[218:219], v183
	v_cvt_pk_f32_fp8_sdwa v[220:221], v183 src0_sel:WORD_1
	v_pk_fma_f32 v[222:223], v[24:25], v[214:215], v[222:223]
	v_pk_fma_f32 v[224:225], v[26:27], v[216:217], v[224:225]
	v_pk_fma_f32 v[222:223], v[28:29], v[218:219], v[222:223]
	v_pk_fma_f32 v[224:225], v[30:31], v[220:221], v[224:225]
	v_pk_add_f32 v[222:223], v[222:223], v[224:225]
	s_nop 0
	v_add_f32_e32 v227, v222, v223
	v_cvt_pk_f32_fp8_e32 v[214:215], v184
	v_cvt_pk_f32_fp8_sdwa v[216:217], v184 src0_sel:WORD_1
	v_cvt_pk_f32_fp8_e32 v[218:219], v185
	v_cvt_pk_f32_fp8_sdwa v[220:221], v185 src0_sel:WORD_1
	v_pk_mul_f32 v[222:223], v[16:17], v[214:215]
	v_pk_mul_f32 v[224:225], v[18:19], v[216:217]
	v_cvt_pk_f32_fp8_e32 v[214:215], v186
	v_cvt_pk_f32_fp8_sdwa v[216:217], v186 src0_sel:WORD_1
	v_pk_fma_f32 v[222:223], v[20:21], v[218:219], v[222:223]
	v_pk_fma_f32 v[224:225], v[22:23], v[220:221], v[224:225]
	v_cvt_pk_f32_fp8_e32 v[218:219], v187
	v_cvt_pk_f32_fp8_sdwa v[220:221], v187 src0_sel:WORD_1
	v_pk_fma_f32 v[222:223], v[24:25], v[214:215], v[222:223]
	v_pk_fma_f32 v[224:225], v[26:27], v[216:217], v[224:225]
	v_pk_fma_f32 v[222:223], v[28:29], v[218:219], v[222:223]
	v_pk_fma_f32 v[224:225], v[30:31], v[220:221], v[224:225]
	v_pk_add_f32 v[222:223], v[222:223], v[224:225]
	s_nop 0
	v_add_f32_e32 v228, v222, v223
	v_cvt_pk_f32_fp8_e32 v[214:215], v188
	v_cvt_pk_f32_fp8_sdwa v[216:217], v188 src0_sel:WORD_1
	v_cvt_pk_f32_fp8_e32 v[218:219], v189
	v_cvt_pk_f32_fp8_sdwa v[220:221], v189 src0_sel:WORD_1
	v_pk_mul_f32 v[222:223], v[16:17], v[214:215]
	v_pk_mul_f32 v[224:225], v[18:19], v[216:217]
	v_cvt_pk_f32_fp8_e32 v[214:215], v190
	v_cvt_pk_f32_fp8_sdwa v[216:217], v190 src0_sel:WORD_1
	v_pk_fma_f32 v[222:223], v[20:21], v[218:219], v[222:223]
	v_pk_fma_f32 v[224:225], v[22:23], v[220:221], v[224:225]
	v_cvt_pk_f32_fp8_e32 v[218:219], v191
	v_cvt_pk_f32_fp8_sdwa v[220:221], v191 src0_sel:WORD_1
	v_pk_fma_f32 v[222:223], v[24:25], v[214:215], v[222:223]
	v_pk_fma_f32 v[224:225], v[26:27], v[216:217], v[224:225]
	v_pk_fma_f32 v[222:223], v[28:29], v[218:219], v[222:223]
	v_pk_fma_f32 v[224:225], v[30:31], v[220:221], v[224:225]
	v_pk_add_f32 v[222:223], v[222:223], v[224:225]
	s_nop 0
	v_add_f32_e32 v229, v222, v223
	v_cvt_pk_f32_fp8_e32 v[214:215], v192
	v_cvt_pk_f32_fp8_sdwa v[216:217], v192 src0_sel:WORD_1
	v_cvt_pk_f32_fp8_e32 v[218:219], v193
	v_cvt_pk_f32_fp8_sdwa v[220:221], v193 src0_sel:WORD_1
	v_pk_mul_f32 v[222:223], v[16:17], v[214:215]
; DI float gelu_exact(float x) { return 0.5f * x * (1.f + erff(x * 0.7071067811865476f)); }
; template <bool STORE>
; DI void peer_item(const Params& p, int item, char* smem) {
;     ...
; #pragma unroll
;       for (int u = 0; u < 8; ++u) {
;         float d = 0.f;
; #pragma unroll
;         for (int i = 0; i < 4; ++i) {
;           f32x2_t lo = __builtin_amdgcn_cvt_pk_f32_fp8((int)uq[u][i], false);
;           f32x2_t hi = __builtin_amdgcn_cvt_pk_f32_fp8((int)uq[u][i], true);
;           d += xf[4 * i] * lo.x + xf[4 * i + 1] * lo.y + xf[4 * i + 2] * hi.x + xf[4 * i + 3] * hi.y;
;         }
;         part[u] = d;
;       }
;       float q4[4], r2[2], h;
; #pragma unroll
;       for (int j = 0; j < 4; ++j) {
;         float mine = b5 ? part[j + 4] : part[j];
;         float other = b5 ? part[j] : part[j + 4];
;         q4[j] = mine + __shfl_xor(other, 32);
;       }
; #pragma unroll
;       for (int j = 0; j < 2; ++j) {
;         float mine = b4 ? q4[j + 2] : q4[j];
;         float other = b4 ? q4[j] : q4[j + 2];
;         r2[j] = mine + __shfl_xor(other, 16);
;       }
;       {
;         float mine = b3 ? r2[1] : r2[0];
;         float other = b3 ? r2[0] : r2[1];
;         h = mine + __shfl_xor(other, 8);
;       }
;       h += __shfl_xor(h, 4);
;       h += __shfl_xor(h, 2);
;       h += __shfl_xor(h, 1);
;       const float amine = gelu_exact(h * su) * gmine * sv;
;       if ((lane & 7) == 0) {
;         EG[tok * 128 + k + (lane >> 3)] = emine;
;         AG[tok * 128 + k + (lane >> 3)] = amine;
;       }
;     }
	v_pk_mul_f32 v[224:225], v[18:19], v[216:217]
	v_cvt_pk_f32_fp8_e32 v[214:215], v194
	v_cvt_pk_f32_fp8_sdwa v[216:217], v194 src0_sel:WORD_1
	v_pk_fma_f32 v[222:223], v[20:21], v[218:219], v[222:223]
	v_pk_fma_f32 v[224:225], v[22:23], v[220:221], v[224:225]
	v_cvt_pk_f32_fp8_e32 v[218:219], v195
	v_cvt_pk_f32_fp8_sdwa v[220:221], v195 src0_sel:WORD_1
	v_pk_fma_f32 v[222:223], v[24:25], v[214:215], v[222:223]
	v_pk_fma_f32 v[224:225], v[26:27], v[216:217], v[224:225]
	v_pk_fma_f32 v[222:223], v[28:29], v[218:219], v[222:223]
	v_pk_fma_f32 v[224:225], v[30:31], v[220:221], v[224:225]
	v_pk_add_f32 v[222:223], v[222:223], v[224:225]
	s_nop 0
	v_add_f32_e32 v230, v222, v223
	v_cvt_pk_f32_fp8_e32 v[214:215], v196
	v_cvt_pk_f32_fp8_sdwa v[216:217], v196 src0_sel:WORD_1
	v_cvt_pk_f32_fp8_e32 v[218:219], v197
	v_cvt_pk_f32_fp8_sdwa v[220:221], v197 src0_sel:WORD_1
	v_pk_mul_f32 v[222:223], v[16:17], v[214:215]
	v_pk_mul_f32 v[224:225], v[18:19], v[216:217]
	v_cvt_pk_f32_fp8_e32 v[214:215], v198
	v_cvt_pk_f32_fp8_sdwa v[216:217], v198 src0_sel:WORD_1
	v_pk_fma_f32 v[222:223], v[20:21], v[218:219], v[222:223]
	v_pk_fma_f32 v[224:225], v[22:23], v[220:221], v[224:225]
	v_cvt_pk_f32_fp8_e32 v[218:219], v199
	v_cvt_pk_f32_fp8_sdwa v[220:221], v199 src0_sel:WORD_1
	v_pk_fma_f32 v[222:223], v[24:25], v[214:215], v[222:223]
	v_pk_fma_f32 v[224:225], v[26:27], v[216:217], v[224:225]
	v_pk_fma_f32 v[222:223], v[28:29], v[218:219], v[222:223]
	v_pk_fma_f32 v[224:225], v[30:31], v[220:221], v[224:225]
	v_pk_add_f32 v[222:223], v[222:223], v[224:225]
	s_nop 0
	v_add_f32_e32 v231, v222, v223
	v_cvt_pk_f32_fp8_e32 v[214:215], v200
	v_cvt_pk_f32_fp8_sdwa v[216:217], v200 src0_sel:WORD_1
	v_cvt_pk_f32_fp8_e32 v[218:219], v201
	v_cvt_pk_f32_fp8_sdwa v[220:221], v201 src0_sel:WORD_1
	v_pk_mul_f32 v[222:223], v[16:17], v[214:215]
	v_pk_mul_f32 v[224:225], v[18:19], v[216:217]
	v_cvt_pk_f32_fp8_e32 v[214:215], v202
	v_cvt_pk_f32_fp8_sdwa v[216:217], v202 src0_sel:WORD_1
	v_pk_fma_f32 v[222:223], v[20:21], v[218:219], v[222:223]
	v_pk_fma_f32 v[224:225], v[22:23], v[220:221], v[224:225]
	v_cvt_pk_f32_fp8_e32 v[218:219], v203
	v_cvt_pk_f32_fp8_sdwa v[220:221], v203 src0_sel:WORD_1
	v_pk_fma_f32 v[222:223], v[24:25], v[214:215], v[222:223]
	v_pk_fma_f32 v[224:225], v[26:27], v[216:217], v[224:225]
	v_pk_fma_f32 v[222:223], v[28:29], v[218:219], v[222:223]
	v_pk_fma_f32 v[224:225], v[30:31], v[220:221], v[224:225]
	v_pk_add_f32 v[222:223], v[222:223], v[224:225]
	s_nop 0
	v_add_f32_e32 v232, v222, v223
	v_cvt_pk_f32_fp8_e32 v[214:215], v204
	v_cvt_pk_f32_fp8_sdwa v[216:217], v204 src0_sel:WORD_1
	v_cvt_pk_f32_fp8_e32 v[218:219], v205
	v_cvt_pk_f32_fp8_sdwa v[220:221], v205 src0_sel:WORD_1
	v_pk_mul_f32 v[222:223], v[16:17], v[214:215]
	v_pk_mul_f32 v[224:225], v[18:19], v[216:217]
	v_cvt_pk_f32_fp8_e32 v[214:215], v206
	v_cvt_pk_f32_fp8_sdwa v[216:217], v206 src0_sel:WORD_1
	v_pk_fma_f32 v[222:223], v[20:21], v[218:219], v[222:223]
	v_pk_fma_f32 v[224:225], v[22:23], v[220:221], v[224:225]
	v_cvt_pk_f32_fp8_e32 v[218:219], v207
	v_cvt_pk_f32_fp8_sdwa v[220:221], v207 src0_sel:WORD_1
	v_pk_fma_f32 v[222:223], v[24:25], v[214:215], v[222:223]
	v_pk_fma_f32 v[224:225], v[26:27], v[216:217], v[224:225]
	v_pk_fma_f32 v[222:223], v[28:29], v[218:219], v[222:223]
	v_pk_fma_f32 v[224:225], v[30:31], v[220:221], v[224:225]
	v_pk_add_f32 v[222:223], v[222:223], v[224:225]
	s_nop 0
	v_add_f32_e32 v233, v222, v223
	v_permlane32_swap_b32_e32 v226, v230
	v_permlane32_swap_b32_e32 v227, v231
	v_permlane32_swap_b32_e32 v228, v232
	v_permlane32_swap_b32_e32 v229, v233
	v_add_f32_e32 v226, v226, v230
	v_add_f32_e32 v228, v228, v232
	v_add_f32_e32 v227, v227, v231
	v_add_f32_e32 v229, v229, v233
	s_nop 1
	v_permlane16_swap_b32_e32 v226, v228
	v_permlane16_swap_b32_e32 v227, v229
	v_add_f32_e32 v226, v226, v228
	v_add_f32_e32 v227, v227, v229
	s_nop 0
	v_cndmask_b32_e64 v230, v226, v227, s[24:25]
	v_cndmask_b32_e64 v231, v227, v226, s[24:25]
	s_nop 1
	v_add_f32_dpp v232, v231, v230 row_ror:8 row_mask:0xf bank_mask:0xf
	s_nop 1
	v_add_f32_dpp v233, v232, v232 quad_perm:[1,0,3,2] row_mask:0xf bank_mask:0xf
	s_nop 1
	v_add_f32_dpp v232, v233, v233 quad_perm:[2,3,0,1] row_mask:0xf bank_mask:0xf
	s_nop 1
	v_add_f32_dpp v233, v232, v232 row_half_mirror row_mask:0xf bank_mask:0xf
	ds_write_b32 v235, v233 offset:33312
	v_readlane_b32 s48, v135, s72
	v_readlane_b32 s49, v135, s73
	v_readlane_b32 s50, v135, s74
	v_readlane_b32 s51, v135, s75
	v_readlane_b32 s52, v135, s76
	v_readlane_b32 s53, v135, s77
	v_readlane_b32 s54, v135, s78
	v_readlane_b32 s55, v135, s79
	s_add_u32 s32, s0, s48
	s_addc_u32 s33, s1, 0
	s_add_u32 s34, s0, s49
	s_addc_u32 s35, s1, 0
	s_add_u32 s36, s0, s50
	s_addc_u32 s37, s1, 0
	s_add_u32 s38, s0, s51
	s_addc_u32 s39, s1, 0
	s_add_u32 s40, s0, s52
	s_addc_u32 s41, s1, 0
	s_add_u32 s42, s0, s53
	s_addc_u32 s43, s1, 0
	s_add_u32 s44, s0, s54
	s_addc_u32 s45, s1, 0
	s_add_u32 s46, s0, s55
	s_addc_u32 s47, s1, 0
	global_load_dwordx4 v[176:179], v234, s[32:33]
	global_load_dwordx4 v[180:183], v234, s[34:35]
	global_load_dwordx4 v[184:187], v234, s[36:37]
	global_load_dwordx4 v[188:191], v234, s[38:39]
	global_load_dwordx4 v[192:195], v234, s[40:41]
	global_load_dwordx4 v[196:199], v234, s[42:43]
	global_load_dwordx4 v[200:203], v234, s[44:45]
	global_load_dwordx4 v[204:207], v234, s[46:47]
	s_waitcnt vmcnt(8)
; template <bool STORE>
; DI void peer_item(const Params& p, int item, char* smem) {
;     ...
;       for (int u = 0; u < 8; ++u) {
;         int e = e_s[tl * 128 + k + u];
;         uq[u] = *(const u32x4*)(U8 + (size_t)e * 1024 + lane * 16);
;       }
;       float part[8];
; #pragma unroll
;       for (int u = 0; u < 8; ++u) {
;         float d = 0.f;
; #pragma unroll
;         for (int i = 0; i < 4; ++i) {
;           f32x2_t lo = __builtin_amdgcn_cvt_pk_f32_fp8((int)uq[u][i], false);
;           f32x2_t hi = __builtin_amdgcn_cvt_pk_f32_fp8((int)uq[u][i], true);
;           d += xf[4 * i] * lo.x + xf[4 * i + 1] * lo.y + xf[4 * i + 2] * hi.x + xf[4 * i + 3] * hi.y;
;         }
;         part[u] = d;
;       }
	v_cvt_pk_f32_fp8_e32 v[214:215], v144
	v_cvt_pk_f32_fp8_sdwa v[216:217], v144 src0_sel:WORD_1
	v_cvt_pk_f32_fp8_e32 v[218:219], v145
	v_cvt_pk_f32_fp8_sdwa v[220:221], v145 src0_sel:WORD_1
	v_pk_mul_f32 v[222:223], v[32:33], v[214:215]
	v_pk_mul_f32 v[224:225], v[34:35], v[216:217]
	v_cvt_pk_f32_fp8_e32 v[214:215], v146
	v_cvt_pk_f32_fp8_sdwa v[216:217], v146 src0_sel:WORD_1
	v_pk_fma_f32 v[222:223], v[36:37], v[218:219], v[222:223]
	v_pk_fma_f32 v[224:225], v[38:39], v[220:221], v[224:225]
	v_cvt_pk_f32_fp8_e32 v[218:219], v147
	v_cvt_pk_f32_fp8_sdwa v[220:221], v147 src0_sel:WORD_1
	v_pk_fma_f32 v[222:223], v[40:41], v[214:215], v[222:223]
	v_pk_fma_f32 v[224:225], v[42:43], v[216:217], v[224:225]
	v_pk_fma_f32 v[222:223], v[44:45], v[218:219], v[222:223]
	v_pk_fma_f32 v[224:225], v[46:47], v[220:221], v[224:225]
	v_pk_add_f32 v[222:223], v[222:223], v[224:225]
	s_nop 0
	v_add_f32_e32 v226, v222, v223
	v_cvt_pk_f32_fp8_e32 v[214:215], v148
	v_cvt_pk_f32_fp8_sdwa v[216:217], v148 src0_sel:WORD_1
	v_cvt_pk_f32_fp8_e32 v[218:219], v149
	v_cvt_pk_f32_fp8_sdwa v[220:221], v149 src0_sel:WORD_1
	v_pk_mul_f32 v[222:223], v[32:33], v[214:215]
	v_pk_mul_f32 v[224:225], v[34:35], v[216:217]
	v_cvt_pk_f32_fp8_e32 v[214:215], v150
	v_cvt_pk_f32_fp8_sdwa v[216:217], v150 src0_sel:WORD_1
	v_pk_fma_f32 v[222:223], v[36:37], v[218:219], v[222:223]
	v_pk_fma_f32 v[224:225], v[38:39], v[220:221], v[224:225]
	v_cvt_pk_f32_fp8_e32 v[218:219], v151
	v_cvt_pk_f32_fp8_sdwa v[220:221], v151 src0_sel:WORD_1
	v_pk_fma_f32 v[222:223], v[40:41], v[214:215], v[222:223]
	v_pk_fma_f32 v[224:225], v[42:43], v[216:217], v[224:225]
	v_pk_fma_f32 v[222:223], v[44:45], v[218:219], v[222:223]
	v_pk_fma_f32 v[224:225], v[46:47], v[220:221], v[224:225]
	v_pk_add_f32 v[222:223], v[222:223], v[224:225]
	s_nop 0
	v_add_f32_e32 v227, v222, v223
	v_cvt_pk_f32_fp8_e32 v[214:215], v152
	v_cvt_pk_f32_fp8_sdwa v[216:217], v152 src0_sel:WORD_1
	v_cvt_pk_f32_fp8_e32 v[218:219], v153
	v_cvt_pk_f32_fp8_sdwa v[220:221], v153 src0_sel:WORD_1
	v_pk_mul_f32 v[222:223], v[32:33], v[214:215]
	v_pk_mul_f32 v[224:225], v[34:35], v[216:217]
	v_cvt_pk_f32_fp8_e32 v[214:215], v154
	v_cvt_pk_f32_fp8_sdwa v[216:217], v154 src0_sel:WORD_1
	v_pk_fma_f32 v[222:223], v[36:37], v[218:219], v[222:223]
	v_pk_fma_f32 v[224:225], v[38:39], v[220:221], v[224:225]
	v_cvt_pk_f32_fp8_e32 v[218:219], v155
	v_cvt_pk_f32_fp8_sdwa v[220:221], v155 src0_sel:WORD_1
	v_pk_fma_f32 v[222:223], v[40:41], v[214:215], v[222:223]
	v_pk_fma_f32 v[224:225], v[42:43], v[216:217], v[224:225]
	v_pk_fma_f32 v[222:223], v[44:45], v[218:219], v[222:223]
	v_pk_fma_f32 v[224:225], v[46:47], v[220:221], v[224:225]
	v_pk_add_f32 v[222:223], v[222:223], v[224:225]
	s_nop 0
	v_add_f32_e32 v228, v222, v223
	v_cvt_pk_f32_fp8_e32 v[214:215], v156
	v_cvt_pk_f32_fp8_sdwa v[216:217], v156 src0_sel:WORD_1
	v_cvt_pk_f32_fp8_e32 v[218:219], v157
	v_cvt_pk_f32_fp8_sdwa v[220:221], v157 src0_sel:WORD_1
	v_pk_mul_f32 v[222:223], v[32:33], v[214:215]
	v_pk_mul_f32 v[224:225], v[34:35], v[216:217]
	v_cvt_pk_f32_fp8_e32 v[214:215], v158
	v_cvt_pk_f32_fp8_sdwa v[216:217], v158 src0_sel:WORD_1
	v_pk_fma_f32 v[222:223], v[36:37], v[218:219], v[222:223]
	v_pk_fma_f32 v[224:225], v[38:39], v[220:221], v[224:225]
	v_cvt_pk_f32_fp8_e32 v[218:219], v159
	v_cvt_pk_f32_fp8_sdwa v[220:221], v159 src0_sel:WORD_1
	v_pk_fma_f32 v[222:223], v[40:41], v[214:215], v[222:223]
	v_pk_fma_f32 v[224:225], v[42:43], v[216:217], v[224:225]
	v_pk_fma_f32 v[222:223], v[44:45], v[218:219], v[222:223]
	v_pk_fma_f32 v[224:225], v[46:47], v[220:221], v[224:225]
	v_pk_add_f32 v[222:223], v[222:223], v[224:225]
	s_nop 0
	v_add_f32_e32 v229, v222, v223
	v_cvt_pk_f32_fp8_e32 v[214:215], v160
	v_cvt_pk_f32_fp8_sdwa v[216:217], v160 src0_sel:WORD_1
	v_cvt_pk_f32_fp8_e32 v[218:219], v161
	v_cvt_pk_f32_fp8_sdwa v[220:221], v161 src0_sel:WORD_1
	v_pk_mul_f32 v[222:223], v[32:33], v[214:215]
	v_pk_mul_f32 v[224:225], v[34:35], v[216:217]
	v_cvt_pk_f32_fp8_e32 v[214:215], v162
	v_cvt_pk_f32_fp8_sdwa v[216:217], v162 src0_sel:WORD_1
	v_pk_fma_f32 v[222:223], v[36:37], v[218:219], v[222:223]
	v_pk_fma_f32 v[224:225], v[38:39], v[220:221], v[224:225]
	v_cvt_pk_f32_fp8_e32 v[218:219], v163
	v_cvt_pk_f32_fp8_sdwa v[220:221], v163 src0_sel:WORD_1
	v_pk_fma_f32 v[222:223], v[40:41], v[214:215], v[222:223]
	v_pk_fma_f32 v[224:225], v[42:43], v[216:217], v[224:225]
	v_pk_fma_f32 v[222:223], v[44:45], v[218:219], v[222:223]
	v_pk_fma_f32 v[224:225], v[46:47], v[220:221], v[224:225]
	v_pk_add_f32 v[222:223], v[222:223], v[224:225]
	s_nop 0
	v_add_f32_e32 v230, v222, v223
	v_cvt_pk_f32_fp8_e32 v[214:215], v164
	v_cvt_pk_f32_fp8_sdwa v[216:217], v164 src0_sel:WORD_1
	v_cvt_pk_f32_fp8_e32 v[218:219], v165
	v_cvt_pk_f32_fp8_sdwa v[220:221], v165 src0_sel:WORD_1
	v_pk_mul_f32 v[222:223], v[32:33], v[214:215]
	v_pk_mul_f32 v[224:225], v[34:35], v[216:217]
	v_cvt_pk_f32_fp8_e32 v[214:215], v166
	v_cvt_pk_f32_fp8_sdwa v[216:217], v166 src0_sel:WORD_1
	v_pk_fma_f32 v[222:223], v[36:37], v[218:219], v[222:223]
	v_pk_fma_f32 v[224:225], v[38:39], v[220:221], v[224:225]
	v_cvt_pk_f32_fp8_e32 v[218:219], v167
	v_cvt_pk_f32_fp8_sdwa v[220:221], v167 src0_sel:WORD_1
	v_pk_fma_f32 v[222:223], v[40:41], v[214:215], v[222:223]
	v_pk_fma_f32 v[224:225], v[42:43], v[216:217], v[224:225]
	v_pk_fma_f32 v[222:223], v[44:45], v[218:219], v[222:223]
	v_pk_fma_f32 v[224:225], v[46:47], v[220:221], v[224:225]
	v_pk_add_f32 v[222:223], v[222:223], v[224:225]
	s_nop 0
	v_add_f32_e32 v231, v222, v223
	v_cvt_pk_f32_fp8_e32 v[214:215], v168
	v_cvt_pk_f32_fp8_sdwa v[216:217], v168 src0_sel:WORD_1
	v_cvt_pk_f32_fp8_e32 v[218:219], v169
; DI float gelu_exact(float x) { return 0.5f * x * (1.f + erff(x * 0.7071067811865476f)); }
; template <bool STORE>
; DI void peer_item(const Params& p, int item, char* smem) {
;     ...
; #pragma unroll
;       for (int u = 0; u < 8; ++u) {
;         float d = 0.f;
; #pragma unroll
;         for (int i = 0; i < 4; ++i) {
;           f32x2_t lo = __builtin_amdgcn_cvt_pk_f32_fp8((int)uq[u][i], false);
;           f32x2_t hi = __builtin_amdgcn_cvt_pk_f32_fp8((int)uq[u][i], true);
;           d += xf[4 * i] * lo.x + xf[4 * i + 1] * lo.y + xf[4 * i + 2] * hi.x + xf[4 * i + 3] * hi.y;
;         }
;         part[u] = d;
;       }
;       float q4[4], r2[2], h;
; #pragma unroll
;       for (int j = 0; j < 4; ++j) {
;         float mine = b5 ? part[j + 4] : part[j];
;         float other = b5 ? part[j] : part[j + 4];
;         q4[j] = mine + __shfl_xor(other, 32);
;       }
; #pragma unroll
;       for (int j = 0; j < 2; ++j) {
;         float mine = b4 ? q4[j + 2] : q4[j];
;         float other = b4 ? q4[j] : q4[j + 2];
;         r2[j] = mine + __shfl_xor(other, 16);
;       }
;       {
;         float mine = b3 ? r2[1] : r2[0];
;         float other = b3 ? r2[0] : r2[1];
;         h = mine + __shfl_xor(other, 8);
;       }
;       h += __shfl_xor(h, 4);
;       h += __shfl_xor(h, 2);
;       h += __shfl_xor(h, 1);
;       const float amine = gelu_exact(h * su) * gmine * sv;
;       if ((lane & 7) == 0) {
;         EG[tok * 128 + k + (lane >> 3)] = emine;
;         AG[tok * 128 + k + (lane >> 3)] = amine;
;       }
;     }
	v_cvt_pk_f32_fp8_sdwa v[220:221], v169 src0_sel:WORD_1
	v_pk_mul_f32 v[222:223], v[32:33], v[214:215]
	v_pk_mul_f32 v[224:225], v[34:35], v[216:217]
	v_cvt_pk_f32_fp8_e32 v[214:215], v170
	v_cvt_pk_f32_fp8_sdwa v[216:217], v170 src0_sel:WORD_1
	v_pk_fma_f32 v[222:223], v[36:37], v[218:219], v[222:223]
	v_pk_fma_f32 v[224:225], v[38:39], v[220:221], v[224:225]
	v_cvt_pk_f32_fp8_e32 v[218:219], v171
	v_cvt_pk_f32_fp8_sdwa v[220:221], v171 src0_sel:WORD_1
	v_pk_fma_f32 v[222:223], v[40:41], v[214:215], v[222:223]
	v_pk_fma_f32 v[224:225], v[42:43], v[216:217], v[224:225]
	v_pk_fma_f32 v[222:223], v[44:45], v[218:219], v[222:223]
	v_pk_fma_f32 v[224:225], v[46:47], v[220:221], v[224:225]
	v_pk_add_f32 v[222:223], v[222:223], v[224:225]
	s_nop 0
	v_add_f32_e32 v232, v222, v223
	v_cvt_pk_f32_fp8_e32 v[214:215], v172
	v_cvt_pk_f32_fp8_sdwa v[216:217], v172 src0_sel:WORD_1
	v_cvt_pk_f32_fp8_e32 v[218:219], v173
	v_cvt_pk_f32_fp8_sdwa v[220:221], v173 src0_sel:WORD_1
	v_pk_mul_f32 v[222:223], v[32:33], v[214:215]
	v_pk_mul_f32 v[224:225], v[34:35], v[216:217]
	v_cvt_pk_f32_fp8_e32 v[214:215], v174
	v_cvt_pk_f32_fp8_sdwa v[216:217], v174 src0_sel:WORD_1
	v_pk_fma_f32 v[222:223], v[36:37], v[218:219], v[222:223]
	v_pk_fma_f32 v[224:225], v[38:39], v[220:221], v[224:225]
	v_cvt_pk_f32_fp8_e32 v[218:219], v175
	v_cvt_pk_f32_fp8_sdwa v[220:221], v175 src0_sel:WORD_1
	v_pk_fma_f32 v[222:223], v[40:41], v[214:215], v[222:223]
	v_pk_fma_f32 v[224:225], v[42:43], v[216:217], v[224:225]
	v_pk_fma_f32 v[222:223], v[44:45], v[218:219], v[222:223]
	v_pk_fma_f32 v[224:225], v[46:47], v[220:221], v[224:225]
	v_pk_add_f32 v[222:223], v[222:223], v[224:225]
	s_nop 0
	v_add_f32_e32 v233, v222, v223
	v_permlane32_swap_b32_e32 v226, v230
	v_permlane32_swap_b32_e32 v227, v231
	v_permlane32_swap_b32_e32 v228, v232
	v_permlane32_swap_b32_e32 v229, v233
	v_add_f32_e32 v226, v226, v230
	v_add_f32_e32 v228, v228, v232
	v_add_f32_e32 v227, v227, v231
	v_add_f32_e32 v229, v229, v233
	s_nop 1
	v_permlane16_swap_b32_e32 v226, v228
	v_permlane16_swap_b32_e32 v227, v229
	v_add_f32_e32 v226, v226, v228
	v_add_f32_e32 v227, v227, v229
	s_nop 0
	v_cndmask_b32_e64 v230, v226, v227, s[24:25]
	v_cndmask_b32_e64 v231, v227, v226, s[24:25]
	s_nop 1
	v_add_f32_dpp v232, v231, v230 row_ror:8 row_mask:0xf bank_mask:0xf
	s_nop 1
	v_add_f32_dpp v233, v232, v232 quad_perm:[1,0,3,2] row_mask:0xf bank_mask:0xf
	s_nop 1
	v_add_f32_dpp v232, v233, v233 quad_perm:[2,3,0,1] row_mask:0xf bank_mask:0xf
	s_nop 1
	v_add_f32_dpp v233, v232, v232 row_half_mirror row_mask:0xf bank_mask:0xf
	ds_write_b32 v235, v233 offset:33824
	v_readlane_b32 s48, v137, s72
	v_readlane_b32 s49, v137, s73
	v_readlane_b32 s50, v137, s74
	v_readlane_b32 s51, v137, s75
	v_readlane_b32 s52, v137, s76
	v_readlane_b32 s53, v137, s77
	v_readlane_b32 s54, v137, s78
	v_readlane_b32 s55, v137, s79
	s_add_u32 s32, s0, s48
	s_addc_u32 s33, s1, 0
	s_add_u32 s34, s0, s49
	s_addc_u32 s35, s1, 0
	s_add_u32 s36, s0, s50
	s_addc_u32 s37, s1, 0
	s_add_u32 s38, s0, s51
	s_addc_u32 s39, s1, 0
	s_add_u32 s40, s0, s52
	s_addc_u32 s41, s1, 0
	s_add_u32 s42, s0, s53
	s_addc_u32 s43, s1, 0
	s_add_u32 s44, s0, s54
	s_addc_u32 s45, s1, 0
	s_add_u32 s46, s0, s55
	s_addc_u32 s47, s1, 0
	global_load_dwordx4 v[144:147], v234, s[32:33]
	global_load_dwordx4 v[148:151], v234, s[34:35]
	global_load_dwordx4 v[152:155], v234, s[36:37]
	global_load_dwordx4 v[156:159], v234, s[38:39]
	global_load_dwordx4 v[160:163], v234, s[40:41]
	global_load_dwordx4 v[164:167], v234, s[42:43]
	global_load_dwordx4 v[168:171], v234, s[44:45]
	global_load_dwordx4 v[172:175], v234, s[46:47]
	s_waitcnt vmcnt(8)
	v_cvt_pk_f32_fp8_e32 v[214:215], v176
	v_cvt_pk_f32_fp8_sdwa v[216:217], v176 src0_sel:WORD_1
	v_cvt_pk_f32_fp8_e32 v[218:219], v177
	v_cvt_pk_f32_fp8_sdwa v[220:221], v177 src0_sel:WORD_1
	v_pk_mul_f32 v[222:223], v[48:49], v[214:215]
	v_pk_mul_f32 v[224:225], v[50:51], v[216:217]
	v_cvt_pk_f32_fp8_e32 v[214:215], v178
	v_cvt_pk_f32_fp8_sdwa v[216:217], v178 src0_sel:WORD_1
	v_pk_fma_f32 v[222:223], v[52:53], v[218:219], v[222:223]
	v_pk_fma_f32 v[224:225], v[54:55], v[220:221], v[224:225]
	v_cvt_pk_f32_fp8_e32 v[218:219], v179
	v_cvt_pk_f32_fp8_sdwa v[220:221], v179 src0_sel:WORD_1
	v_pk_fma_f32 v[222:223], v[56:57], v[214:215], v[222:223]
	v_pk_fma_f32 v[224:225], v[58:59], v[216:217], v[224:225]
	v_pk_fma_f32 v[222:223], v[60:61], v[218:219], v[222:223]
	v_pk_fma_f32 v[224:225], v[62:63], v[220:221], v[224:225]
	v_pk_add_f32 v[222:223], v[222:223], v[224:225]
	s_nop 0
	v_add_f32_e32 v226, v222, v223
	v_cvt_pk_f32_fp8_e32 v[214:215], v180
	v_cvt_pk_f32_fp8_sdwa v[216:217], v180 src0_sel:WORD_1
	v_cvt_pk_f32_fp8_e32 v[218:219], v181
	v_cvt_pk_f32_fp8_sdwa v[220:221], v181 src0_sel:WORD_1
	v_pk_mul_f32 v[222:223], v[48:49], v[214:215]
	v_pk_mul_f32 v[224:225], v[50:51], v[216:217]
	v_cvt_pk_f32_fp8_e32 v[214:215], v182
	v_cvt_pk_f32_fp8_sdwa v[216:217], v182 src0_sel:WORD_1
	v_pk_fma_f32 v[222:223], v[52:53], v[218:219], v[222:223]
	v_pk_fma_f32 v[224:225], v[54:55], v[220:221], v[224:225]
	v_cvt_pk_f32_fp8_e32 v[218:219], v183
	v_cvt_pk_f32_fp8_sdwa v[220:221], v183 src0_sel:WORD_1
	v_pk_fma_f32 v[222:223], v[56:57], v[214:215], v[222:223]
	v_pk_fma_f32 v[224:225], v[58:59], v[216:217], v[224:225]
	v_pk_fma_f32 v[222:223], v[60:61], v[218:219], v[222:223]
	v_pk_fma_f32 v[224:225], v[62:63], v[220:221], v[224:225]
	v_pk_add_f32 v[222:223], v[222:223], v[224:225]
	s_nop 0
	v_add_f32_e32 v227, v222, v223
	v_cvt_pk_f32_fp8_e32 v[214:215], v184
	v_cvt_pk_f32_fp8_sdwa v[216:217], v184 src0_sel:WORD_1
	v_cvt_pk_f32_fp8_e32 v[218:219], v185
	v_cvt_pk_f32_fp8_sdwa v[220:221], v185 src0_sel:WORD_1
; template <bool STORE>
; DI void peer_item(const Params& p, int item, char* smem) {
;     ...
; #pragma unroll
;       for (int u = 0; u < 8; ++u) {
;         float d = 0.f;
; #pragma unroll
;         for (int i = 0; i < 4; ++i) {
;           f32x2_t lo = __builtin_amdgcn_cvt_pk_f32_fp8((int)uq[u][i], false);
;           f32x2_t hi = __builtin_amdgcn_cvt_pk_f32_fp8((int)uq[u][i], true);
;           d += xf[4 * i] * lo.x + xf[4 * i + 1] * lo.y + xf[4 * i + 2] * hi.x + xf[4 * i + 3] * hi.y;
;         }
;         part[u] = d;
;       }
;       float q4[4], r2[2], h;
; #pragma unroll
;       for (int j = 0; j < 4; ++j) {
;         float mine = b5 ? part[j + 4] : part[j];
;         float other = b5 ? part[j] : part[j + 4];
;         q4[j] = mine + __shfl_xor(other, 32);
	v_pk_mul_f32 v[222:223], v[48:49], v[214:215]
	v_pk_mul_f32 v[224:225], v[50:51], v[216:217]
	v_cvt_pk_f32_fp8_e32 v[214:215], v186
	v_cvt_pk_f32_fp8_sdwa v[216:217], v186 src0_sel:WORD_1
	v_pk_fma_f32 v[222:223], v[52:53], v[218:219], v[222:223]
	v_pk_fma_f32 v[224:225], v[54:55], v[220:221], v[224:225]
	v_cvt_pk_f32_fp8_e32 v[218:219], v187
	v_cvt_pk_f32_fp8_sdwa v[220:221], v187 src0_sel:WORD_1
	v_pk_fma_f32 v[222:223], v[56:57], v[214:215], v[222:223]
	v_pk_fma_f32 v[224:225], v[58:59], v[216:217], v[224:225]
	v_pk_fma_f32 v[222:223], v[60:61], v[218:219], v[222:223]
	v_pk_fma_f32 v[224:225], v[62:63], v[220:221], v[224:225]
	v_pk_add_f32 v[222:223], v[222:223], v[224:225]
	s_nop 0
	v_add_f32_e32 v228, v222, v223
	v_cvt_pk_f32_fp8_e32 v[214:215], v188
	v_cvt_pk_f32_fp8_sdwa v[216:217], v188 src0_sel:WORD_1
	v_cvt_pk_f32_fp8_e32 v[218:219], v189
	v_cvt_pk_f32_fp8_sdwa v[220:221], v189 src0_sel:WORD_1
	v_pk_mul_f32 v[222:223], v[48:49], v[214:215]
	v_pk_mul_f32 v[224:225], v[50:51], v[216:217]
	v_cvt_pk_f32_fp8_e32 v[214:215], v190
	v_cvt_pk_f32_fp8_sdwa v[216:217], v190 src0_sel:WORD_1
	v_pk_fma_f32 v[222:223], v[52:53], v[218:219], v[222:223]
	v_pk_fma_f32 v[224:225], v[54:55], v[220:221], v[224:225]
	v_cvt_pk_f32_fp8_e32 v[218:219], v191
	v_cvt_pk_f32_fp8_sdwa v[220:221], v191 src0_sel:WORD_1
	v_pk_fma_f32 v[222:223], v[56:57], v[214:215], v[222:223]
	v_pk_fma_f32 v[224:225], v[58:59], v[216:217], v[224:225]
	v_pk_fma_f32 v[222:223], v[60:61], v[218:219], v[222:223]
	v_pk_fma_f32 v[224:225], v[62:63], v[220:221], v[224:225]
	v_pk_add_f32 v[222:223], v[222:223], v[224:225]
	s_nop 0
	v_add_f32_e32 v229, v222, v223
	v_cvt_pk_f32_fp8_e32 v[214:215], v192
	v_cvt_pk_f32_fp8_sdwa v[216:217], v192 src0_sel:WORD_1
	v_cvt_pk_f32_fp8_e32 v[218:219], v193
	v_cvt_pk_f32_fp8_sdwa v[220:221], v193 src0_sel:WORD_1
	v_pk_mul_f32 v[222:223], v[48:49], v[214:215]
	v_pk_mul_f32 v[224:225], v[50:51], v[216:217]
	v_cvt_pk_f32_fp8_e32 v[214:215], v194
	v_cvt_pk_f32_fp8_sdwa v[216:217], v194 src0_sel:WORD_1
	v_pk_fma_f32 v[222:223], v[52:53], v[218:219], v[222:223]
	v_pk_fma_f32 v[224:225], v[54:55], v[220:221], v[224:225]
	v_cvt_pk_f32_fp8_e32 v[218:219], v195
	v_cvt_pk_f32_fp8_sdwa v[220:221], v195 src0_sel:WORD_1
	v_pk_fma_f32 v[222:223], v[56:57], v[214:215], v[222:223]
	v_pk_fma_f32 v[224:225], v[58:59], v[216:217], v[224:225]
	v_pk_fma_f32 v[222:223], v[60:61], v[218:219], v[222:223]
	v_pk_fma_f32 v[224:225], v[62:63], v[220:221], v[224:225]
	v_pk_add_f32 v[222:223], v[222:223], v[224:225]
	s_nop 0
	v_add_f32_e32 v230, v222, v223
	v_cvt_pk_f32_fp8_e32 v[214:215], v196
	v_cvt_pk_f32_fp8_sdwa v[216:217], v196 src0_sel:WORD_1
	v_cvt_pk_f32_fp8_e32 v[218:219], v197
	v_cvt_pk_f32_fp8_sdwa v[220:221], v197 src0_sel:WORD_1
	v_pk_mul_f32 v[222:223], v[48:49], v[214:215]
	v_pk_mul_f32 v[224:225], v[50:51], v[216:217]
	v_cvt_pk_f32_fp8_e32 v[214:215], v198
	v_cvt_pk_f32_fp8_sdwa v[216:217], v198 src0_sel:WORD_1
	v_pk_fma_f32 v[222:223], v[52:53], v[218:219], v[222:223]
	v_pk_fma_f32 v[224:225], v[54:55], v[220:221], v[224:225]
	v_cvt_pk_f32_fp8_e32 v[218:219], v199
	v_cvt_pk_f32_fp8_sdwa v[220:221], v199 src0_sel:WORD_1
	v_pk_fma_f32 v[222:223], v[56:57], v[214:215], v[222:223]
	v_pk_fma_f32 v[224:225], v[58:59], v[216:217], v[224:225]
	v_pk_fma_f32 v[222:223], v[60:61], v[218:219], v[222:223]
	v_pk_fma_f32 v[224:225], v[62:63], v[220:221], v[224:225]
	v_pk_add_f32 v[222:223], v[222:223], v[224:225]
	s_nop 0
	v_add_f32_e32 v231, v222, v223
	v_cvt_pk_f32_fp8_e32 v[214:215], v200
	v_cvt_pk_f32_fp8_sdwa v[216:217], v200 src0_sel:WORD_1
	v_cvt_pk_f32_fp8_e32 v[218:219], v201
	v_cvt_pk_f32_fp8_sdwa v[220:221], v201 src0_sel:WORD_1
	v_pk_mul_f32 v[222:223], v[48:49], v[214:215]
	v_pk_mul_f32 v[224:225], v[50:51], v[216:217]
	v_cvt_pk_f32_fp8_e32 v[214:215], v202
	v_cvt_pk_f32_fp8_sdwa v[216:217], v202 src0_sel:WORD_1
	v_pk_fma_f32 v[222:223], v[52:53], v[218:219], v[222:223]
	v_pk_fma_f32 v[224:225], v[54:55], v[220:221], v[224:225]
	v_cvt_pk_f32_fp8_e32 v[218:219], v203
	v_cvt_pk_f32_fp8_sdwa v[220:221], v203 src0_sel:WORD_1
	v_pk_fma_f32 v[222:223], v[56:57], v[214:215], v[222:223]
	v_pk_fma_f32 v[224:225], v[58:59], v[216:217], v[224:225]
	v_pk_fma_f32 v[222:223], v[60:61], v[218:219], v[222:223]
	v_pk_fma_f32 v[224:225], v[62:63], v[220:221], v[224:225]
	v_pk_add_f32 v[222:223], v[222:223], v[224:225]
	s_nop 0
	v_add_f32_e32 v232, v222, v223
	v_cvt_pk_f32_fp8_e32 v[214:215], v204
	v_cvt_pk_f32_fp8_sdwa v[216:217], v204 src0_sel:WORD_1
	v_cvt_pk_f32_fp8_e32 v[218:219], v205
	v_cvt_pk_f32_fp8_sdwa v[220:221], v205 src0_sel:WORD_1
	v_pk_mul_f32 v[222:223], v[48:49], v[214:215]
	v_pk_mul_f32 v[224:225], v[50:51], v[216:217]
	v_cvt_pk_f32_fp8_e32 v[214:215], v206
	v_cvt_pk_f32_fp8_sdwa v[216:217], v206 src0_sel:WORD_1
	v_pk_fma_f32 v[222:223], v[52:53], v[218:219], v[222:223]
	v_pk_fma_f32 v[224:225], v[54:55], v[220:221], v[224:225]
	v_cvt_pk_f32_fp8_e32 v[218:219], v207
	v_cvt_pk_f32_fp8_sdwa v[220:221], v207 src0_sel:WORD_1
	v_pk_fma_f32 v[222:223], v[56:57], v[214:215], v[222:223]
	v_pk_fma_f32 v[224:225], v[58:59], v[216:217], v[224:225]
	v_pk_fma_f32 v[222:223], v[60:61], v[218:219], v[222:223]
	v_pk_fma_f32 v[224:225], v[62:63], v[220:221], v[224:225]
	v_pk_add_f32 v[222:223], v[222:223], v[224:225]
	s_nop 0
	v_add_f32_e32 v233, v222, v223
	v_permlane32_swap_b32_e32 v226, v230
	v_permlane32_swap_b32_e32 v227, v231
	v_permlane32_swap_b32_e32 v228, v232
	v_permlane32_swap_b32_e32 v229, v233
	v_add_f32_e32 v226, v226, v230
	v_add_f32_e32 v228, v228, v232
	v_add_f32_e32 v227, v227, v231
	v_add_f32_e32 v229, v229, v233
	s_nop 1
	v_permlane16_swap_b32_e32 v226, v228
; DI float gelu_exact(float x) { return 0.5f * x * (1.f + erff(x * 0.7071067811865476f)); }
; template <bool STORE>
; DI void peer_item(const Params& p, int item, char* smem) {
;     ...
; #pragma unroll
;       for (int u = 0; u < 8; ++u) {
;         float d = 0.f;
; #pragma unroll
;         for (int i = 0; i < 4; ++i) {
;           f32x2_t lo = __builtin_amdgcn_cvt_pk_f32_fp8((int)uq[u][i], false);
;           f32x2_t hi = __builtin_amdgcn_cvt_pk_f32_fp8((int)uq[u][i], true);
;           d += xf[4 * i] * lo.x + xf[4 * i + 1] * lo.y + xf[4 * i + 2] * hi.x + xf[4 * i + 3] * hi.y;
;         }
;         part[u] = d;
;       }
;       float q4[4], r2[2], h;
; #pragma unroll
;       for (int j = 0; j < 4; ++j) {
;         float mine = b5 ? part[j + 4] : part[j];
;         float other = b5 ? part[j] : part[j + 4];
;         q4[j] = mine + __shfl_xor(other, 32);
;       }
; #pragma unroll
;       for (int j = 0; j < 2; ++j) {
;         float mine = b4 ? q4[j + 2] : q4[j];
;         float other = b4 ? q4[j] : q4[j + 2];
;         r2[j] = mine + __shfl_xor(other, 16);
;       }
;       {
;         float mine = b3 ? r2[1] : r2[0];
;         float other = b3 ? r2[0] : r2[1];
;         h = mine + __shfl_xor(other, 8);
;       }
;       h += __shfl_xor(h, 4);
;       h += __shfl_xor(h, 2);
;       h += __shfl_xor(h, 1);
;       const float amine = gelu_exact(h * su) * gmine * sv;
;       if ((lane & 7) == 0) {
;         EG[tok * 128 + k + (lane >> 3)] = emine;
;         AG[tok * 128 + k + (lane >> 3)] = amine;
;       }
;     }
	v_permlane16_swap_b32_e32 v227, v229
	v_add_f32_e32 v226, v226, v228
	v_add_f32_e32 v227, v227, v229
	s_nop 0
	v_cndmask_b32_e64 v230, v226, v227, s[24:25]
	v_cndmask_b32_e64 v231, v227, v226, s[24:25]
	s_nop 1
	v_add_f32_dpp v232, v231, v230 row_ror:8 row_mask:0xf bank_mask:0xf
	s_nop 1
	v_add_f32_dpp v233, v232, v232 quad_perm:[1,0,3,2] row_mask:0xf bank_mask:0xf
	s_nop 1
	v_add_f32_dpp v232, v233, v233 quad_perm:[2,3,0,1] row_mask:0xf bank_mask:0xf
	s_nop 1
	v_add_f32_dpp v233, v232, v232 row_half_mirror row_mask:0xf bank_mask:0xf
	ds_write_b32 v235, v233 offset:34336
	v_readlane_b32 s48, v139, s72
	v_readlane_b32 s49, v139, s73
	v_readlane_b32 s50, v139, s74
	v_readlane_b32 s51, v139, s75
	v_readlane_b32 s52, v139, s76
	v_readlane_b32 s53, v139, s77
	v_readlane_b32 s54, v139, s78
	v_readlane_b32 s55, v139, s79
	s_add_u32 s32, s0, s48
	s_addc_u32 s33, s1, 0
	s_add_u32 s34, s0, s49
	s_addc_u32 s35, s1, 0
	s_add_u32 s36, s0, s50
	s_addc_u32 s37, s1, 0
	s_add_u32 s38, s0, s51
	s_addc_u32 s39, s1, 0
	s_add_u32 s40, s0, s52
	s_addc_u32 s41, s1, 0
	s_add_u32 s42, s0, s53
	s_addc_u32 s43, s1, 0
	s_add_u32 s44, s0, s54
	s_addc_u32 s45, s1, 0
	s_add_u32 s46, s0, s55
	s_addc_u32 s47, s1, 0
	global_load_dwordx4 v[176:179], v234, s[32:33]
	global_load_dwordx4 v[180:183], v234, s[34:35]
	global_load_dwordx4 v[184:187], v234, s[36:37]
	global_load_dwordx4 v[188:191], v234, s[38:39]
	global_load_dwordx4 v[192:195], v234, s[40:41]
	global_load_dwordx4 v[196:199], v234, s[42:43]
	global_load_dwordx4 v[200:203], v234, s[44:45]
	global_load_dwordx4 v[204:207], v234, s[46:47]
	s_waitcnt vmcnt(8)
	v_cvt_pk_f32_fp8_e32 v[214:215], v144
	v_cvt_pk_f32_fp8_sdwa v[216:217], v144 src0_sel:WORD_1
	v_cvt_pk_f32_fp8_e32 v[218:219], v145
	v_cvt_pk_f32_fp8_sdwa v[220:221], v145 src0_sel:WORD_1
	v_pk_mul_f32 v[222:223], v[64:65], v[214:215]
	v_pk_mul_f32 v[224:225], v[66:67], v[216:217]
	v_cvt_pk_f32_fp8_e32 v[214:215], v146
	v_cvt_pk_f32_fp8_sdwa v[216:217], v146 src0_sel:WORD_1
	v_pk_fma_f32 v[222:223], v[68:69], v[218:219], v[222:223]
	v_pk_fma_f32 v[224:225], v[70:71], v[220:221], v[224:225]
	v_cvt_pk_f32_fp8_e32 v[218:219], v147
	v_cvt_pk_f32_fp8_sdwa v[220:221], v147 src0_sel:WORD_1
	v_pk_fma_f32 v[222:223], v[72:73], v[214:215], v[222:223]
	v_pk_fma_f32 v[224:225], v[74:75], v[216:217], v[224:225]
	v_pk_fma_f32 v[222:223], v[76:77], v[218:219], v[222:223]
	v_pk_fma_f32 v[224:225], v[78:79], v[220:221], v[224:225]
	v_pk_add_f32 v[222:223], v[222:223], v[224:225]
	s_nop 0
	v_add_f32_e32 v226, v222, v223
	v_cvt_pk_f32_fp8_e32 v[214:215], v148
	v_cvt_pk_f32_fp8_sdwa v[216:217], v148 src0_sel:WORD_1
	v_cvt_pk_f32_fp8_e32 v[218:219], v149
	v_cvt_pk_f32_fp8_sdwa v[220:221], v149 src0_sel:WORD_1
	v_pk_mul_f32 v[222:223], v[64:65], v[214:215]
	v_pk_mul_f32 v[224:225], v[66:67], v[216:217]
	v_cvt_pk_f32_fp8_e32 v[214:215], v150
	v_cvt_pk_f32_fp8_sdwa v[216:217], v150 src0_sel:WORD_1
	v_pk_fma_f32 v[222:223], v[68:69], v[218:219], v[222:223]
	v_pk_fma_f32 v[224:225], v[70:71], v[220:221], v[224:225]
	v_cvt_pk_f32_fp8_e32 v[218:219], v151
	v_cvt_pk_f32_fp8_sdwa v[220:221], v151 src0_sel:WORD_1
	v_pk_fma_f32 v[222:223], v[72:73], v[214:215], v[222:223]
	v_pk_fma_f32 v[224:225], v[74:75], v[216:217], v[224:225]
	v_pk_fma_f32 v[222:223], v[76:77], v[218:219], v[222:223]
	v_pk_fma_f32 v[224:225], v[78:79], v[220:221], v[224:225]
	v_pk_add_f32 v[222:223], v[222:223], v[224:225]
	s_nop 0
	v_add_f32_e32 v227, v222, v223
	v_cvt_pk_f32_fp8_e32 v[214:215], v152
	v_cvt_pk_f32_fp8_sdwa v[216:217], v152 src0_sel:WORD_1
	v_cvt_pk_f32_fp8_e32 v[218:219], v153
	v_cvt_pk_f32_fp8_sdwa v[220:221], v153 src0_sel:WORD_1
	v_pk_mul_f32 v[222:223], v[64:65], v[214:215]
	v_pk_mul_f32 v[224:225], v[66:67], v[216:217]
	v_cvt_pk_f32_fp8_e32 v[214:215], v154
	v_cvt_pk_f32_fp8_sdwa v[216:217], v154 src0_sel:WORD_1
	v_pk_fma_f32 v[222:223], v[68:69], v[218:219], v[222:223]
	v_pk_fma_f32 v[224:225], v[70:71], v[220:221], v[224:225]
	v_cvt_pk_f32_fp8_e32 v[218:219], v155
	v_cvt_pk_f32_fp8_sdwa v[220:221], v155 src0_sel:WORD_1
	v_pk_fma_f32 v[222:223], v[72:73], v[214:215], v[222:223]
	v_pk_fma_f32 v[224:225], v[74:75], v[216:217], v[224:225]
	v_pk_fma_f32 v[222:223], v[76:77], v[218:219], v[222:223]
	v_pk_fma_f32 v[224:225], v[78:79], v[220:221], v[224:225]
	v_pk_add_f32 v[222:223], v[222:223], v[224:225]
	s_nop 0
	v_add_f32_e32 v228, v222, v223
	v_cvt_pk_f32_fp8_e32 v[214:215], v156
	v_cvt_pk_f32_fp8_sdwa v[216:217], v156 src0_sel:WORD_1
	v_cvt_pk_f32_fp8_e32 v[218:219], v157
	v_cvt_pk_f32_fp8_sdwa v[220:221], v157 src0_sel:WORD_1
	v_pk_mul_f32 v[222:223], v[64:65], v[214:215]
	v_pk_mul_f32 v[224:225], v[66:67], v[216:217]
	v_cvt_pk_f32_fp8_e32 v[214:215], v158
	v_cvt_pk_f32_fp8_sdwa v[216:217], v158 src0_sel:WORD_1
	v_pk_fma_f32 v[222:223], v[68:69], v[218:219], v[222:223]
	v_pk_fma_f32 v[224:225], v[70:71], v[220:221], v[224:225]
	v_cvt_pk_f32_fp8_e32 v[218:219], v159
	v_cvt_pk_f32_fp8_sdwa v[220:221], v159 src0_sel:WORD_1
	v_pk_fma_f32 v[222:223], v[72:73], v[214:215], v[222:223]
	v_pk_fma_f32 v[224:225], v[74:75], v[216:217], v[224:225]
	v_pk_fma_f32 v[222:223], v[76:77], v[218:219], v[222:223]
	v_pk_fma_f32 v[224:225], v[78:79], v[220:221], v[224:225]
	v_pk_add_f32 v[222:223], v[222:223], v[224:225]
	s_nop 0
	v_add_f32_e32 v229, v222, v223
	v_cvt_pk_f32_fp8_e32 v[214:215], v160
	v_cvt_pk_f32_fp8_sdwa v[216:217], v160 src0_sel:WORD_1
	v_cvt_pk_f32_fp8_e32 v[218:219], v161
	v_cvt_pk_f32_fp8_sdwa v[220:221], v161 src0_sel:WORD_1
	v_pk_mul_f32 v[222:223], v[64:65], v[214:215]
	v_pk_mul_f32 v[224:225], v[66:67], v[216:217]
	v_cvt_pk_f32_fp8_e32 v[214:215], v162
	v_cvt_pk_f32_fp8_sdwa v[216:217], v162 src0_sel:WORD_1
; DI float gelu_exact(float x) { return 0.5f * x * (1.f + erff(x * 0.7071067811865476f)); }
; template <bool STORE>
; DI void peer_item(const Params& p, int item, char* smem) {
;     ...
; #pragma unroll
;       for (int u = 0; u < 8; ++u) {
;         float d = 0.f;
; #pragma unroll
;         for (int i = 0; i < 4; ++i) {
;           f32x2_t lo = __builtin_amdgcn_cvt_pk_f32_fp8((int)uq[u][i], false);
;           f32x2_t hi = __builtin_amdgcn_cvt_pk_f32_fp8((int)uq[u][i], true);
;           d += xf[4 * i] * lo.x + xf[4 * i + 1] * lo.y + xf[4 * i + 2] * hi.x + xf[4 * i + 3] * hi.y;
;         }
;         part[u] = d;
;       }
;       float q4[4], r2[2], h;
; #pragma unroll
;       for (int j = 0; j < 4; ++j) {
;         float mine = b5 ? part[j + 4] : part[j];
;         float other = b5 ? part[j] : part[j + 4];
;         q4[j] = mine + __shfl_xor(other, 32);
;       }
; #pragma unroll
;       for (int j = 0; j < 2; ++j) {
;         float mine = b4 ? q4[j + 2] : q4[j];
;         float other = b4 ? q4[j] : q4[j + 2];
;         r2[j] = mine + __shfl_xor(other, 16);
;       }
;       {
;         float mine = b3 ? r2[1] : r2[0];
;         float other = b3 ? r2[0] : r2[1];
;         h = mine + __shfl_xor(other, 8);
;       }
;       h += __shfl_xor(h, 4);
;       h += __shfl_xor(h, 2);
;       h += __shfl_xor(h, 1);
;       const float amine = gelu_exact(h * su) * gmine * sv;
;       if ((lane & 7) == 0) {
;         EG[tok * 128 + k + (lane >> 3)] = emine;
;         AG[tok * 128 + k + (lane >> 3)] = amine;
;       }
;     }
	v_pk_fma_f32 v[222:223], v[68:69], v[218:219], v[222:223]
	v_pk_fma_f32 v[224:225], v[70:71], v[220:221], v[224:225]
	v_cvt_pk_f32_fp8_e32 v[218:219], v163
	v_cvt_pk_f32_fp8_sdwa v[220:221], v163 src0_sel:WORD_1
	v_pk_fma_f32 v[222:223], v[72:73], v[214:215], v[222:223]
	v_pk_fma_f32 v[224:225], v[74:75], v[216:217], v[224:225]
	v_pk_fma_f32 v[222:223], v[76:77], v[218:219], v[222:223]
	v_pk_fma_f32 v[224:225], v[78:79], v[220:221], v[224:225]
	v_pk_add_f32 v[222:223], v[222:223], v[224:225]
	s_nop 0
	v_add_f32_e32 v230, v222, v223
	v_cvt_pk_f32_fp8_e32 v[214:215], v164
	v_cvt_pk_f32_fp8_sdwa v[216:217], v164 src0_sel:WORD_1
	v_cvt_pk_f32_fp8_e32 v[218:219], v165
	v_cvt_pk_f32_fp8_sdwa v[220:221], v165 src0_sel:WORD_1
	v_pk_mul_f32 v[222:223], v[64:65], v[214:215]
	v_pk_mul_f32 v[224:225], v[66:67], v[216:217]
	v_cvt_pk_f32_fp8_e32 v[214:215], v166
	v_cvt_pk_f32_fp8_sdwa v[216:217], v166 src0_sel:WORD_1
	v_pk_fma_f32 v[222:223], v[68:69], v[218:219], v[222:223]
	v_pk_fma_f32 v[224:225], v[70:71], v[220:221], v[224:225]
	v_cvt_pk_f32_fp8_e32 v[218:219], v167
	v_cvt_pk_f32_fp8_sdwa v[220:221], v167 src0_sel:WORD_1
	v_pk_fma_f32 v[222:223], v[72:73], v[214:215], v[222:223]
	v_pk_fma_f32 v[224:225], v[74:75], v[216:217], v[224:225]
	v_pk_fma_f32 v[222:223], v[76:77], v[218:219], v[222:223]
	v_pk_fma_f32 v[224:225], v[78:79], v[220:221], v[224:225]
	v_pk_add_f32 v[222:223], v[222:223], v[224:225]
	s_nop 0
	v_add_f32_e32 v231, v222, v223
	v_cvt_pk_f32_fp8_e32 v[214:215], v168
	v_cvt_pk_f32_fp8_sdwa v[216:217], v168 src0_sel:WORD_1
	v_cvt_pk_f32_fp8_e32 v[218:219], v169
	v_cvt_pk_f32_fp8_sdwa v[220:221], v169 src0_sel:WORD_1
	v_pk_mul_f32 v[222:223], v[64:65], v[214:215]
	v_pk_mul_f32 v[224:225], v[66:67], v[216:217]
	v_cvt_pk_f32_fp8_e32 v[214:215], v170
	v_cvt_pk_f32_fp8_sdwa v[216:217], v170 src0_sel:WORD_1
	v_pk_fma_f32 v[222:223], v[68:69], v[218:219], v[222:223]
	v_pk_fma_f32 v[224:225], v[70:71], v[220:221], v[224:225]
	v_cvt_pk_f32_fp8_e32 v[218:219], v171
	v_cvt_pk_f32_fp8_sdwa v[220:221], v171 src0_sel:WORD_1
	v_pk_fma_f32 v[222:223], v[72:73], v[214:215], v[222:223]
	v_pk_fma_f32 v[224:225], v[74:75], v[216:217], v[224:225]
	v_pk_fma_f32 v[222:223], v[76:77], v[218:219], v[222:223]
	v_pk_fma_f32 v[224:225], v[78:79], v[220:221], v[224:225]
	v_pk_add_f32 v[222:223], v[222:223], v[224:225]
	s_nop 0
	v_add_f32_e32 v232, v222, v223
	v_cvt_pk_f32_fp8_e32 v[214:215], v172
	v_cvt_pk_f32_fp8_sdwa v[216:217], v172 src0_sel:WORD_1
	v_cvt_pk_f32_fp8_e32 v[218:219], v173
	v_cvt_pk_f32_fp8_sdwa v[220:221], v173 src0_sel:WORD_1
	v_pk_mul_f32 v[222:223], v[64:65], v[214:215]
	v_pk_mul_f32 v[224:225], v[66:67], v[216:217]
	v_cvt_pk_f32_fp8_e32 v[214:215], v174
	v_cvt_pk_f32_fp8_sdwa v[216:217], v174 src0_sel:WORD_1
	v_pk_fma_f32 v[222:223], v[68:69], v[218:219], v[222:223]
	v_pk_fma_f32 v[224:225], v[70:71], v[220:221], v[224:225]
	v_cvt_pk_f32_fp8_e32 v[218:219], v175
	v_cvt_pk_f32_fp8_sdwa v[220:221], v175 src0_sel:WORD_1
	v_pk_fma_f32 v[222:223], v[72:73], v[214:215], v[222:223]
	v_pk_fma_f32 v[224:225], v[74:75], v[216:217], v[224:225]
	v_pk_fma_f32 v[222:223], v[76:77], v[218:219], v[222:223]
	v_pk_fma_f32 v[224:225], v[78:79], v[220:221], v[224:225]
	v_pk_add_f32 v[222:223], v[222:223], v[224:225]
	s_nop 0
	v_add_f32_e32 v233, v222, v223
	v_permlane32_swap_b32_e32 v226, v230
	v_permlane32_swap_b32_e32 v227, v231
	v_permlane32_swap_b32_e32 v228, v232
	v_permlane32_swap_b32_e32 v229, v233
	v_add_f32_e32 v226, v226, v230
	v_add_f32_e32 v228, v228, v232
	v_add_f32_e32 v227, v227, v231
	v_add_f32_e32 v229, v229, v233
	s_nop 1
	v_permlane16_swap_b32_e32 v226, v228
	v_permlane16_swap_b32_e32 v227, v229
	v_add_f32_e32 v226, v226, v228
	v_add_f32_e32 v227, v227, v229
	s_nop 0
	v_cndmask_b32_e64 v230, v226, v227, s[24:25]
	v_cndmask_b32_e64 v231, v227, v226, s[24:25]
	s_nop 1
	v_add_f32_dpp v232, v231, v230 row_ror:8 row_mask:0xf bank_mask:0xf
	s_nop 1
	v_add_f32_dpp v233, v232, v232 quad_perm:[1,0,3,2] row_mask:0xf bank_mask:0xf
	s_nop 1
	v_add_f32_dpp v232, v233, v233 quad_perm:[2,3,0,1] row_mask:0xf bank_mask:0xf
	s_nop 1
	v_add_f32_dpp v233, v232, v232 row_half_mirror row_mask:0xf bank_mask:0xf
	ds_write_b32 v235, v233 offset:34848
	v_readlane_b32 s48, v141, s72
	v_readlane_b32 s49, v141, s73
	v_readlane_b32 s50, v141, s74
	v_readlane_b32 s51, v141, s75
	v_readlane_b32 s52, v141, s76
	v_readlane_b32 s53, v141, s77
	v_readlane_b32 s54, v141, s78
	v_readlane_b32 s55, v141, s79
	s_add_u32 s32, s0, s48
	s_addc_u32 s33, s1, 0
	s_add_u32 s34, s0, s49
	s_addc_u32 s35, s1, 0
	s_add_u32 s36, s0, s50
	s_addc_u32 s37, s1, 0
	s_add_u32 s38, s0, s51
	s_addc_u32 s39, s1, 0
	s_add_u32 s40, s0, s52
	s_addc_u32 s41, s1, 0
	s_add_u32 s42, s0, s53
	s_addc_u32 s43, s1, 0
	s_add_u32 s44, s0, s54
	s_addc_u32 s45, s1, 0
	s_add_u32 s46, s0, s55
	s_addc_u32 s47, s1, 0
	global_load_dwordx4 v[144:147], v234, s[32:33]
	global_load_dwordx4 v[148:151], v234, s[34:35]
	global_load_dwordx4 v[152:155], v234, s[36:37]
	global_load_dwordx4 v[156:159], v234, s[38:39]
	global_load_dwordx4 v[160:163], v234, s[40:41]
	global_load_dwordx4 v[164:167], v234, s[42:43]
	global_load_dwordx4 v[168:171], v234, s[44:45]
	global_load_dwordx4 v[172:175], v234, s[46:47]
	s_waitcnt vmcnt(8)
; template <bool STORE>
; DI void peer_item(const Params& p, int item, char* smem) {
;     ...
;       for (int u = 0; u < 8; ++u) {
;         int e = e_s[tl * 128 + k + u];
;         uq[u] = *(const u32x4*)(U8 + (size_t)e * 1024 + lane * 16);
;       }
;       float part[8];
; #pragma unroll
;       for (int u = 0; u < 8; ++u) {
;         float d = 0.f;
; #pragma unroll
;         for (int i = 0; i < 4; ++i) {
;           f32x2_t lo = __builtin_amdgcn_cvt_pk_f32_fp8((int)uq[u][i], false);
;           f32x2_t hi = __builtin_amdgcn_cvt_pk_f32_fp8((int)uq[u][i], true);
;           d += xf[4 * i] * lo.x + xf[4 * i + 1] * lo.y + xf[4 * i + 2] * hi.x + xf[4 * i + 3] * hi.y;
;         }
;         part[u] = d;
;       }
	v_cvt_pk_f32_fp8_e32 v[214:215], v176
	v_cvt_pk_f32_fp8_sdwa v[216:217], v176 src0_sel:WORD_1
	v_cvt_pk_f32_fp8_e32 v[218:219], v177
	v_cvt_pk_f32_fp8_sdwa v[220:221], v177 src0_sel:WORD_1
	v_pk_mul_f32 v[222:223], v[80:81], v[214:215]
	v_pk_mul_f32 v[224:225], v[82:83], v[216:217]
	v_cvt_pk_f32_fp8_e32 v[214:215], v178
	v_cvt_pk_f32_fp8_sdwa v[216:217], v178 src0_sel:WORD_1
	v_pk_fma_f32 v[222:223], v[84:85], v[218:219], v[222:223]
	v_pk_fma_f32 v[224:225], v[86:87], v[220:221], v[224:225]
	v_cvt_pk_f32_fp8_e32 v[218:219], v179
	v_cvt_pk_f32_fp8_sdwa v[220:221], v179 src0_sel:WORD_1
	v_pk_fma_f32 v[222:223], v[88:89], v[214:215], v[222:223]
	v_pk_fma_f32 v[224:225], v[90:91], v[216:217], v[224:225]
	v_pk_fma_f32 v[222:223], v[92:93], v[218:219], v[222:223]
	v_pk_fma_f32 v[224:225], v[94:95], v[220:221], v[224:225]
	v_pk_add_f32 v[222:223], v[222:223], v[224:225]
	s_nop 0
	v_add_f32_e32 v226, v222, v223
	v_cvt_pk_f32_fp8_e32 v[214:215], v180
	v_cvt_pk_f32_fp8_sdwa v[216:217], v180 src0_sel:WORD_1
	v_cvt_pk_f32_fp8_e32 v[218:219], v181
	v_cvt_pk_f32_fp8_sdwa v[220:221], v181 src0_sel:WORD_1
	v_pk_mul_f32 v[222:223], v[80:81], v[214:215]
	v_pk_mul_f32 v[224:225], v[82:83], v[216:217]
	v_cvt_pk_f32_fp8_e32 v[214:215], v182
	v_cvt_pk_f32_fp8_sdwa v[216:217], v182 src0_sel:WORD_1
	v_pk_fma_f32 v[222:223], v[84:85], v[218:219], v[222:223]
	v_pk_fma_f32 v[224:225], v[86:87], v[220:221], v[224:225]
	v_cvt_pk_f32_fp8_e32 v[218:219], v183
	v_cvt_pk_f32_fp8_sdwa v[220:221], v183 src0_sel:WORD_1
	v_pk_fma_f32 v[222:223], v[88:89], v[214:215], v[222:223]
	v_pk_fma_f32 v[224:225], v[90:91], v[216:217], v[224:225]
	v_pk_fma_f32 v[222:223], v[92:93], v[218:219], v[222:223]
	v_pk_fma_f32 v[224:225], v[94:95], v[220:221], v[224:225]
	v_pk_add_f32 v[222:223], v[222:223], v[224:225]
	s_nop 0
	v_add_f32_e32 v227, v222, v223
	v_cvt_pk_f32_fp8_e32 v[214:215], v184
	v_cvt_pk_f32_fp8_sdwa v[216:217], v184 src0_sel:WORD_1
	v_cvt_pk_f32_fp8_e32 v[218:219], v185
	v_cvt_pk_f32_fp8_sdwa v[220:221], v185 src0_sel:WORD_1
	v_pk_mul_f32 v[222:223], v[80:81], v[214:215]
	v_pk_mul_f32 v[224:225], v[82:83], v[216:217]
	v_cvt_pk_f32_fp8_e32 v[214:215], v186
	v_cvt_pk_f32_fp8_sdwa v[216:217], v186 src0_sel:WORD_1
	v_pk_fma_f32 v[222:223], v[84:85], v[218:219], v[222:223]
	v_pk_fma_f32 v[224:225], v[86:87], v[220:221], v[224:225]
	v_cvt_pk_f32_fp8_e32 v[218:219], v187
	v_cvt_pk_f32_fp8_sdwa v[220:221], v187 src0_sel:WORD_1
	v_pk_fma_f32 v[222:223], v[88:89], v[214:215], v[222:223]
	v_pk_fma_f32 v[224:225], v[90:91], v[216:217], v[224:225]
	v_pk_fma_f32 v[222:223], v[92:93], v[218:219], v[222:223]
	v_pk_fma_f32 v[224:225], v[94:95], v[220:221], v[224:225]
	v_pk_add_f32 v[222:223], v[222:223], v[224:225]
	s_nop 0
	v_add_f32_e32 v228, v222, v223
	v_cvt_pk_f32_fp8_e32 v[214:215], v188
	v_cvt_pk_f32_fp8_sdwa v[216:217], v188 src0_sel:WORD_1
	v_cvt_pk_f32_fp8_e32 v[218:219], v189
	v_cvt_pk_f32_fp8_sdwa v[220:221], v189 src0_sel:WORD_1
	v_pk_mul_f32 v[222:223], v[80:81], v[214:215]
	v_pk_mul_f32 v[224:225], v[82:83], v[216:217]
	v_cvt_pk_f32_fp8_e32 v[214:215], v190
	v_cvt_pk_f32_fp8_sdwa v[216:217], v190 src0_sel:WORD_1
	v_pk_fma_f32 v[222:223], v[84:85], v[218:219], v[222:223]
	v_pk_fma_f32 v[224:225], v[86:87], v[220:221], v[224:225]
	v_cvt_pk_f32_fp8_e32 v[218:219], v191
	v_cvt_pk_f32_fp8_sdwa v[220:221], v191 src0_sel:WORD_1
	v_pk_fma_f32 v[222:223], v[88:89], v[214:215], v[222:223]
	v_pk_fma_f32 v[224:225], v[90:91], v[216:217], v[224:225]
	v_pk_fma_f32 v[222:223], v[92:93], v[218:219], v[222:223]
	v_pk_fma_f32 v[224:225], v[94:95], v[220:221], v[224:225]
	v_pk_add_f32 v[222:223], v[222:223], v[224:225]
	s_nop 0
	v_add_f32_e32 v229, v222, v223
	v_cvt_pk_f32_fp8_e32 v[214:215], v192
	v_cvt_pk_f32_fp8_sdwa v[216:217], v192 src0_sel:WORD_1
	v_cvt_pk_f32_fp8_e32 v[218:219], v193
	v_cvt_pk_f32_fp8_sdwa v[220:221], v193 src0_sel:WORD_1
	v_pk_mul_f32 v[222:223], v[80:81], v[214:215]
	v_pk_mul_f32 v[224:225], v[82:83], v[216:217]
	v_cvt_pk_f32_fp8_e32 v[214:215], v194
	v_cvt_pk_f32_fp8_sdwa v[216:217], v194 src0_sel:WORD_1
	v_pk_fma_f32 v[222:223], v[84:85], v[218:219], v[222:223]
	v_pk_fma_f32 v[224:225], v[86:87], v[220:221], v[224:225]
	v_cvt_pk_f32_fp8_e32 v[218:219], v195
	v_cvt_pk_f32_fp8_sdwa v[220:221], v195 src0_sel:WORD_1
	v_pk_fma_f32 v[222:223], v[88:89], v[214:215], v[222:223]
	v_pk_fma_f32 v[224:225], v[90:91], v[216:217], v[224:225]
	v_pk_fma_f32 v[222:223], v[92:93], v[218:219], v[222:223]
	v_pk_fma_f32 v[224:225], v[94:95], v[220:221], v[224:225]
	v_pk_add_f32 v[222:223], v[222:223], v[224:225]
	s_nop 0
	v_add_f32_e32 v230, v222, v223
	v_cvt_pk_f32_fp8_e32 v[214:215], v196
	v_cvt_pk_f32_fp8_sdwa v[216:217], v196 src0_sel:WORD_1
	v_cvt_pk_f32_fp8_e32 v[218:219], v197
	v_cvt_pk_f32_fp8_sdwa v[220:221], v197 src0_sel:WORD_1
	v_pk_mul_f32 v[222:223], v[80:81], v[214:215]
	v_pk_mul_f32 v[224:225], v[82:83], v[216:217]
	v_cvt_pk_f32_fp8_e32 v[214:215], v198
	v_cvt_pk_f32_fp8_sdwa v[216:217], v198 src0_sel:WORD_1
	v_pk_fma_f32 v[222:223], v[84:85], v[218:219], v[222:223]
	v_pk_fma_f32 v[224:225], v[86:87], v[220:221], v[224:225]
	v_cvt_pk_f32_fp8_e32 v[218:219], v199
	v_cvt_pk_f32_fp8_sdwa v[220:221], v199 src0_sel:WORD_1
	v_pk_fma_f32 v[222:223], v[88:89], v[214:215], v[222:223]
	v_pk_fma_f32 v[224:225], v[90:91], v[216:217], v[224:225]
	v_pk_fma_f32 v[222:223], v[92:93], v[218:219], v[222:223]
	v_pk_fma_f32 v[224:225], v[94:95], v[220:221], v[224:225]
	v_pk_add_f32 v[222:223], v[222:223], v[224:225]
	s_nop 0
	v_add_f32_e32 v231, v222, v223
	v_cvt_pk_f32_fp8_e32 v[214:215], v200
	v_cvt_pk_f32_fp8_sdwa v[216:217], v200 src0_sel:WORD_1
	v_cvt_pk_f32_fp8_e32 v[218:219], v201
; DI float gelu_exact(float x) { return 0.5f * x * (1.f + erff(x * 0.7071067811865476f)); }
; template <bool STORE>
; DI void peer_item(const Params& p, int item, char* smem) {
;     ...
; #pragma unroll
;       for (int u = 0; u < 8; ++u) {
;         float d = 0.f;
; #pragma unroll
;         for (int i = 0; i < 4; ++i) {
;           f32x2_t lo = __builtin_amdgcn_cvt_pk_f32_fp8((int)uq[u][i], false);
;           f32x2_t hi = __builtin_amdgcn_cvt_pk_f32_fp8((int)uq[u][i], true);
;           d += xf[4 * i] * lo.x + xf[4 * i + 1] * lo.y + xf[4 * i + 2] * hi.x + xf[4 * i + 3] * hi.y;
;         }
;         part[u] = d;
;       }
;       float q4[4], r2[2], h;
; #pragma unroll
;       for (int j = 0; j < 4; ++j) {
;         float mine = b5 ? part[j + 4] : part[j];
;         float other = b5 ? part[j] : part[j + 4];
;         q4[j] = mine + __shfl_xor(other, 32);
;       }
; #pragma unroll
;       for (int j = 0; j < 2; ++j) {
;         float mine = b4 ? q4[j + 2] : q4[j];
;         float other = b4 ? q4[j] : q4[j + 2];
;         r2[j] = mine + __shfl_xor(other, 16);
;       }
;       {
;         float mine = b3 ? r2[1] : r2[0];
;         float other = b3 ? r2[0] : r2[1];
;         h = mine + __shfl_xor(other, 8);
;       }
;       h += __shfl_xor(h, 4);
;       h += __shfl_xor(h, 2);
;       h += __shfl_xor(h, 1);
;       const float amine = gelu_exact(h * su) * gmine * sv;
;       if ((lane & 7) == 0) {
;         EG[tok * 128 + k + (lane >> 3)] = emine;
;         AG[tok * 128 + k + (lane >> 3)] = amine;
;       }
;     }
	v_cvt_pk_f32_fp8_sdwa v[220:221], v201 src0_sel:WORD_1
	v_pk_mul_f32 v[222:223], v[80:81], v[214:215]
	v_pk_mul_f32 v[224:225], v[82:83], v[216:217]
	v_cvt_pk_f32_fp8_e32 v[214:215], v202
	v_cvt_pk_f32_fp8_sdwa v[216:217], v202 src0_sel:WORD_1
	v_pk_fma_f32 v[222:223], v[84:85], v[218:219], v[222:223]
	v_pk_fma_f32 v[224:225], v[86:87], v[220:221], v[224:225]
	v_cvt_pk_f32_fp8_e32 v[218:219], v203
	v_cvt_pk_f32_fp8_sdwa v[220:221], v203 src0_sel:WORD_1
	v_pk_fma_f32 v[222:223], v[88:89], v[214:215], v[222:223]
	v_pk_fma_f32 v[224:225], v[90:91], v[216:217], v[224:225]
	v_pk_fma_f32 v[222:223], v[92:93], v[218:219], v[222:223]
	v_pk_fma_f32 v[224:225], v[94:95], v[220:221], v[224:225]
	v_pk_add_f32 v[222:223], v[222:223], v[224:225]
	s_nop 0
	v_add_f32_e32 v232, v222, v223
	v_cvt_pk_f32_fp8_e32 v[214:215], v204
	v_cvt_pk_f32_fp8_sdwa v[216:217], v204 src0_sel:WORD_1
	v_cvt_pk_f32_fp8_e32 v[218:219], v205
	v_cvt_pk_f32_fp8_sdwa v[220:221], v205 src0_sel:WORD_1
	v_pk_mul_f32 v[222:223], v[80:81], v[214:215]
	v_pk_mul_f32 v[224:225], v[82:83], v[216:217]
	v_cvt_pk_f32_fp8_e32 v[214:215], v206
	v_cvt_pk_f32_fp8_sdwa v[216:217], v206 src0_sel:WORD_1
	v_pk_fma_f32 v[222:223], v[84:85], v[218:219], v[222:223]
	v_pk_fma_f32 v[224:225], v[86:87], v[220:221], v[224:225]
	v_cvt_pk_f32_fp8_e32 v[218:219], v207
	v_cvt_pk_f32_fp8_sdwa v[220:221], v207 src0_sel:WORD_1
	v_pk_fma_f32 v[222:223], v[88:89], v[214:215], v[222:223]
	v_pk_fma_f32 v[224:225], v[90:91], v[216:217], v[224:225]
	v_pk_fma_f32 v[222:223], v[92:93], v[218:219], v[222:223]
	v_pk_fma_f32 v[224:225], v[94:95], v[220:221], v[224:225]
	v_pk_add_f32 v[222:223], v[222:223], v[224:225]
	s_nop 0
	v_add_f32_e32 v233, v222, v223
	v_permlane32_swap_b32_e32 v226, v230
	v_permlane32_swap_b32_e32 v227, v231
	v_permlane32_swap_b32_e32 v228, v232
	v_permlane32_swap_b32_e32 v229, v233
	v_add_f32_e32 v226, v226, v230
	v_add_f32_e32 v228, v228, v232
	v_add_f32_e32 v227, v227, v231
	v_add_f32_e32 v229, v229, v233
	s_nop 1
	v_permlane16_swap_b32_e32 v226, v228
	v_permlane16_swap_b32_e32 v227, v229
	v_add_f32_e32 v226, v226, v228
	v_add_f32_e32 v227, v227, v229
	s_nop 0
	v_cndmask_b32_e64 v230, v226, v227, s[24:25]
	v_cndmask_b32_e64 v231, v227, v226, s[24:25]
	s_nop 1
	v_add_f32_dpp v232, v231, v230 row_ror:8 row_mask:0xf bank_mask:0xf
	s_nop 1
	v_add_f32_dpp v233, v232, v232 quad_perm:[1,0,3,2] row_mask:0xf bank_mask:0xf
	s_nop 1
	v_add_f32_dpp v232, v233, v233 quad_perm:[2,3,0,1] row_mask:0xf bank_mask:0xf
	s_nop 1
	v_add_f32_dpp v233, v232, v232 row_half_mirror row_mask:0xf bank_mask:0xf
	ds_write_b32 v235, v233 offset:35360
	v_readlane_b32 s48, v143, s72
	v_readlane_b32 s49, v143, s73
	v_readlane_b32 s50, v143, s74
	v_readlane_b32 s51, v143, s75
	v_readlane_b32 s52, v143, s76
	v_readlane_b32 s53, v143, s77
	v_readlane_b32 s54, v143, s78
	v_readlane_b32 s55, v143, s79
	s_add_u32 s32, s0, s48
	s_addc_u32 s33, s1, 0
	s_add_u32 s34, s0, s49
	s_addc_u32 s35, s1, 0
	s_add_u32 s36, s0, s50
	s_addc_u32 s37, s1, 0
	s_add_u32 s38, s0, s51
	s_addc_u32 s39, s1, 0
	s_add_u32 s40, s0, s52
	s_addc_u32 s41, s1, 0
	s_add_u32 s42, s0, s53
	s_addc_u32 s43, s1, 0
	s_add_u32 s44, s0, s54
	s_addc_u32 s45, s1, 0
	s_add_u32 s46, s0, s55
	s_addc_u32 s47, s1, 0
	global_load_dwordx4 v[176:179], v234, s[32:33]
	global_load_dwordx4 v[180:183], v234, s[34:35]
	global_load_dwordx4 v[184:187], v234, s[36:37]
	global_load_dwordx4 v[188:191], v234, s[38:39]
	global_load_dwordx4 v[192:195], v234, s[40:41]
	global_load_dwordx4 v[196:199], v234, s[42:43]
	global_load_dwordx4 v[200:203], v234, s[44:45]
	global_load_dwordx4 v[204:207], v234, s[46:47]
	s_waitcnt vmcnt(8)
	v_cvt_pk_f32_fp8_e32 v[214:215], v144
	v_cvt_pk_f32_fp8_sdwa v[216:217], v144 src0_sel:WORD_1
	v_cvt_pk_f32_fp8_e32 v[218:219], v145
	v_cvt_pk_f32_fp8_sdwa v[220:221], v145 src0_sel:WORD_1
	v_pk_mul_f32 v[222:223], v[96:97], v[214:215]
	v_pk_mul_f32 v[224:225], v[98:99], v[216:217]
	v_cvt_pk_f32_fp8_e32 v[214:215], v146
	v_cvt_pk_f32_fp8_sdwa v[216:217], v146 src0_sel:WORD_1
	v_pk_fma_f32 v[222:223], v[100:101], v[218:219], v[222:223]
	v_pk_fma_f32 v[224:225], v[102:103], v[220:221], v[224:225]
	v_cvt_pk_f32_fp8_e32 v[218:219], v147
	v_cvt_pk_f32_fp8_sdwa v[220:221], v147 src0_sel:WORD_1
	v_pk_fma_f32 v[222:223], v[104:105], v[214:215], v[222:223]
	v_pk_fma_f32 v[224:225], v[106:107], v[216:217], v[224:225]
	v_pk_fma_f32 v[222:223], v[108:109], v[218:219], v[222:223]
	v_pk_fma_f32 v[224:225], v[110:111], v[220:221], v[224:225]
	v_pk_add_f32 v[222:223], v[222:223], v[224:225]
	s_nop 0
	v_add_f32_e32 v226, v222, v223
	v_cvt_pk_f32_fp8_e32 v[214:215], v148
	v_cvt_pk_f32_fp8_sdwa v[216:217], v148 src0_sel:WORD_1
	v_cvt_pk_f32_fp8_e32 v[218:219], v149
	v_cvt_pk_f32_fp8_sdwa v[220:221], v149 src0_sel:WORD_1
	v_pk_mul_f32 v[222:223], v[96:97], v[214:215]
	v_pk_mul_f32 v[224:225], v[98:99], v[216:217]
	v_cvt_pk_f32_fp8_e32 v[214:215], v150
	v_cvt_pk_f32_fp8_sdwa v[216:217], v150 src0_sel:WORD_1
	v_pk_fma_f32 v[222:223], v[100:101], v[218:219], v[222:223]
	v_pk_fma_f32 v[224:225], v[102:103], v[220:221], v[224:225]
	v_cvt_pk_f32_fp8_e32 v[218:219], v151
	v_cvt_pk_f32_fp8_sdwa v[220:221], v151 src0_sel:WORD_1
	v_pk_fma_f32 v[222:223], v[104:105], v[214:215], v[222:223]
	v_pk_fma_f32 v[224:225], v[106:107], v[216:217], v[224:225]
	v_pk_fma_f32 v[222:223], v[108:109], v[218:219], v[222:223]
	v_pk_fma_f32 v[224:225], v[110:111], v[220:221], v[224:225]
	v_pk_add_f32 v[222:223], v[222:223], v[224:225]
	s_nop 0
	v_add_f32_e32 v227, v222, v223
	v_cvt_pk_f32_fp8_e32 v[214:215], v152
	v_cvt_pk_f32_fp8_sdwa v[216:217], v152 src0_sel:WORD_1
	v_cvt_pk_f32_fp8_e32 v[218:219], v153
; template <bool STORE>
; DI void peer_item(const Params& p, int item, char* smem) {
;     ...
; #pragma unroll
;       for (int u = 0; u < 8; ++u) {
;         float d = 0.f;
; #pragma unroll
;         for (int i = 0; i < 4; ++i) {
;           f32x2_t lo = __builtin_amdgcn_cvt_pk_f32_fp8((int)uq[u][i], false);
;           f32x2_t hi = __builtin_amdgcn_cvt_pk_f32_fp8((int)uq[u][i], true);
;           d += xf[4 * i] * lo.x + xf[4 * i + 1] * lo.y + xf[4 * i + 2] * hi.x + xf[4 * i + 3] * hi.y;
;         }
;         part[u] = d;
;       }
;       float q4[4], r2[2], h;
; #pragma unroll
;       for (int j = 0; j < 4; ++j) {
;         float mine = b5 ? part[j + 4] : part[j];
;         float other = b5 ? part[j] : part[j + 4];
;         q4[j] = mine + __shfl_xor(other, 32);
	v_cvt_pk_f32_fp8_sdwa v[220:221], v153 src0_sel:WORD_1
	v_pk_mul_f32 v[222:223], v[96:97], v[214:215]
	v_pk_mul_f32 v[224:225], v[98:99], v[216:217]
	v_cvt_pk_f32_fp8_e32 v[214:215], v154
	v_cvt_pk_f32_fp8_sdwa v[216:217], v154 src0_sel:WORD_1
	v_pk_fma_f32 v[222:223], v[100:101], v[218:219], v[222:223]
	v_pk_fma_f32 v[224:225], v[102:103], v[220:221], v[224:225]
	v_cvt_pk_f32_fp8_e32 v[218:219], v155
	v_cvt_pk_f32_fp8_sdwa v[220:221], v155 src0_sel:WORD_1
	v_pk_fma_f32 v[222:223], v[104:105], v[214:215], v[222:223]
	v_pk_fma_f32 v[224:225], v[106:107], v[216:217], v[224:225]
	v_pk_fma_f32 v[222:223], v[108:109], v[218:219], v[222:223]
	v_pk_fma_f32 v[224:225], v[110:111], v[220:221], v[224:225]
	v_pk_add_f32 v[222:223], v[222:223], v[224:225]
	s_nop 0
	v_add_f32_e32 v228, v222, v223
	v_cvt_pk_f32_fp8_e32 v[214:215], v156
	v_cvt_pk_f32_fp8_sdwa v[216:217], v156 src0_sel:WORD_1
	v_cvt_pk_f32_fp8_e32 v[218:219], v157
	v_cvt_pk_f32_fp8_sdwa v[220:221], v157 src0_sel:WORD_1
	v_pk_mul_f32 v[222:223], v[96:97], v[214:215]
	v_pk_mul_f32 v[224:225], v[98:99], v[216:217]
	v_cvt_pk_f32_fp8_e32 v[214:215], v158
	v_cvt_pk_f32_fp8_sdwa v[216:217], v158 src0_sel:WORD_1
	v_pk_fma_f32 v[222:223], v[100:101], v[218:219], v[222:223]
	v_pk_fma_f32 v[224:225], v[102:103], v[220:221], v[224:225]
	v_cvt_pk_f32_fp8_e32 v[218:219], v159
	v_cvt_pk_f32_fp8_sdwa v[220:221], v159 src0_sel:WORD_1
	v_pk_fma_f32 v[222:223], v[104:105], v[214:215], v[222:223]
	v_pk_fma_f32 v[224:225], v[106:107], v[216:217], v[224:225]
	v_pk_fma_f32 v[222:223], v[108:109], v[218:219], v[222:223]
	v_pk_fma_f32 v[224:225], v[110:111], v[220:221], v[224:225]
	v_pk_add_f32 v[222:223], v[222:223], v[224:225]
	s_nop 0
	v_add_f32_e32 v229, v222, v223
	v_cvt_pk_f32_fp8_e32 v[214:215], v160
	v_cvt_pk_f32_fp8_sdwa v[216:217], v160 src0_sel:WORD_1
	v_cvt_pk_f32_fp8_e32 v[218:219], v161
	v_cvt_pk_f32_fp8_sdwa v[220:221], v161 src0_sel:WORD_1
	v_pk_mul_f32 v[222:223], v[96:97], v[214:215]
	v_pk_mul_f32 v[224:225], v[98:99], v[216:217]
	v_cvt_pk_f32_fp8_e32 v[214:215], v162
	v_cvt_pk_f32_fp8_sdwa v[216:217], v162 src0_sel:WORD_1
	v_pk_fma_f32 v[222:223], v[100:101], v[218:219], v[222:223]
	v_pk_fma_f32 v[224:225], v[102:103], v[220:221], v[224:225]
	v_cvt_pk_f32_fp8_e32 v[218:219], v163
	v_cvt_pk_f32_fp8_sdwa v[220:221], v163 src0_sel:WORD_1
	v_pk_fma_f32 v[222:223], v[104:105], v[214:215], v[222:223]
	v_pk_fma_f32 v[224:225], v[106:107], v[216:217], v[224:225]
	v_pk_fma_f32 v[222:223], v[108:109], v[218:219], v[222:223]
	v_pk_fma_f32 v[224:225], v[110:111], v[220:221], v[224:225]
	v_pk_add_f32 v[222:223], v[222:223], v[224:225]
	s_nop 0
	v_add_f32_e32 v230, v222, v223
	v_cvt_pk_f32_fp8_e32 v[214:215], v164
	v_cvt_pk_f32_fp8_sdwa v[216:217], v164 src0_sel:WORD_1
	v_cvt_pk_f32_fp8_e32 v[218:219], v165
	v_cvt_pk_f32_fp8_sdwa v[220:221], v165 src0_sel:WORD_1
	v_pk_mul_f32 v[222:223], v[96:97], v[214:215]
	v_pk_mul_f32 v[224:225], v[98:99], v[216:217]
	v_cvt_pk_f32_fp8_e32 v[214:215], v166
	v_cvt_pk_f32_fp8_sdwa v[216:217], v166 src0_sel:WORD_1
	v_pk_fma_f32 v[222:223], v[100:101], v[218:219], v[222:223]
	v_pk_fma_f32 v[224:225], v[102:103], v[220:221], v[224:225]
	v_cvt_pk_f32_fp8_e32 v[218:219], v167
	v_cvt_pk_f32_fp8_sdwa v[220:221], v167 src0_sel:WORD_1
	v_pk_fma_f32 v[222:223], v[104:105], v[214:215], v[222:223]
	v_pk_fma_f32 v[224:225], v[106:107], v[216:217], v[224:225]
	v_pk_fma_f32 v[222:223], v[108:109], v[218:219], v[222:223]
	v_pk_fma_f32 v[224:225], v[110:111], v[220:221], v[224:225]
	v_pk_add_f32 v[222:223], v[222:223], v[224:225]
	s_nop 0
	v_add_f32_e32 v231, v222, v223
	v_cvt_pk_f32_fp8_e32 v[214:215], v168
	v_cvt_pk_f32_fp8_sdwa v[216:217], v168 src0_sel:WORD_1
	v_cvt_pk_f32_fp8_e32 v[218:219], v169
	v_cvt_pk_f32_fp8_sdwa v[220:221], v169 src0_sel:WORD_1
	v_pk_mul_f32 v[222:223], v[96:97], v[214:215]
	v_pk_mul_f32 v[224:225], v[98:99], v[216:217]
	v_cvt_pk_f32_fp8_e32 v[214:215], v170
	v_cvt_pk_f32_fp8_sdwa v[216:217], v170 src0_sel:WORD_1
	v_pk_fma_f32 v[222:223], v[100:101], v[218:219], v[222:223]
	v_pk_fma_f32 v[224:225], v[102:103], v[220:221], v[224:225]
	v_cvt_pk_f32_fp8_e32 v[218:219], v171
	v_cvt_pk_f32_fp8_sdwa v[220:221], v171 src0_sel:WORD_1
	v_pk_fma_f32 v[222:223], v[104:105], v[214:215], v[222:223]
	v_pk_fma_f32 v[224:225], v[106:107], v[216:217], v[224:225]
	v_pk_fma_f32 v[222:223], v[108:109], v[218:219], v[222:223]
	v_pk_fma_f32 v[224:225], v[110:111], v[220:221], v[224:225]
	v_pk_add_f32 v[222:223], v[222:223], v[224:225]
	s_nop 0
	v_add_f32_e32 v232, v222, v223
	v_cvt_pk_f32_fp8_e32 v[214:215], v172
	v_cvt_pk_f32_fp8_sdwa v[216:217], v172 src0_sel:WORD_1
	v_cvt_pk_f32_fp8_e32 v[218:219], v173
	v_cvt_pk_f32_fp8_sdwa v[220:221], v173 src0_sel:WORD_1
	v_pk_mul_f32 v[222:223], v[96:97], v[214:215]
	v_pk_mul_f32 v[224:225], v[98:99], v[216:217]
	v_cvt_pk_f32_fp8_e32 v[214:215], v174
	v_cvt_pk_f32_fp8_sdwa v[216:217], v174 src0_sel:WORD_1
	v_pk_fma_f32 v[222:223], v[100:101], v[218:219], v[222:223]
	v_pk_fma_f32 v[224:225], v[102:103], v[220:221], v[224:225]
	v_cvt_pk_f32_fp8_e32 v[218:219], v175
	v_cvt_pk_f32_fp8_sdwa v[220:221], v175 src0_sel:WORD_1
	v_pk_fma_f32 v[222:223], v[104:105], v[214:215], v[222:223]
	v_pk_fma_f32 v[224:225], v[106:107], v[216:217], v[224:225]
	v_pk_fma_f32 v[222:223], v[108:109], v[218:219], v[222:223]
	v_pk_fma_f32 v[224:225], v[110:111], v[220:221], v[224:225]
	v_pk_add_f32 v[222:223], v[222:223], v[224:225]
	s_nop 0
	v_add_f32_e32 v233, v222, v223
	v_permlane32_swap_b32_e32 v226, v230
	v_permlane32_swap_b32_e32 v227, v231
	v_permlane32_swap_b32_e32 v228, v232
	v_permlane32_swap_b32_e32 v229, v233
	v_add_f32_e32 v226, v226, v230
; DI float gelu_exact(float x) { return 0.5f * x * (1.f + erff(x * 0.7071067811865476f)); }
; template <bool STORE>
; DI void peer_item(const Params& p, int item, char* smem) {
;     ...
;     for (int k = 0; k < 128; k += 8) {
;       u32x4 uq[8];
;       const int emine = e_s[tl * 128 + k + (lane >> 3)];
;       const float gmine = g_s[tl * 128 + k + (lane >> 3)];
;       const float su = SU[emine], sv = SV[emine];
; #pragma unroll
;       for (int u = 0; u < 8; ++u) {
;         int e = e_s[tl * 128 + k + u];
;         uq[u] = *(const u32x4*)(U8 + (size_t)e * 1024 + lane * 16);
;       }
;       float part[8];
; #pragma unroll
;       for (int u = 0; u < 8; ++u) {
;         float d = 0.f;
; #pragma unroll
;         for (int i = 0; i < 4; ++i) {
;           f32x2_t lo = __builtin_amdgcn_cvt_pk_f32_fp8((int)uq[u][i], false);
;           f32x2_t hi = __builtin_amdgcn_cvt_pk_f32_fp8((int)uq[u][i], true);
;           d += xf[4 * i] * lo.x + xf[4 * i + 1] * lo.y + xf[4 * i + 2] * hi.x + xf[4 * i + 3] * hi.y;
;         }
;         part[u] = d;
;       }
;       float q4[4], r2[2], h;
; #pragma unroll
;       for (int j = 0; j < 4; ++j) {
;         float mine = b5 ? part[j + 4] : part[j];
;         float other = b5 ? part[j] : part[j + 4];
;         q4[j] = mine + __shfl_xor(other, 32);
;       }
; #pragma unroll
;       for (int j = 0; j < 2; ++j) {
;         float mine = b4 ? q4[j + 2] : q4[j];
;         float other = b4 ? q4[j] : q4[j + 2];
;         r2[j] = mine + __shfl_xor(other, 16);
;       }
;       {
;         float mine = b3 ? r2[1] : r2[0];
;         float other = b3 ? r2[0] : r2[1];
;         h = mine + __shfl_xor(other, 8);
;       }
;       h += __shfl_xor(h, 4);
;       h += __shfl_xor(h, 2);
;       h += __shfl_xor(h, 1);
;       const float amine = gelu_exact(h * su) * gmine * sv;
;       if ((lane & 7) == 0) {
;         EG[tok * 128 + k + (lane >> 3)] = emine;
;         AG[tok * 128 + k + (lane >> 3)] = amine;
;       }
;     }
	v_add_f32_e32 v228, v228, v232
	v_add_f32_e32 v227, v227, v231
	v_add_f32_e32 v229, v229, v233
	s_nop 1
	v_permlane16_swap_b32_e32 v226, v228
	v_permlane16_swap_b32_e32 v227, v229
	v_add_f32_e32 v226, v226, v228
	v_add_f32_e32 v227, v227, v229
	s_nop 0
	v_cndmask_b32_e64 v230, v226, v227, s[24:25]
	v_cndmask_b32_e64 v231, v227, v226, s[24:25]
	s_nop 1
	v_add_f32_dpp v232, v231, v230 row_ror:8 row_mask:0xf bank_mask:0xf
	s_nop 1
	v_add_f32_dpp v233, v232, v232 quad_perm:[1,0,3,2] row_mask:0xf bank_mask:0xf
	s_nop 1
	v_add_f32_dpp v232, v233, v233 quad_perm:[2,3,0,1] row_mask:0xf bank_mask:0xf
	s_nop 1
	v_add_f32_dpp v233, v232, v232 row_half_mirror row_mask:0xf bank_mask:0xf
	ds_write_b32 v235, v233 offset:35872
	s_add_u32 s72, s72, 8
	s_add_u32 s73, s73, 8
	s_add_u32 s74, s74, 8
	s_add_u32 s75, s75, 8
	s_add_u32 s76, s76, 8
	s_add_u32 s77, s77, 8
	s_add_u32 s78, s78, 8
	s_add_u32 s79, s79, 8
	s_and_b32 s72, s72, 63
	s_and_b32 s73, s73, 63
	s_and_b32 s74, s74, 63
	s_and_b32 s75, s75, 63
	s_and_b32 s76, s76, 63
	s_and_b32 s77, s77, 63
	s_and_b32 s78, s78, 63
	s_and_b32 s79, s79, 63
	v_readlane_b32 s48, v128, s72
	v_readlane_b32 s49, v128, s73
	v_readlane_b32 s50, v128, s74
	v_readlane_b32 s51, v128, s75
	v_readlane_b32 s52, v128, s76
	v_readlane_b32 s53, v128, s77
	v_readlane_b32 s54, v128, s78
	v_readlane_b32 s55, v128, s79
	s_add_u32 s32, s0, s48
	s_addc_u32 s33, s1, 0
	s_add_u32 s34, s0, s49
	s_addc_u32 s35, s1, 0
	s_add_u32 s36, s0, s50
	s_addc_u32 s37, s1, 0
	s_add_u32 s38, s0, s51
	s_addc_u32 s39, s1, 0
	s_add_u32 s40, s0, s52
	s_addc_u32 s41, s1, 0
	s_add_u32 s42, s0, s53
	s_addc_u32 s43, s1, 0
	s_add_u32 s44, s0, s54
	s_addc_u32 s45, s1, 0
	s_add_u32 s46, s0, s55
	s_addc_u32 s47, s1, 0
	global_load_dwordx4 v[144:147], v234, s[32:33]
	global_load_dwordx4 v[148:151], v234, s[34:35]
	global_load_dwordx4 v[152:155], v234, s[36:37]
	global_load_dwordx4 v[156:159], v234, s[38:39]
	global_load_dwordx4 v[160:163], v234, s[40:41]
	global_load_dwordx4 v[164:167], v234, s[42:43]
	global_load_dwordx4 v[168:171], v234, s[44:45]
	global_load_dwordx4 v[172:175], v234, s[46:47]
	s_waitcnt vmcnt(8)
	v_cvt_pk_f32_fp8_e32 v[214:215], v176
	v_cvt_pk_f32_fp8_sdwa v[216:217], v176 src0_sel:WORD_1
	v_cvt_pk_f32_fp8_e32 v[218:219], v177
	v_cvt_pk_f32_fp8_sdwa v[220:221], v177 src0_sel:WORD_1
	v_pk_mul_f32 v[222:223], v[112:113], v[214:215]
	v_pk_mul_f32 v[224:225], v[114:115], v[216:217]
	v_cvt_pk_f32_fp8_e32 v[214:215], v178
	v_cvt_pk_f32_fp8_sdwa v[216:217], v178 src0_sel:WORD_1
	v_pk_fma_f32 v[222:223], v[116:117], v[218:219], v[222:223]
	v_pk_fma_f32 v[224:225], v[118:119], v[220:221], v[224:225]
	v_cvt_pk_f32_fp8_e32 v[218:219], v179
	v_cvt_pk_f32_fp8_sdwa v[220:221], v179 src0_sel:WORD_1
	v_pk_fma_f32 v[222:223], v[120:121], v[214:215], v[222:223]
	v_pk_fma_f32 v[224:225], v[122:123], v[216:217], v[224:225]
	v_pk_fma_f32 v[222:223], v[124:125], v[218:219], v[222:223]
	v_pk_fma_f32 v[224:225], v[126:127], v[220:221], v[224:225]
	v_pk_add_f32 v[222:223], v[222:223], v[224:225]
	s_nop 0
	v_add_f32_e32 v226, v222, v223
	v_cvt_pk_f32_fp8_e32 v[214:215], v180
	v_cvt_pk_f32_fp8_sdwa v[216:217], v180 src0_sel:WORD_1
	v_cvt_pk_f32_fp8_e32 v[218:219], v181
	v_cvt_pk_f32_fp8_sdwa v[220:221], v181 src0_sel:WORD_1
	v_pk_mul_f32 v[222:223], v[112:113], v[214:215]
	v_pk_mul_f32 v[224:225], v[114:115], v[216:217]
	v_cvt_pk_f32_fp8_e32 v[214:215], v182
	v_cvt_pk_f32_fp8_sdwa v[216:217], v182 src0_sel:WORD_1
	v_pk_fma_f32 v[222:223], v[116:117], v[218:219], v[222:223]
	v_pk_fma_f32 v[224:225], v[118:119], v[220:221], v[224:225]
	v_cvt_pk_f32_fp8_e32 v[218:219], v183
	v_cvt_pk_f32_fp8_sdwa v[220:221], v183 src0_sel:WORD_1
	v_pk_fma_f32 v[222:223], v[120:121], v[214:215], v[222:223]
	v_pk_fma_f32 v[224:225], v[122:123], v[216:217], v[224:225]
	v_pk_fma_f32 v[222:223], v[124:125], v[218:219], v[222:223]
	v_pk_fma_f32 v[224:225], v[126:127], v[220:221], v[224:225]
	v_pk_add_f32 v[222:223], v[222:223], v[224:225]
	s_nop 0
	v_add_f32_e32 v227, v222, v223
	v_cvt_pk_f32_fp8_e32 v[214:215], v184
	v_cvt_pk_f32_fp8_sdwa v[216:217], v184 src0_sel:WORD_1
	v_cvt_pk_f32_fp8_e32 v[218:219], v185
	v_cvt_pk_f32_fp8_sdwa v[220:221], v185 src0_sel:WORD_1
	v_pk_mul_f32 v[222:223], v[112:113], v[214:215]
	v_pk_mul_f32 v[224:225], v[114:115], v[216:217]
	v_cvt_pk_f32_fp8_e32 v[214:215], v186
	v_cvt_pk_f32_fp8_sdwa v[216:217], v186 src0_sel:WORD_1
	v_pk_fma_f32 v[222:223], v[116:117], v[218:219], v[222:223]
	v_pk_fma_f32 v[224:225], v[118:119], v[220:221], v[224:225]
	v_cvt_pk_f32_fp8_e32 v[218:219], v187
	v_cvt_pk_f32_fp8_sdwa v[220:221], v187 src0_sel:WORD_1
	v_pk_fma_f32 v[222:223], v[120:121], v[214:215], v[222:223]
	v_pk_fma_f32 v[224:225], v[122:123], v[216:217], v[224:225]
	v_pk_fma_f32 v[222:223], v[124:125], v[218:219], v[222:223]
	v_pk_fma_f32 v[224:225], v[126:127], v[220:221], v[224:225]
	v_pk_add_f32 v[222:223], v[222:223], v[224:225]
	s_nop 0
	v_add_f32_e32 v228, v222, v223
	v_cvt_pk_f32_fp8_e32 v[214:215], v188
	v_cvt_pk_f32_fp8_sdwa v[216:217], v188 src0_sel:WORD_1
	v_cvt_pk_f32_fp8_e32 v[218:219], v189
	v_cvt_pk_f32_fp8_sdwa v[220:221], v189 src0_sel:WORD_1
	v_pk_mul_f32 v[222:223], v[112:113], v[214:215]
	v_pk_mul_f32 v[224:225], v[114:115], v[216:217]
	v_cvt_pk_f32_fp8_e32 v[214:215], v190
	v_cvt_pk_f32_fp8_sdwa v[216:217], v190 src0_sel:WORD_1
	v_pk_fma_f32 v[222:223], v[116:117], v[218:219], v[222:223]
	v_pk_fma_f32 v[224:225], v[118:119], v[220:221], v[224:225]
	v_cvt_pk_f32_fp8_e32 v[218:219], v191
	v_cvt_pk_f32_fp8_sdwa v[220:221], v191 src0_sel:WORD_1
	v_pk_fma_f32 v[222:223], v[120:121], v[214:215], v[222:223]
	v_pk_fma_f32 v[224:225], v[122:123], v[216:217], v[224:225]
; DI float gelu_exact(float x) { return 0.5f * x * (1.f + erff(x * 0.7071067811865476f)); }
; template <bool STORE>
; DI void peer_item(const Params& p, int item, char* smem) {
;     ...
; #pragma unroll
;       for (int u = 0; u < 8; ++u) {
;         float d = 0.f;
; #pragma unroll
;         for (int i = 0; i < 4; ++i) {
;           f32x2_t lo = __builtin_amdgcn_cvt_pk_f32_fp8((int)uq[u][i], false);
;           f32x2_t hi = __builtin_amdgcn_cvt_pk_f32_fp8((int)uq[u][i], true);
;           d += xf[4 * i] * lo.x + xf[4 * i + 1] * lo.y + xf[4 * i + 2] * hi.x + xf[4 * i + 3] * hi.y;
;         }
;         part[u] = d;
;       }
;       float q4[4], r2[2], h;
; #pragma unroll
;       for (int j = 0; j < 4; ++j) {
;         float mine = b5 ? part[j + 4] : part[j];
;         float other = b5 ? part[j] : part[j + 4];
;         q4[j] = mine + __shfl_xor(other, 32);
;       }
; #pragma unroll
;       for (int j = 0; j < 2; ++j) {
;         float mine = b4 ? q4[j + 2] : q4[j];
;         float other = b4 ? q4[j] : q4[j + 2];
;         r2[j] = mine + __shfl_xor(other, 16);
;       }
;       {
;         float mine = b3 ? r2[1] : r2[0];
;         float other = b3 ? r2[0] : r2[1];
;         h = mine + __shfl_xor(other, 8);
;       }
;       h += __shfl_xor(h, 4);
;       h += __shfl_xor(h, 2);
;       h += __shfl_xor(h, 1);
;       const float amine = gelu_exact(h * su) * gmine * sv;
;       if ((lane & 7) == 0) {
;         EG[tok * 128 + k + (lane >> 3)] = emine;
;         AG[tok * 128 + k + (lane >> 3)] = amine;
;       }
;     }
	v_pk_fma_f32 v[222:223], v[124:125], v[218:219], v[222:223]
	v_pk_fma_f32 v[224:225], v[126:127], v[220:221], v[224:225]
	v_pk_add_f32 v[222:223], v[222:223], v[224:225]
	s_nop 0
	v_add_f32_e32 v229, v222, v223
	v_cvt_pk_f32_fp8_e32 v[214:215], v192
	v_cvt_pk_f32_fp8_sdwa v[216:217], v192 src0_sel:WORD_1
	v_cvt_pk_f32_fp8_e32 v[218:219], v193
	v_cvt_pk_f32_fp8_sdwa v[220:221], v193 src0_sel:WORD_1
	v_pk_mul_f32 v[222:223], v[112:113], v[214:215]
	v_pk_mul_f32 v[224:225], v[114:115], v[216:217]
	v_cvt_pk_f32_fp8_e32 v[214:215], v194
	v_cvt_pk_f32_fp8_sdwa v[216:217], v194 src0_sel:WORD_1
	v_pk_fma_f32 v[222:223], v[116:117], v[218:219], v[222:223]
	v_pk_fma_f32 v[224:225], v[118:119], v[220:221], v[224:225]
	v_cvt_pk_f32_fp8_e32 v[218:219], v195
	v_cvt_pk_f32_fp8_sdwa v[220:221], v195 src0_sel:WORD_1
	v_pk_fma_f32 v[222:223], v[120:121], v[214:215], v[222:223]
	v_pk_fma_f32 v[224:225], v[122:123], v[216:217], v[224:225]
	v_pk_fma_f32 v[222:223], v[124:125], v[218:219], v[222:223]
	v_pk_fma_f32 v[224:225], v[126:127], v[220:221], v[224:225]
	v_pk_add_f32 v[222:223], v[222:223], v[224:225]
	s_nop 0
	v_add_f32_e32 v230, v222, v223
	v_cvt_pk_f32_fp8_e32 v[214:215], v196
	v_cvt_pk_f32_fp8_sdwa v[216:217], v196 src0_sel:WORD_1
	v_cvt_pk_f32_fp8_e32 v[218:219], v197
	v_cvt_pk_f32_fp8_sdwa v[220:221], v197 src0_sel:WORD_1
	v_pk_mul_f32 v[222:223], v[112:113], v[214:215]
	v_pk_mul_f32 v[224:225], v[114:115], v[216:217]
	v_cvt_pk_f32_fp8_e32 v[214:215], v198
	v_cvt_pk_f32_fp8_sdwa v[216:217], v198 src0_sel:WORD_1
	v_pk_fma_f32 v[222:223], v[116:117], v[218:219], v[222:223]
	v_pk_fma_f32 v[224:225], v[118:119], v[220:221], v[224:225]
	v_cvt_pk_f32_fp8_e32 v[218:219], v199
	v_cvt_pk_f32_fp8_sdwa v[220:221], v199 src0_sel:WORD_1
	v_pk_fma_f32 v[222:223], v[120:121], v[214:215], v[222:223]
	v_pk_fma_f32 v[224:225], v[122:123], v[216:217], v[224:225]
	v_pk_fma_f32 v[222:223], v[124:125], v[218:219], v[222:223]
	v_pk_fma_f32 v[224:225], v[126:127], v[220:221], v[224:225]
	v_pk_add_f32 v[222:223], v[222:223], v[224:225]
	s_nop 0
	v_add_f32_e32 v231, v222, v223
	v_cvt_pk_f32_fp8_e32 v[214:215], v200
	v_cvt_pk_f32_fp8_sdwa v[216:217], v200 src0_sel:WORD_1
	v_cvt_pk_f32_fp8_e32 v[218:219], v201
	v_cvt_pk_f32_fp8_sdwa v[220:221], v201 src0_sel:WORD_1
	v_pk_mul_f32 v[222:223], v[112:113], v[214:215]
	v_pk_mul_f32 v[224:225], v[114:115], v[216:217]
	v_cvt_pk_f32_fp8_e32 v[214:215], v202
	v_cvt_pk_f32_fp8_sdwa v[216:217], v202 src0_sel:WORD_1
	v_pk_fma_f32 v[222:223], v[116:117], v[218:219], v[222:223]
	v_pk_fma_f32 v[224:225], v[118:119], v[220:221], v[224:225]
	v_cvt_pk_f32_fp8_e32 v[218:219], v203
	v_cvt_pk_f32_fp8_sdwa v[220:221], v203 src0_sel:WORD_1
	v_pk_fma_f32 v[222:223], v[120:121], v[214:215], v[222:223]
	v_pk_fma_f32 v[224:225], v[122:123], v[216:217], v[224:225]
	v_pk_fma_f32 v[222:223], v[124:125], v[218:219], v[222:223]
	v_pk_fma_f32 v[224:225], v[126:127], v[220:221], v[224:225]
	v_pk_add_f32 v[222:223], v[222:223], v[224:225]
	s_nop 0
	v_add_f32_e32 v232, v222, v223
	v_cvt_pk_f32_fp8_e32 v[214:215], v204
	v_cvt_pk_f32_fp8_sdwa v[216:217], v204 src0_sel:WORD_1
	v_cvt_pk_f32_fp8_e32 v[218:219], v205
	v_cvt_pk_f32_fp8_sdwa v[220:221], v205 src0_sel:WORD_1
	v_pk_mul_f32 v[222:223], v[112:113], v[214:215]
	v_pk_mul_f32 v[224:225], v[114:115], v[216:217]
	v_cvt_pk_f32_fp8_e32 v[214:215], v206
	v_cvt_pk_f32_fp8_sdwa v[216:217], v206 src0_sel:WORD_1
	v_pk_fma_f32 v[222:223], v[116:117], v[218:219], v[222:223]
	v_pk_fma_f32 v[224:225], v[118:119], v[220:221], v[224:225]
	v_cvt_pk_f32_fp8_e32 v[218:219], v207
	v_cvt_pk_f32_fp8_sdwa v[220:221], v207 src0_sel:WORD_1
	v_pk_fma_f32 v[222:223], v[120:121], v[214:215], v[222:223]
	v_pk_fma_f32 v[224:225], v[122:123], v[216:217], v[224:225]
	v_pk_fma_f32 v[222:223], v[124:125], v[218:219], v[222:223]
	v_pk_fma_f32 v[224:225], v[126:127], v[220:221], v[224:225]
	v_pk_add_f32 v[222:223], v[222:223], v[224:225]
	s_nop 0
	v_add_f32_e32 v233, v222, v223
	v_permlane32_swap_b32_e32 v226, v230
	v_permlane32_swap_b32_e32 v227, v231
	v_permlane32_swap_b32_e32 v228, v232
	v_permlane32_swap_b32_e32 v229, v233
	v_add_f32_e32 v226, v226, v230
	v_add_f32_e32 v228, v228, v232
	v_add_f32_e32 v227, v227, v231
	v_add_f32_e32 v229, v229, v233
	s_nop 1
	v_permlane16_swap_b32_e32 v226, v228
	v_permlane16_swap_b32_e32 v227, v229
	v_add_f32_e32 v226, v226, v228
	v_add_f32_e32 v227, v227, v229
	s_nop 0
	v_cndmask_b32_e64 v230, v226, v227, s[24:25]
	v_cndmask_b32_e64 v231, v227, v226, s[24:25]
	s_nop 1
	v_add_f32_dpp v232, v231, v230 row_ror:8 row_mask:0xf bank_mask:0xf
	s_nop 1
	v_add_f32_dpp v233, v232, v232 quad_perm:[1,0,3,2] row_mask:0xf bank_mask:0xf
	s_nop 1
	v_add_f32_dpp v232, v233, v233 quad_perm:[2,3,0,1] row_mask:0xf bank_mask:0xf
	s_nop 1
	v_add_f32_dpp v233, v232, v232 row_half_mirror row_mask:0xf bank_mask:0xf
	ds_write_b32 v235, v233 offset:36384
	v_add_u32_e32 v235, 64, v235
	s_add_u32 s12, s12, 1
	s_cmp_lt_u32 s12, 8
	s_cbranch_scc1 .Lup_k
; DI float gelu_exact(float x) { return 0.5f * x * (1.f + erff(x * 0.7071067811865476f)); }
; template <bool STORE>
; DI void peer_item(const Params& p, int item, char* smem) {
;     ...
;       const int emine = e_s[tl * 128 + k + (lane >> 3)];
;       const float gmine = g_s[tl * 128 + k + (lane >> 3)];
;       const float su = SU[emine], sv = SV[emine];
;     ...
;       const float amine = gelu_exact(h * su) * gmine * sv;
;       if ((lane & 7) == 0) {
;         EG[tok * 128 + k + (lane >> 3)] = emine;
;         AG[tok * 128 + k + (lane >> 3)] = amine;
;       }
	s_waitcnt vmcnt(0) lgkmcnt(0)
	s_lshl_b32 s13, s14, 9
	s_add_u32 s26, s4, s13
	s_addc_u32 s27, s5, 0
	s_add_u32 s28, s6, s13
	s_addc_u32 s29, s7, 0
	ds_read_b32 v0, v237 offset:32768
	ds_read_b32 v1, v237 offset:33024
	ds_read_b32 v2, v237 offset:0
	ds_read_b32 v3, v237 offset:256
	ds_read_b32 v4, v237 offset:16384
	ds_read_b32 v5, v237 offset:16640
	ds_read_b32 v16, v237 offset:33280
	ds_read_b32 v17, v237 offset:33536
	ds_read_b32 v18, v237 offset:512
	ds_read_b32 v19, v237 offset:768
	ds_read_b32 v20, v237 offset:16896
	ds_read_b32 v21, v237 offset:17152
	ds_read_b32 v32, v237 offset:33792
	ds_read_b32 v33, v237 offset:34048
	ds_read_b32 v34, v237 offset:1024
	ds_read_b32 v35, v237 offset:1280
	ds_read_b32 v36, v237 offset:17408
	ds_read_b32 v37, v237 offset:17664
	ds_read_b32 v48, v237 offset:34304
	ds_read_b32 v49, v237 offset:34560
	ds_read_b32 v50, v237 offset:1536
	ds_read_b32 v51, v237 offset:1792
	ds_read_b32 v52, v237 offset:17920
	ds_read_b32 v53, v237 offset:18176
	ds_read_b32 v64, v237 offset:34816
	ds_read_b32 v65, v237 offset:35072
	ds_read_b32 v66, v237 offset:2048
	ds_read_b32 v67, v237 offset:2304
	ds_read_b32 v68, v237 offset:18432
	ds_read_b32 v69, v237 offset:18688
	ds_read_b32 v80, v237 offset:35328
	ds_read_b32 v81, v237 offset:35584
	ds_read_b32 v82, v237 offset:2560
	ds_read_b32 v83, v237 offset:2816
	ds_read_b32 v84, v237 offset:18944
	ds_read_b32 v85, v237 offset:19200
	ds_read_b32 v96, v237 offset:35840
	ds_read_b32 v97, v237 offset:36096
	ds_read_b32 v98, v237 offset:3072
	ds_read_b32 v99, v237 offset:3328
	ds_read_b32 v100, v237 offset:19456
	ds_read_b32 v101, v237 offset:19712
	ds_read_b32 v112, v237 offset:36352
	ds_read_b32 v113, v237 offset:36608
	ds_read_b32 v114, v237 offset:3584
	ds_read_b32 v115, v237 offset:3840
	ds_read_b32 v116, v237 offset:19968
	ds_read_b32 v117, v237 offset:20224
	s_waitcnt lgkmcnt(15)
	v_lshlrev_b32_e32 v10, 2, v2
	v_lshlrev_b32_e32 v11, 2, v3
	global_load_dword v6, v10, s[8:9]
	global_load_dword v7, v11, s[8:9]
	global_load_dword v8, v10, s[10:11]
	global_load_dword v9, v11, s[10:11]
	s_waitcnt lgkmcnt(15)
	v_lshlrev_b32_e32 v26, 2, v18
	v_lshlrev_b32_e32 v27, 2, v19
	global_load_dword v22, v26, s[8:9]
	global_load_dword v23, v27, s[8:9]
	global_load_dword v24, v26, s[10:11]
	global_load_dword v25, v27, s[10:11]
	s_waitcnt lgkmcnt(15)
	v_lshlrev_b32_e32 v42, 2, v34
	v_lshlrev_b32_e32 v43, 2, v35
	global_load_dword v38, v42, s[8:9]
	global_load_dword v39, v43, s[8:9]
	global_load_dword v40, v42, s[10:11]
	global_load_dword v41, v43, s[10:11]
	s_waitcnt lgkmcnt(15)
	v_lshlrev_b32_e32 v58, 2, v50
	v_lshlrev_b32_e32 v59, 2, v51
	global_load_dword v54, v58, s[8:9]
	global_load_dword v55, v59, s[8:9]
	global_load_dword v56, v58, s[10:11]
	global_load_dword v57, v59, s[10:11]
	s_waitcnt lgkmcnt(15)
	v_lshlrev_b32_e32 v74, 2, v66
	v_lshlrev_b32_e32 v75, 2, v67
	global_load_dword v70, v74, s[8:9]
	global_load_dword v71, v75, s[8:9]
	global_load_dword v72, v74, s[10:11]
	global_load_dword v73, v75, s[10:11]
	s_waitcnt lgkmcnt(12)
	v_lshlrev_b32_e32 v90, 2, v82
	v_lshlrev_b32_e32 v91, 2, v83
	global_load_dword v86, v90, s[8:9]
	global_load_dword v87, v91, s[8:9]
	global_load_dword v88, v90, s[10:11]
	global_load_dword v89, v91, s[10:11]
	s_waitcnt lgkmcnt(6)
	v_lshlrev_b32_e32 v106, 2, v98
	v_lshlrev_b32_e32 v107, 2, v99
	global_load_dword v102, v106, s[8:9]
	global_load_dword v103, v107, s[8:9]
	global_load_dword v104, v106, s[10:11]
	global_load_dword v105, v107, s[10:11]
	s_waitcnt lgkmcnt(0)
	v_lshlrev_b32_e32 v122, 2, v114
	v_lshlrev_b32_e32 v123, 2, v115
	global_load_dword v118, v122, s[8:9]
	global_load_dword v119, v123, s[8:9]
	global_load_dword v120, v122, s[10:11]
	global_load_dword v121, v123, s[10:11]
	s_waitcnt vmcnt(28)
	v_mul_f32_e32 v144, v6, v0
	v_mul_f32_e32 v145, 0x3f3504f3, v144
	v_mov_b32_e32 v146, 0xb9c68948
	v_fma_f32 v146, |v145|, s80, v146
	v_fma_f32 v146, |v145|, v146, s81
	v_fma_f32 v146, |v145|, v146, s82
	v_fma_f32 v146, |v145|, v146, s83
	v_fma_f32 v146, |v145|, v146, s84
	v_fma_f32 v146, |v145|, v146, s85
	v_fma_f32 v146, |v145|, v146, |v145|
	v_mul_f32_e32 v147, 0xbfb8aa3b, v146
	v_fma_f32 v148, v146, s86, -v147
	v_rndne_f32_e32 v149, v147
	v_fmac_f32_e32 v148, 0xb2a5705f, v146
	v_sub_f32_e32 v147, v147, v149
	v_add_f32_e32 v147, v147, v148
	v_cvt_i32_f32_e32 v148, v149
	v_exp_f32_e32 v147, v147
	v_cmp_nlt_f32_e32 vcc, s87, v146
	v_ldexp_f32 v147, v147, v148
	s_nop 0
	v_cndmask_b32_e32 v147, 0, v147, vcc
	v_cmp_ngt_f32_e32 vcc, s88, v146
	v_mov_b32_e32 v148, 0x7f800000
	s_nop 0
	v_cndmask_b32_e32 v147, v148, v147, vcc
	v_sub_f32_e32 v147, 1.0, v147
	v_mul_f32_e32 v148, v145, v145
	v_mov_b32_e32 v149, 0x3ba10414
	v_fmamk_f32 v149, v148, 0xba1345e1, v149
	v_fmaak_f32 v149, v148, v149, 0xbcdac9b8
	v_fmaak_f32 v149, v148, v149, 0x3de703be
	v_fmaak_f32 v149, v148, v149, 0xbec09330
	v_fmaak_f32 v149, v148, v149, 0x3e0375d0
	v_fma_f32 v149, |v145|, v149, |v145|
	v_cmp_nlt_f32_e64 vcc, |v145|, 1.0
	s_nop 1
	v_cndmask_b32_e32 v147, v149, v147, vcc
	v_bfi_b32 v147, s89, v147, v145
	v_mul_f32_e32 v144, 0.5, v144
	v_add_f32_e32 v147, 1.0, v147
	v_mul_f32_e32 v144, v144, v147
	v_mul_f32_e32 v144, v4, v144
	v_mul_f32_e32 v0, v8, v144
	v_mul_f32_e32 v144, v7, v1
	v_mul_f32_e32 v145, 0x3f3504f3, v144
	v_mov_b32_e32 v146, 0xb9c68948
	v_fma_f32 v146, |v145|, s80, v146
	v_fma_f32 v146, |v145|, v146, s81
	v_fma_f32 v146, |v145|, v146, s82
	v_fma_f32 v146, |v145|, v146, s83
	v_fma_f32 v146, |v145|, v146, s84
	v_fma_f32 v146, |v145|, v146, s85
	v_fma_f32 v146, |v145|, v146, |v145|
	v_mul_f32_e32 v147, 0xbfb8aa3b, v146
	v_fma_f32 v148, v146, s86, -v147
	v_rndne_f32_e32 v149, v147
	v_fmac_f32_e32 v148, 0xb2a5705f, v146
	v_sub_f32_e32 v147, v147, v149
	v_add_f32_e32 v147, v147, v148
	v_cvt_i32_f32_e32 v148, v149
	v_exp_f32_e32 v147, v147
	v_cmp_nlt_f32_e32 vcc, s87, v146
	v_ldexp_f32 v147, v147, v148
	s_nop 0
	v_cndmask_b32_e32 v147, 0, v147, vcc
	v_cmp_ngt_f32_e32 vcc, s88, v146
	v_mov_b32_e32 v148, 0x7f800000
	s_nop 0
	v_cndmask_b32_e32 v147, v148, v147, vcc
	v_sub_f32_e32 v147, 1.0, v147
	v_mul_f32_e32 v148, v145, v145
	v_mov_b32_e32 v149, 0x3ba10414
	v_fmamk_f32 v149, v148, 0xba1345e1, v149
	v_fmaak_f32 v149, v148, v149, 0xbcdac9b8
	v_fmaak_f32 v149, v148, v149, 0x3de703be
	v_fmaak_f32 v149, v148, v149, 0xbec09330
	v_fmaak_f32 v149, v148, v149, 0x3e0375d0
	v_fma_f32 v149, |v145|, v149, |v145|
	v_cmp_nlt_f32_e64 vcc, |v145|, 1.0
	s_nop 1
	v_cndmask_b32_e32 v147, v149, v147, vcc
	v_bfi_b32 v147, s89, v147, v145
	v_mul_f32_e32 v144, 0.5, v144
	v_add_f32_e32 v147, 1.0, v147
	v_mul_f32_e32 v144, v144, v147
	v_mul_f32_e32 v144, v5, v144
	v_mul_f32_e32 v1, v9, v144
	global_store_dword v238, v2, s[26:27] offset:0
	global_store_dword v238, v3, s[26:27] offset:256
	global_store_dword v238, v0, s[28:29] offset:0
	global_store_dword v238, v1, s[28:29] offset:256
	s_waitcnt vmcnt(28)
; DI float gelu_exact(float x) { return 0.5f * x * (1.f + erff(x * 0.7071067811865476f)); }
; template <bool STORE>
; DI void peer_item(const Params& p, int item, char* smem) {
;     ...
;       const float amine = gelu_exact(h * su) * gmine * sv;
;       if ((lane & 7) == 0) {
;         EG[tok * 128 + k + (lane >> 3)] = emine;
;         AG[tok * 128 + k + (lane >> 3)] = amine;
;       }
	v_mul_f32_e32 v144, v22, v16
	v_mul_f32_e32 v145, 0x3f3504f3, v144
	v_mov_b32_e32 v146, 0xb9c68948
	v_fma_f32 v146, |v145|, s80, v146
	v_fma_f32 v146, |v145|, v146, s81
	v_fma_f32 v146, |v145|, v146, s82
	v_fma_f32 v146, |v145|, v146, s83
	v_fma_f32 v146, |v145|, v146, s84
	v_fma_f32 v146, |v145|, v146, s85
	v_fma_f32 v146, |v145|, v146, |v145|
	v_mul_f32_e32 v147, 0xbfb8aa3b, v146
	v_fma_f32 v148, v146, s86, -v147
	v_rndne_f32_e32 v149, v147
	v_fmac_f32_e32 v148, 0xb2a5705f, v146
	v_sub_f32_e32 v147, v147, v149
	v_add_f32_e32 v147, v147, v148
	v_cvt_i32_f32_e32 v148, v149
	v_exp_f32_e32 v147, v147
	v_cmp_nlt_f32_e32 vcc, s87, v146
	v_ldexp_f32 v147, v147, v148
	s_nop 0
	v_cndmask_b32_e32 v147, 0, v147, vcc
	v_cmp_ngt_f32_e32 vcc, s88, v146
	v_mov_b32_e32 v148, 0x7f800000
	s_nop 0
	v_cndmask_b32_e32 v147, v148, v147, vcc
	v_sub_f32_e32 v147, 1.0, v147
	v_mul_f32_e32 v148, v145, v145
	v_mov_b32_e32 v149, 0x3ba10414
	v_fmamk_f32 v149, v148, 0xba1345e1, v149
	v_fmaak_f32 v149, v148, v149, 0xbcdac9b8
	v_fmaak_f32 v149, v148, v149, 0x3de703be
	v_fmaak_f32 v149, v148, v149, 0xbec09330
	v_fmaak_f32 v149, v148, v149, 0x3e0375d0
	v_fma_f32 v149, |v145|, v149, |v145|
	v_cmp_nlt_f32_e64 vcc, |v145|, 1.0
	s_nop 1
	v_cndmask_b32_e32 v147, v149, v147, vcc
	v_bfi_b32 v147, s89, v147, v145
	v_mul_f32_e32 v144, 0.5, v144
	v_add_f32_e32 v147, 1.0, v147
	v_mul_f32_e32 v144, v144, v147
	v_mul_f32_e32 v144, v20, v144
	v_mul_f32_e32 v16, v24, v144
	v_mul_f32_e32 v144, v23, v17
	v_mul_f32_e32 v145, 0x3f3504f3, v144
	v_mov_b32_e32 v146, 0xb9c68948
	v_fma_f32 v146, |v145|, s80, v146
	v_fma_f32 v146, |v145|, v146, s81
	v_fma_f32 v146, |v145|, v146, s82
	v_fma_f32 v146, |v145|, v146, s83
	v_fma_f32 v146, |v145|, v146, s84
	v_fma_f32 v146, |v145|, v146, s85
	v_fma_f32 v146, |v145|, v146, |v145|
	v_mul_f32_e32 v147, 0xbfb8aa3b, v146
	v_fma_f32 v148, v146, s86, -v147
	v_rndne_f32_e32 v149, v147
	v_fmac_f32_e32 v148, 0xb2a5705f, v146
	v_sub_f32_e32 v147, v147, v149
	v_add_f32_e32 v147, v147, v148
	v_cvt_i32_f32_e32 v148, v149
	v_exp_f32_e32 v147, v147
	v_cmp_nlt_f32_e32 vcc, s87, v146
	v_ldexp_f32 v147, v147, v148
	s_nop 0
	v_cndmask_b32_e32 v147, 0, v147, vcc
	v_cmp_ngt_f32_e32 vcc, s88, v146
	v_mov_b32_e32 v148, 0x7f800000
	s_nop 0
	v_cndmask_b32_e32 v147, v148, v147, vcc
	v_sub_f32_e32 v147, 1.0, v147
	v_mul_f32_e32 v148, v145, v145
	v_mov_b32_e32 v149, 0x3ba10414
	v_fmamk_f32 v149, v148, 0xba1345e1, v149
	v_fmaak_f32 v149, v148, v149, 0xbcdac9b8
	v_fmaak_f32 v149, v148, v149, 0x3de703be
	v_fmaak_f32 v149, v148, v149, 0xbec09330
	v_fmaak_f32 v149, v148, v149, 0x3e0375d0
	v_fma_f32 v149, |v145|, v149, |v145|
	v_cmp_nlt_f32_e64 vcc, |v145|, 1.0
	s_nop 1
	v_cndmask_b32_e32 v147, v149, v147, vcc
	v_bfi_b32 v147, s89, v147, v145
	v_mul_f32_e32 v144, 0.5, v144
	v_add_f32_e32 v147, 1.0, v147
	v_mul_f32_e32 v144, v144, v147
	v_mul_f32_e32 v144, v21, v144
	v_mul_f32_e32 v17, v25, v144
	global_store_dword v238, v18, s[26:27] offset:512
	global_store_dword v238, v19, s[26:27] offset:768
	global_store_dword v238, v16, s[28:29] offset:512
	global_store_dword v238, v17, s[28:29] offset:768
	s_waitcnt vmcnt(28)
	v_mul_f32_e32 v144, v38, v32
	v_mul_f32_e32 v145, 0x3f3504f3, v144
	v_mov_b32_e32 v146, 0xb9c68948
	v_fma_f32 v146, |v145|, s80, v146
	v_fma_f32 v146, |v145|, v146, s81
	v_fma_f32 v146, |v145|, v146, s82
	v_fma_f32 v146, |v145|, v146, s83
	v_fma_f32 v146, |v145|, v146, s84
	v_fma_f32 v146, |v145|, v146, s85
	v_fma_f32 v146, |v145|, v146, |v145|
	v_mul_f32_e32 v147, 0xbfb8aa3b, v146
	v_fma_f32 v148, v146, s86, -v147
	v_rndne_f32_e32 v149, v147
	v_fmac_f32_e32 v148, 0xb2a5705f, v146
	v_sub_f32_e32 v147, v147, v149
	v_add_f32_e32 v147, v147, v148
	v_cvt_i32_f32_e32 v148, v149
	v_exp_f32_e32 v147, v147
	v_cmp_nlt_f32_e32 vcc, s87, v146
	v_ldexp_f32 v147, v147, v148
	s_nop 0
	v_cndmask_b32_e32 v147, 0, v147, vcc
	v_cmp_ngt_f32_e32 vcc, s88, v146
	v_mov_b32_e32 v148, 0x7f800000
	s_nop 0
	v_cndmask_b32_e32 v147, v148, v147, vcc
	v_sub_f32_e32 v147, 1.0, v147
	v_mul_f32_e32 v148, v145, v145
	v_mov_b32_e32 v149, 0x3ba10414
	v_fmamk_f32 v149, v148, 0xba1345e1, v149
	v_fmaak_f32 v149, v148, v149, 0xbcdac9b8
	v_fmaak_f32 v149, v148, v149, 0x3de703be
	v_fmaak_f32 v149, v148, v149, 0xbec09330
	v_fmaak_f32 v149, v148, v149, 0x3e0375d0
	v_fma_f32 v149, |v145|, v149, |v145|
	v_cmp_nlt_f32_e64 vcc, |v145|, 1.0
	s_nop 1
	v_cndmask_b32_e32 v147, v149, v147, vcc
	v_bfi_b32 v147, s89, v147, v145
	v_mul_f32_e32 v144, 0.5, v144
	v_add_f32_e32 v147, 1.0, v147
	v_mul_f32_e32 v144, v144, v147
	v_mul_f32_e32 v144, v36, v144
	v_mul_f32_e32 v32, v40, v144
	v_mul_f32_e32 v144, v39, v33
	v_mul_f32_e32 v145, 0x3f3504f3, v144
	v_mov_b32_e32 v146, 0xb9c68948
	v_fma_f32 v146, |v145|, s80, v146
	v_fma_f32 v146, |v145|, v146, s81
	v_fma_f32 v146, |v145|, v146, s82
	v_fma_f32 v146, |v145|, v146, s83
	v_fma_f32 v146, |v145|, v146, s84
	v_fma_f32 v146, |v145|, v146, s85
	v_fma_f32 v146, |v145|, v146, |v145|
	v_mul_f32_e32 v147, 0xbfb8aa3b, v146
	v_fma_f32 v148, v146, s86, -v147
	v_rndne_f32_e32 v149, v147
	v_fmac_f32_e32 v148, 0xb2a5705f, v146
	v_sub_f32_e32 v147, v147, v149
	v_add_f32_e32 v147, v147, v148
	v_cvt_i32_f32_e32 v148, v149
	v_exp_f32_e32 v147, v147
	v_cmp_nlt_f32_e32 vcc, s87, v146
	v_ldexp_f32 v147, v147, v148
	s_nop 0
	v_cndmask_b32_e32 v147, 0, v147, vcc
	v_cmp_ngt_f32_e32 vcc, s88, v146
	v_mov_b32_e32 v148, 0x7f800000
	s_nop 0
	v_cndmask_b32_e32 v147, v148, v147, vcc
	v_sub_f32_e32 v147, 1.0, v147
	v_mul_f32_e32 v148, v145, v145
	v_mov_b32_e32 v149, 0x3ba10414
	v_fmamk_f32 v149, v148, 0xba1345e1, v149
	v_fmaak_f32 v149, v148, v149, 0xbcdac9b8
	v_fmaak_f32 v149, v148, v149, 0x3de703be
	v_fmaak_f32 v149, v148, v149, 0xbec09330
	v_fmaak_f32 v149, v148, v149, 0x3e0375d0
	v_fma_f32 v149, |v145|, v149, |v145|
	v_cmp_nlt_f32_e64 vcc, |v145|, 1.0
	s_nop 1
	v_cndmask_b32_e32 v147, v149, v147, vcc
	v_bfi_b32 v147, s89, v147, v145
	v_mul_f32_e32 v144, 0.5, v144
	v_add_f32_e32 v147, 1.0, v147
	v_mul_f32_e32 v144, v144, v147
	v_mul_f32_e32 v144, v37, v144
	v_mul_f32_e32 v33, v41, v144
	global_store_dword v238, v34, s[26:27] offset:1024
	global_store_dword v238, v35, s[26:27] offset:1280
	global_store_dword v238, v32, s[28:29] offset:1024
	global_store_dword v238, v33, s[28:29] offset:1280
	s_waitcnt vmcnt(28)
; DI float gelu_exact(float x) { return 0.5f * x * (1.f + erff(x * 0.7071067811865476f)); }
; template <bool STORE>
; DI void peer_item(const Params& p, int item, char* smem) {
;     ...
;       const float amine = gelu_exact(h * su) * gmine * sv;
;       if ((lane & 7) == 0) {
;         EG[tok * 128 + k + (lane >> 3)] = emine;
;         AG[tok * 128 + k + (lane >> 3)] = amine;
;       }
	v_mul_f32_e32 v144, v54, v48
	v_mul_f32_e32 v145, 0x3f3504f3, v144
	v_mov_b32_e32 v146, 0xb9c68948
	v_fma_f32 v146, |v145|, s80, v146
	v_fma_f32 v146, |v145|, v146, s81
	v_fma_f32 v146, |v145|, v146, s82
	v_fma_f32 v146, |v145|, v146, s83
	v_fma_f32 v146, |v145|, v146, s84
	v_fma_f32 v146, |v145|, v146, s85
	v_fma_f32 v146, |v145|, v146, |v145|
	v_mul_f32_e32 v147, 0xbfb8aa3b, v146
	v_fma_f32 v148, v146, s86, -v147
	v_rndne_f32_e32 v149, v147
	v_fmac_f32_e32 v148, 0xb2a5705f, v146
	v_sub_f32_e32 v147, v147, v149
	v_add_f32_e32 v147, v147, v148
	v_cvt_i32_f32_e32 v148, v149
	v_exp_f32_e32 v147, v147
	v_cmp_nlt_f32_e32 vcc, s87, v146
	v_ldexp_f32 v147, v147, v148
	s_nop 0
	v_cndmask_b32_e32 v147, 0, v147, vcc
	v_cmp_ngt_f32_e32 vcc, s88, v146
	v_mov_b32_e32 v148, 0x7f800000
	s_nop 0
	v_cndmask_b32_e32 v147, v148, v147, vcc
	v_sub_f32_e32 v147, 1.0, v147
	v_mul_f32_e32 v148, v145, v145
	v_mov_b32_e32 v149, 0x3ba10414
	v_fmamk_f32 v149, v148, 0xba1345e1, v149
	v_fmaak_f32 v149, v148, v149, 0xbcdac9b8
	v_fmaak_f32 v149, v148, v149, 0x3de703be
	v_fmaak_f32 v149, v148, v149, 0xbec09330
	v_fmaak_f32 v149, v148, v149, 0x3e0375d0
	v_fma_f32 v149, |v145|, v149, |v145|
	v_cmp_nlt_f32_e64 vcc, |v145|, 1.0
	s_nop 1
	v_cndmask_b32_e32 v147, v149, v147, vcc
	v_bfi_b32 v147, s89, v147, v145
	v_mul_f32_e32 v144, 0.5, v144
	v_add_f32_e32 v147, 1.0, v147
	v_mul_f32_e32 v144, v144, v147
	v_mul_f32_e32 v144, v52, v144
	v_mul_f32_e32 v48, v56, v144
	v_mul_f32_e32 v144, v55, v49
	v_mul_f32_e32 v145, 0x3f3504f3, v144
	v_mov_b32_e32 v146, 0xb9c68948
	v_fma_f32 v146, |v145|, s80, v146
	v_fma_f32 v146, |v145|, v146, s81
	v_fma_f32 v146, |v145|, v146, s82
	v_fma_f32 v146, |v145|, v146, s83
	v_fma_f32 v146, |v145|, v146, s84
	v_fma_f32 v146, |v145|, v146, s85
	v_fma_f32 v146, |v145|, v146, |v145|
	v_mul_f32_e32 v147, 0xbfb8aa3b, v146
	v_fma_f32 v148, v146, s86, -v147
	v_rndne_f32_e32 v149, v147
	v_fmac_f32_e32 v148, 0xb2a5705f, v146
	v_sub_f32_e32 v147, v147, v149
	v_add_f32_e32 v147, v147, v148
	v_cvt_i32_f32_e32 v148, v149
	v_exp_f32_e32 v147, v147
	v_cmp_nlt_f32_e32 vcc, s87, v146
	v_ldexp_f32 v147, v147, v148
	s_nop 0
	v_cndmask_b32_e32 v147, 0, v147, vcc
	v_cmp_ngt_f32_e32 vcc, s88, v146
	v_mov_b32_e32 v148, 0x7f800000
	s_nop 0
	v_cndmask_b32_e32 v147, v148, v147, vcc
	v_sub_f32_e32 v147, 1.0, v147
	v_mul_f32_e32 v148, v145, v145
	v_mov_b32_e32 v149, 0x3ba10414
	v_fmamk_f32 v149, v148, 0xba1345e1, v149
	v_fmaak_f32 v149, v148, v149, 0xbcdac9b8
	v_fmaak_f32 v149, v148, v149, 0x3de703be
	v_fmaak_f32 v149, v148, v149, 0xbec09330
	v_fmaak_f32 v149, v148, v149, 0x3e0375d0
	v_fma_f32 v149, |v145|, v149, |v145|
	v_cmp_nlt_f32_e64 vcc, |v145|, 1.0
	s_nop 1
	v_cndmask_b32_e32 v147, v149, v147, vcc
	v_bfi_b32 v147, s89, v147, v145
	v_mul_f32_e32 v144, 0.5, v144
	v_add_f32_e32 v147, 1.0, v147
	v_mul_f32_e32 v144, v144, v147
	v_mul_f32_e32 v144, v53, v144
	v_mul_f32_e32 v49, v57, v144
	global_store_dword v238, v50, s[26:27] offset:1536
	global_store_dword v238, v51, s[26:27] offset:1792
	global_store_dword v238, v48, s[28:29] offset:1536
	global_store_dword v238, v49, s[28:29] offset:1792
	s_waitcnt vmcnt(28)
	v_mul_f32_e32 v144, v70, v64
	v_mul_f32_e32 v145, 0x3f3504f3, v144
	v_mov_b32_e32 v146, 0xb9c68948
	v_fma_f32 v146, |v145|, s80, v146
	v_fma_f32 v146, |v145|, v146, s81
	v_fma_f32 v146, |v145|, v146, s82
	v_fma_f32 v146, |v145|, v146, s83
	v_fma_f32 v146, |v145|, v146, s84
	v_fma_f32 v146, |v145|, v146, s85
	v_fma_f32 v146, |v145|, v146, |v145|
	v_mul_f32_e32 v147, 0xbfb8aa3b, v146
	v_fma_f32 v148, v146, s86, -v147
	v_rndne_f32_e32 v149, v147
	v_fmac_f32_e32 v148, 0xb2a5705f, v146
	v_sub_f32_e32 v147, v147, v149
	v_add_f32_e32 v147, v147, v148
	v_cvt_i32_f32_e32 v148, v149
	v_exp_f32_e32 v147, v147
	v_cmp_nlt_f32_e32 vcc, s87, v146
	v_ldexp_f32 v147, v147, v148
	s_nop 0
	v_cndmask_b32_e32 v147, 0, v147, vcc
	v_cmp_ngt_f32_e32 vcc, s88, v146
	v_mov_b32_e32 v148, 0x7f800000
	s_nop 0
	v_cndmask_b32_e32 v147, v148, v147, vcc
	v_sub_f32_e32 v147, 1.0, v147
	v_mul_f32_e32 v148, v145, v145
	v_mov_b32_e32 v149, 0x3ba10414
	v_fmamk_f32 v149, v148, 0xba1345e1, v149
	v_fmaak_f32 v149, v148, v149, 0xbcdac9b8
	v_fmaak_f32 v149, v148, v149, 0x3de703be
	v_fmaak_f32 v149, v148, v149, 0xbec09330
	v_fmaak_f32 v149, v148, v149, 0x3e0375d0
	v_fma_f32 v149, |v145|, v149, |v145|
	v_cmp_nlt_f32_e64 vcc, |v145|, 1.0
	s_nop 1
	v_cndmask_b32_e32 v147, v149, v147, vcc
	v_bfi_b32 v147, s89, v147, v145
	v_mul_f32_e32 v144, 0.5, v144
	v_add_f32_e32 v147, 1.0, v147
	v_mul_f32_e32 v144, v144, v147
	v_mul_f32_e32 v144, v68, v144
	v_mul_f32_e32 v64, v72, v144
	v_mul_f32_e32 v144, v71, v65
	v_mul_f32_e32 v145, 0x3f3504f3, v144
	v_mov_b32_e32 v146, 0xb9c68948
	v_fma_f32 v146, |v145|, s80, v146
	v_fma_f32 v146, |v145|, v146, s81
	v_fma_f32 v146, |v145|, v146, s82
	v_fma_f32 v146, |v145|, v146, s83
	v_fma_f32 v146, |v145|, v146, s84
	v_fma_f32 v146, |v145|, v146, s85
	v_fma_f32 v146, |v145|, v146, |v145|
	v_mul_f32_e32 v147, 0xbfb8aa3b, v146
	v_fma_f32 v148, v146, s86, -v147
	v_rndne_f32_e32 v149, v147
	v_fmac_f32_e32 v148, 0xb2a5705f, v146
	v_sub_f32_e32 v147, v147, v149
	v_add_f32_e32 v147, v147, v148
	v_cvt_i32_f32_e32 v148, v149
	v_exp_f32_e32 v147, v147
	v_cmp_nlt_f32_e32 vcc, s87, v146
	v_ldexp_f32 v147, v147, v148
	s_nop 0
	v_cndmask_b32_e32 v147, 0, v147, vcc
	v_cmp_ngt_f32_e32 vcc, s88, v146
	v_mov_b32_e32 v148, 0x7f800000
	s_nop 0
	v_cndmask_b32_e32 v147, v148, v147, vcc
	v_sub_f32_e32 v147, 1.0, v147
	v_mul_f32_e32 v148, v145, v145
	v_mov_b32_e32 v149, 0x3ba10414
	v_fmamk_f32 v149, v148, 0xba1345e1, v149
	v_fmaak_f32 v149, v148, v149, 0xbcdac9b8
	v_fmaak_f32 v149, v148, v149, 0x3de703be
	v_fmaak_f32 v149, v148, v149, 0xbec09330
	v_fmaak_f32 v149, v148, v149, 0x3e0375d0
	v_fma_f32 v149, |v145|, v149, |v145|
	v_cmp_nlt_f32_e64 vcc, |v145|, 1.0
	s_nop 1
	v_cndmask_b32_e32 v147, v149, v147, vcc
	v_bfi_b32 v147, s89, v147, v145
	v_mul_f32_e32 v144, 0.5, v144
	v_add_f32_e32 v147, 1.0, v147
	v_mul_f32_e32 v144, v144, v147
	v_mul_f32_e32 v144, v69, v144
	v_mul_f32_e32 v65, v73, v144
	global_store_dword v238, v66, s[26:27] offset:2048
	global_store_dword v238, v67, s[26:27] offset:2304
	global_store_dword v238, v64, s[28:29] offset:2048
	global_store_dword v238, v65, s[28:29] offset:2304
	s_waitcnt vmcnt(28)
; DI float gelu_exact(float x) { return 0.5f * x * (1.f + erff(x * 0.7071067811865476f)); }
; template <bool STORE>
; DI void peer_item(const Params& p, int item, char* smem) {
;     ...
;       const float amine = gelu_exact(h * su) * gmine * sv;
;       if ((lane & 7) == 0) {
;         EG[tok * 128 + k + (lane >> 3)] = emine;
;         AG[tok * 128 + k + (lane >> 3)] = amine;
;       }
	v_mul_f32_e32 v144, v86, v80
	v_mul_f32_e32 v145, 0x3f3504f3, v144
	v_mov_b32_e32 v146, 0xb9c68948
	v_fma_f32 v146, |v145|, s80, v146
	v_fma_f32 v146, |v145|, v146, s81
	v_fma_f32 v146, |v145|, v146, s82
	v_fma_f32 v146, |v145|, v146, s83
	v_fma_f32 v146, |v145|, v146, s84
	v_fma_f32 v146, |v145|, v146, s85
	v_fma_f32 v146, |v145|, v146, |v145|
	v_mul_f32_e32 v147, 0xbfb8aa3b, v146
	v_fma_f32 v148, v146, s86, -v147
	v_rndne_f32_e32 v149, v147
	v_fmac_f32_e32 v148, 0xb2a5705f, v146
	v_sub_f32_e32 v147, v147, v149
	v_add_f32_e32 v147, v147, v148
	v_cvt_i32_f32_e32 v148, v149
	v_exp_f32_e32 v147, v147
	v_cmp_nlt_f32_e32 vcc, s87, v146
	v_ldexp_f32 v147, v147, v148
	s_nop 0
	v_cndmask_b32_e32 v147, 0, v147, vcc
	v_cmp_ngt_f32_e32 vcc, s88, v146
	v_mov_b32_e32 v148, 0x7f800000
	s_nop 0
	v_cndmask_b32_e32 v147, v148, v147, vcc
	v_sub_f32_e32 v147, 1.0, v147
	v_mul_f32_e32 v148, v145, v145
	v_mov_b32_e32 v149, 0x3ba10414
	v_fmamk_f32 v149, v148, 0xba1345e1, v149
	v_fmaak_f32 v149, v148, v149, 0xbcdac9b8
	v_fmaak_f32 v149, v148, v149, 0x3de703be
	v_fmaak_f32 v149, v148, v149, 0xbec09330
	v_fmaak_f32 v149, v148, v149, 0x3e0375d0
	v_fma_f32 v149, |v145|, v149, |v145|
	v_cmp_nlt_f32_e64 vcc, |v145|, 1.0
	s_nop 1
	v_cndmask_b32_e32 v147, v149, v147, vcc
	v_bfi_b32 v147, s89, v147, v145
	v_mul_f32_e32 v144, 0.5, v144
	v_add_f32_e32 v147, 1.0, v147
	v_mul_f32_e32 v144, v144, v147
	v_mul_f32_e32 v144, v84, v144
	v_mul_f32_e32 v80, v88, v144
	v_mul_f32_e32 v144, v87, v81
	v_mul_f32_e32 v145, 0x3f3504f3, v144
	v_mov_b32_e32 v146, 0xb9c68948
	v_fma_f32 v146, |v145|, s80, v146
	v_fma_f32 v146, |v145|, v146, s81
	v_fma_f32 v146, |v145|, v146, s82
	v_fma_f32 v146, |v145|, v146, s83
	v_fma_f32 v146, |v145|, v146, s84
	v_fma_f32 v146, |v145|, v146, s85
	v_fma_f32 v146, |v145|, v146, |v145|
	v_mul_f32_e32 v147, 0xbfb8aa3b, v146
	v_fma_f32 v148, v146, s86, -v147
	v_rndne_f32_e32 v149, v147
	v_fmac_f32_e32 v148, 0xb2a5705f, v146
	v_sub_f32_e32 v147, v147, v149
	v_add_f32_e32 v147, v147, v148
	v_cvt_i32_f32_e32 v148, v149
	v_exp_f32_e32 v147, v147
	v_cmp_nlt_f32_e32 vcc, s87, v146
	v_ldexp_f32 v147, v147, v148
	s_nop 0
	v_cndmask_b32_e32 v147, 0, v147, vcc
	v_cmp_ngt_f32_e32 vcc, s88, v146
	v_mov_b32_e32 v148, 0x7f800000
	s_nop 0
	v_cndmask_b32_e32 v147, v148, v147, vcc
	v_sub_f32_e32 v147, 1.0, v147
	v_mul_f32_e32 v148, v145, v145
	v_mov_b32_e32 v149, 0x3ba10414
	v_fmamk_f32 v149, v148, 0xba1345e1, v149
	v_fmaak_f32 v149, v148, v149, 0xbcdac9b8
	v_fmaak_f32 v149, v148, v149, 0x3de703be
	v_fmaak_f32 v149, v148, v149, 0xbec09330
	v_fmaak_f32 v149, v148, v149, 0x3e0375d0
	v_fma_f32 v149, |v145|, v149, |v145|
	v_cmp_nlt_f32_e64 vcc, |v145|, 1.0
	s_nop 1
	v_cndmask_b32_e32 v147, v149, v147, vcc
	v_bfi_b32 v147, s89, v147, v145
	v_mul_f32_e32 v144, 0.5, v144
	v_add_f32_e32 v147, 1.0, v147
	v_mul_f32_e32 v144, v144, v147
	v_mul_f32_e32 v144, v85, v144
	v_mul_f32_e32 v81, v89, v144
	global_store_dword v238, v82, s[26:27] offset:2560
	global_store_dword v238, v83, s[26:27] offset:2816
	global_store_dword v238, v80, s[28:29] offset:2560
	global_store_dword v238, v81, s[28:29] offset:2816
	s_waitcnt vmcnt(28)
	v_mul_f32_e32 v144, v102, v96
	v_mul_f32_e32 v145, 0x3f3504f3, v144
	v_mov_b32_e32 v146, 0xb9c68948
	v_fma_f32 v146, |v145|, s80, v146
	v_fma_f32 v146, |v145|, v146, s81
	v_fma_f32 v146, |v145|, v146, s82
	v_fma_f32 v146, |v145|, v146, s83
	v_fma_f32 v146, |v145|, v146, s84
	v_fma_f32 v146, |v145|, v146, s85
	v_fma_f32 v146, |v145|, v146, |v145|
	v_mul_f32_e32 v147, 0xbfb8aa3b, v146
	v_fma_f32 v148, v146, s86, -v147
	v_rndne_f32_e32 v149, v147
	v_fmac_f32_e32 v148, 0xb2a5705f, v146
	v_sub_f32_e32 v147, v147, v149
	v_add_f32_e32 v147, v147, v148
	v_cvt_i32_f32_e32 v148, v149
	v_exp_f32_e32 v147, v147
	v_cmp_nlt_f32_e32 vcc, s87, v146
	v_ldexp_f32 v147, v147, v148
	s_nop 0
	v_cndmask_b32_e32 v147, 0, v147, vcc
	v_cmp_ngt_f32_e32 vcc, s88, v146
	v_mov_b32_e32 v148, 0x7f800000
	s_nop 0
	v_cndmask_b32_e32 v147, v148, v147, vcc
	v_sub_f32_e32 v147, 1.0, v147
	v_mul_f32_e32 v148, v145, v145
	v_mov_b32_e32 v149, 0x3ba10414
	v_fmamk_f32 v149, v148, 0xba1345e1, v149
	v_fmaak_f32 v149, v148, v149, 0xbcdac9b8
	v_fmaak_f32 v149, v148, v149, 0x3de703be
	v_fmaak_f32 v149, v148, v149, 0xbec09330
	v_fmaak_f32 v149, v148, v149, 0x3e0375d0
	v_fma_f32 v149, |v145|, v149, |v145|
	v_cmp_nlt_f32_e64 vcc, |v145|, 1.0
	s_nop 1
	v_cndmask_b32_e32 v147, v149, v147, vcc
	v_bfi_b32 v147, s89, v147, v145
	v_mul_f32_e32 v144, 0.5, v144
	v_add_f32_e32 v147, 1.0, v147
	v_mul_f32_e32 v144, v144, v147
	v_mul_f32_e32 v144, v100, v144
	v_mul_f32_e32 v96, v104, v144
	v_mul_f32_e32 v144, v103, v97
	v_mul_f32_e32 v145, 0x3f3504f3, v144
	v_mov_b32_e32 v146, 0xb9c68948
	v_fma_f32 v146, |v145|, s80, v146
	v_fma_f32 v146, |v145|, v146, s81
	v_fma_f32 v146, |v145|, v146, s82
	v_fma_f32 v146, |v145|, v146, s83
	v_fma_f32 v146, |v145|, v146, s84
	v_fma_f32 v146, |v145|, v146, s85
	v_fma_f32 v146, |v145|, v146, |v145|
	v_mul_f32_e32 v147, 0xbfb8aa3b, v146
	v_fma_f32 v148, v146, s86, -v147
	v_rndne_f32_e32 v149, v147
	v_fmac_f32_e32 v148, 0xb2a5705f, v146
	v_sub_f32_e32 v147, v147, v149
	v_add_f32_e32 v147, v147, v148
	v_cvt_i32_f32_e32 v148, v149
	v_exp_f32_e32 v147, v147
	v_cmp_nlt_f32_e32 vcc, s87, v146
	v_ldexp_f32 v147, v147, v148
	s_nop 0
	v_cndmask_b32_e32 v147, 0, v147, vcc
	v_cmp_ngt_f32_e32 vcc, s88, v146
	v_mov_b32_e32 v148, 0x7f800000
	s_nop 0
	v_cndmask_b32_e32 v147, v148, v147, vcc
	v_sub_f32_e32 v147, 1.0, v147
	v_mul_f32_e32 v148, v145, v145
	v_mov_b32_e32 v149, 0x3ba10414
	v_fmamk_f32 v149, v148, 0xba1345e1, v149
	v_fmaak_f32 v149, v148, v149, 0xbcdac9b8
	v_fmaak_f32 v149, v148, v149, 0x3de703be
	v_fmaak_f32 v149, v148, v149, 0xbec09330
	v_fmaak_f32 v149, v148, v149, 0x3e0375d0
	v_fma_f32 v149, |v145|, v149, |v145|
	v_cmp_nlt_f32_e64 vcc, |v145|, 1.0
	s_nop 1
	v_cndmask_b32_e32 v147, v149, v147, vcc
	v_bfi_b32 v147, s89, v147, v145
	v_mul_f32_e32 v144, 0.5, v144
	v_add_f32_e32 v147, 1.0, v147
	v_mul_f32_e32 v144, v144, v147
	v_mul_f32_e32 v144, v101, v144
	v_mul_f32_e32 v97, v105, v144
	global_store_dword v238, v98, s[26:27] offset:3072
	global_store_dword v238, v99, s[26:27] offset:3328
	global_store_dword v238, v96, s[28:29] offset:3072
	global_store_dword v238, v97, s[28:29] offset:3328
	s_waitcnt vmcnt(28)
; DI float gelu_exact(float x) { return 0.5f * x * (1.f + erff(x * 0.7071067811865476f)); }
; template <bool STORE>
; DI void peer_item(const Params& p, int item, char* smem) {
;     ...
;       h += __shfl_xor(h, 4);
;       h += __shfl_xor(h, 2);
;       h += __shfl_xor(h, 1);
;       const float amine = gelu_exact(h * su) * gmine * sv;
;       if ((lane & 7) == 0) {
;         EG[tok * 128 + k + (lane >> 3)] = emine;
;         AG[tok * 128 + k + (lane >> 3)] = amine;
;       }
;     }
	v_mul_f32_e32 v144, v118, v112
	v_mul_f32_e32 v145, 0x3f3504f3, v144
	v_mov_b32_e32 v146, 0xb9c68948
	v_fma_f32 v146, |v145|, s80, v146
	v_fma_f32 v146, |v145|, v146, s81
	v_fma_f32 v146, |v145|, v146, s82
	v_fma_f32 v146, |v145|, v146, s83
	v_fma_f32 v146, |v145|, v146, s84
	v_fma_f32 v146, |v145|, v146, s85
	v_fma_f32 v146, |v145|, v146, |v145|
	v_mul_f32_e32 v147, 0xbfb8aa3b, v146
	v_fma_f32 v148, v146, s86, -v147
	v_rndne_f32_e32 v149, v147
	v_fmac_f32_e32 v148, 0xb2a5705f, v146
	v_sub_f32_e32 v147, v147, v149
	v_add_f32_e32 v147, v147, v148
	v_cvt_i32_f32_e32 v148, v149
	v_exp_f32_e32 v147, v147
	v_cmp_nlt_f32_e32 vcc, s87, v146
	v_ldexp_f32 v147, v147, v148
	s_nop 0
	v_cndmask_b32_e32 v147, 0, v147, vcc
	v_cmp_ngt_f32_e32 vcc, s88, v146
	v_mov_b32_e32 v148, 0x7f800000
	s_nop 0
	v_cndmask_b32_e32 v147, v148, v147, vcc
	v_sub_f32_e32 v147, 1.0, v147
	v_mul_f32_e32 v148, v145, v145
	v_mov_b32_e32 v149, 0x3ba10414
	v_fmamk_f32 v149, v148, 0xba1345e1, v149
	v_fmaak_f32 v149, v148, v149, 0xbcdac9b8
	v_fmaak_f32 v149, v148, v149, 0x3de703be
	v_fmaak_f32 v149, v148, v149, 0xbec09330
	v_fmaak_f32 v149, v148, v149, 0x3e0375d0
	v_fma_f32 v149, |v145|, v149, |v145|
	v_cmp_nlt_f32_e64 vcc, |v145|, 1.0
	s_nop 1
	v_cndmask_b32_e32 v147, v149, v147, vcc
	v_bfi_b32 v147, s89, v147, v145
	v_mul_f32_e32 v144, 0.5, v144
	v_add_f32_e32 v147, 1.0, v147
	v_mul_f32_e32 v144, v144, v147
	v_mul_f32_e32 v144, v116, v144
	v_mul_f32_e32 v112, v120, v144
	v_mul_f32_e32 v144, v119, v113
	v_mul_f32_e32 v145, 0x3f3504f3, v144
	v_mov_b32_e32 v146, 0xb9c68948
	v_fma_f32 v146, |v145|, s80, v146
	v_fma_f32 v146, |v145|, v146, s81
	v_fma_f32 v146, |v145|, v146, s82
	v_fma_f32 v146, |v145|, v146, s83
	v_fma_f32 v146, |v145|, v146, s84
	v_fma_f32 v146, |v145|, v146, s85
	v_fma_f32 v146, |v145|, v146, |v145|
	v_mul_f32_e32 v147, 0xbfb8aa3b, v146
	v_fma_f32 v148, v146, s86, -v147
	v_rndne_f32_e32 v149, v147
	v_fmac_f32_e32 v148, 0xb2a5705f, v146
	v_sub_f32_e32 v147, v147, v149
	v_add_f32_e32 v147, v147, v148
	v_cvt_i32_f32_e32 v148, v149
	v_exp_f32_e32 v147, v147
	v_cmp_nlt_f32_e32 vcc, s87, v146
	v_ldexp_f32 v147, v147, v148
	s_nop 0
	v_cndmask_b32_e32 v147, 0, v147, vcc
	v_cmp_ngt_f32_e32 vcc, s88, v146
	v_mov_b32_e32 v148, 0x7f800000
	s_nop 0
	v_cndmask_b32_e32 v147, v148, v147, vcc
	v_sub_f32_e32 v147, 1.0, v147
	v_mul_f32_e32 v148, v145, v145
	v_mov_b32_e32 v149, 0x3ba10414
	v_fmamk_f32 v149, v148, 0xba1345e1, v149
	v_fmaak_f32 v149, v148, v149, 0xbcdac9b8
	v_fmaak_f32 v149, v148, v149, 0x3de703be
	v_fmaak_f32 v149, v148, v149, 0xbec09330
	v_fmaak_f32 v149, v148, v149, 0x3e0375d0
	v_fma_f32 v149, |v145|, v149, |v145|
	v_cmp_nlt_f32_e64 vcc, |v145|, 1.0
	s_nop 1
	v_cndmask_b32_e32 v147, v149, v147, vcc
	v_bfi_b32 v147, s89, v147, v145
	v_mul_f32_e32 v144, 0.5, v144
	v_add_f32_e32 v147, 1.0, v147
	v_mul_f32_e32 v144, v144, v147
	v_mul_f32_e32 v144, v117, v144
	v_mul_f32_e32 v113, v121, v144
	global_store_dword v238, v114, s[26:27] offset:3584
	global_store_dword v238, v115, s[26:27] offset:3840
	global_store_dword v238, v112, s[28:29] offset:3584
	global_store_dword v238, v113, s[28:29] offset:3840
	ds_read_b32 v3, v236 offset:512
	ds_read_b32 v53, v236 offset:768
	ds_read_b32 v64, v236 offset:1024
	ds_read_b32 v65, v236 offset:1280
	ds_read_b32 v66, v236 offset:1536
	ds_read_b32 v67, v236 offset:1792
	ds_read_b32 v68, v236 offset:2048
	ds_read_b32 v69, v236 offset:2304
	ds_read_b32 v70, v236 offset:2560
	ds_read_b32 v71, v236 offset:2816
	ds_read_b32 v72, v236 offset:3072
	ds_read_b32 v73, v236 offset:3328
	ds_read_b32 v74, v236 offset:3584
	ds_read_b32 v75, v236 offset:3840
	ds_read_b32 v76, v236 offset:4096
	ds_read_b32 v77, v236 offset:4352
	ds_read_b32 v78, v236 offset:4608
	ds_read_b32 v79, v236 offset:4864
	ds_read_b32 v80, v236 offset:5120
	ds_read_b32 v81, v236 offset:5376
	ds_read_b32 v82, v236 offset:5632
	ds_read_b32 v83, v236 offset:5888
	ds_read_b32 v96, v236 offset:6144
	ds_read_b32 v210, v236 offset:6400
	ds_read_b32 v211, v236 offset:6656
	ds_read_b32 v212, v236 offset:6912
	v_readlane_b32 s6, v254, 0
	v_readlane_b32 s7, v254, 1
	v_readlane_b32 s12, v254, 2
	v_readlane_b32 s13, v254, 3
	v_readlane_b32 s14, v254, 4
	v_readlane_b32 s15, v254, 5
	v_readlane_b32 s16, v254, 6
	v_readlane_b32 s17, v254, 7
	v_readlane_b32 s18, v254, 8
	v_readlane_b32 s19, v254, 9
	v_readlane_b32 s20, v254, 10
	v_readlane_b32 s21, v254, 11
	v_readlane_b32 s22, v254, 12
	v_readlane_b32 s23, v254, 13
	v_readlane_b32 s24, v254, 14
	v_readlane_b32 s25, v254, 15
	v_readlane_b32 s26, v254, 16
	v_readlane_b32 s27, v254, 17
	v_readlane_b32 s28, v254, 18
	v_readlane_b32 s29, v254, 19
	v_readlane_b32 s30, v254, 20
	v_readlane_b32 s31, v254, 21
	v_readlane_b32 s33, v254, 22
	v_readlane_b32 s34, v254, 23
	v_readlane_b32 s35, v254, 24
	v_readlane_b32 s36, v254, 25
	v_readlane_b32 s37, v254, 26
	v_readlane_b32 s38, v254, 27
	v_readlane_b32 s39, v254, 28
	v_readlane_b32 s40, v254, 29
	v_readlane_b32 s41, v254, 30
	v_readlane_b32 s42, v254, 31
	v_readlane_b32 s44, v254, 32
	v_readlane_b32 s45, v254, 33
	v_readlane_b32 s48, v254, 34
	v_readlane_b32 s49, v254, 35
	v_readlane_b32 s50, v254, 36
	v_readlane_b32 s51, v254, 37
	v_readlane_b32 s52, v254, 38
	v_readlane_b32 s53, v254, 39
	v_readlane_b32 s55, v254, 40
	v_readlane_b32 s60, v254, 41
	v_readlane_b32 s61, v254, 42
	v_readlane_b32 s62, v254, 43
	v_readlane_b32 s63, v254, 44
	v_readlane_b32 s66, v254, 45
	v_readlane_b32 s67, v254, 46
	v_readlane_b32 s68, v254, 47
	v_readlane_b32 s69, v254, 48
	v_readlane_b32 s74, v254, 49
	v_readlane_b32 s75, v254, 50
	v_readlane_b32 s76, v254, 51
	v_readlane_b32 s77, v254, 52
	v_readlane_b32 s78, v254, 53
	v_readlane_b32 s79, v254, 54
	v_readlane_b32 s88, v254, 55
	s_waitcnt lgkmcnt(0)
	s_nop 3
